# LDS-DMA issue: three of the six pieces of the second K-loop load segment moved to the head of the third (2+3+5+6), closing wait vmcnt(5)
# baseline (speedup 1.0000x reference)
.LBB0_163:
	ds_read_b128 v[144:147], v151
	ds_read_b128 v[156:159], v151 offset:1024
	ds_read_b128 v[160:163], v151 offset:2048
	ds_read_b128 v[164:167], v151 offset:3072
	ds_read_b128 v[168:171], v152
	ds_read_b128 v[172:175], v152 offset:1024
	ds_read_b128 v[176:179], v152 offset:2048
	ds_read_b128 v[180:183], v152 offset:3072
	s_add_u32 s26, s24, 0xfffc0080
	s_addc_u32 s27, s25, -1
	s_cmp_eq_u32 s55, 12
	s_cselect_b32 s29, s19, s27
	s_cselect_b32 s28, s51, s26
	s_cselect_b32 s27, s17, s54
	s_cselect_b32 s26, s52, s53
	s_add_i32 m0, s38, 0xc000
	ds_read_b128 v[184:187], v153
	ds_read_b128 v[188:191], v153 offset:1024
	ds_read_b128 v[192:195], v153 offset:2048
	ds_read_b128 v[196:199], v153 offset:3072
	ds_read_b128 v[200:203], v153 offset:4096
	ds_read_b128 v[208:211], v153 offset:5120
	ds_read_b128 v[212:215], v153 offset:6144
	ds_read_b128 v[216:219], v153 offset:7168
	global_load_lds_dwordx4 v138, s[24:25]
	s_add_i32 m0, s38, 0xe000
	s_nop 0
	global_load_lds_dwordx4 v136, s[24:25]
	s_waitcnt vmcnt(8)
	s_waitcnt lgkmcnt(0)
	s_barrier
	s_waitcnt lgkmcnt(0)
	v_mfma_f32_16x16x32_bf16 v[124:127], v[144:147], v[184:187], v[124:127]
	v_mfma_f32_16x16x32_bf16 v[120:123], v[160:163], v[184:187], v[120:123]
	v_mfma_f32_16x16x32_bf16 v[108:111], v[144:147], v[192:195], v[108:111]
	v_mfma_f32_16x16x32_bf16 v[104:107], v[160:163], v[192:195], v[104:107]
	v_mfma_f32_16x16x32_bf16 v[92:95], v[144:147], v[200:203], v[92:95]
	v_mfma_f32_16x16x32_bf16 v[88:91], v[160:163], v[200:203], v[88:91]
	v_mfma_f32_16x16x32_bf16 v[76:79], v[144:147], v[212:215], v[76:79]
	v_mfma_f32_16x16x32_bf16 v[72:75], v[160:163], v[212:215], v[72:75]
	v_mfma_f32_16x16x32_bf16 v[124:127], v[156:159], v[188:191], v[124:127]
	v_mfma_f32_16x16x32_bf16 v[120:123], v[164:167], v[188:191], v[120:123]
	v_mfma_f32_16x16x32_bf16 v[108:111], v[156:159], v[196:199], v[108:111]
	v_mfma_f32_16x16x32_bf16 v[104:107], v[164:167], v[196:199], v[104:107]
	v_mfma_f32_16x16x32_bf16 v[92:95], v[156:159], v[208:211], v[92:95]
	v_mfma_f32_16x16x32_bf16 v[88:91], v[164:167], v[208:211], v[88:91]
	v_mfma_f32_16x16x32_bf16 v[76:79], v[156:159], v[216:219], v[76:79]
	v_mfma_f32_16x16x32_bf16 v[72:75], v[164:167], v[216:219], v[72:75]
	v_mfma_f32_16x16x32_bf16 v[116:119], v[168:171], v[184:187], v[116:119]
	v_mfma_f32_16x16x32_bf16 v[112:115], v[176:179], v[184:187], v[112:115]
	v_mfma_f32_16x16x32_bf16 v[100:103], v[168:171], v[192:195], v[100:103]
	v_mfma_f32_16x16x32_bf16 v[96:99], v[176:179], v[192:195], v[96:99]
	v_mfma_f32_16x16x32_bf16 v[84:87], v[168:171], v[200:203], v[84:87]
	v_mfma_f32_16x16x32_bf16 v[80:83], v[176:179], v[200:203], v[80:83]
	v_mfma_f32_16x16x32_bf16 v[68:71], v[168:171], v[212:215], v[68:71]
	v_mfma_f32_16x16x32_bf16 v[64:67], v[176:179], v[212:215], v[64:67]
	v_mfma_f32_16x16x32_bf16 v[116:119], v[172:175], v[188:191], v[116:119]
	v_mfma_f32_16x16x32_bf16 v[112:115], v[180:183], v[188:191], v[112:115]
	v_mfma_f32_16x16x32_bf16 v[100:103], v[172:175], v[196:199], v[100:103]
	v_mfma_f32_16x16x32_bf16 v[96:99], v[180:183], v[196:199], v[96:99]
	v_mfma_f32_16x16x32_bf16 v[84:87], v[172:175], v[208:211], v[84:87]
	v_mfma_f32_16x16x32_bf16 v[80:83], v[180:183], v[208:211], v[80:83]
	v_mfma_f32_16x16x32_bf16 v[68:71], v[172:175], v[216:219], v[68:71]
	v_mfma_f32_16x16x32_bf16 v[64:67], v[180:183], v[216:219], v[64:67]
	s_barrier
	s_add_i32 s56, s48, s35
	s_mov_b32 m0, s56
	ds_read_b128 v[184:187], v153 offset:16384
	ds_read_b128 v[188:191], v153 offset:17408
	ds_read_b128 v[192:195], v153 offset:18432
	ds_read_b128 v[196:199], v153 offset:19456
	ds_read_b128 v[200:203], v153 offset:20480
	ds_read_b128 v[208:211], v153 offset:21504
	ds_read_b128 v[212:215], v153 offset:22528
	ds_read_b128 v[216:219], v153 offset:23552
	global_load_lds_dwordx4 v132, s[26:27]
	s_add_i32 m0, s56, 0x2000
	s_add_u32 s56, s26, 0x40000
	s_mov_b64 s[98:99], s[26:27]
	s_addc_u32 s57, s27, 0
	s_add_i32 s58, s49, s35
	global_load_lds_dwordx4 v128, s[26:27]
	s_mov_b32 m0, s58
	s_mov_b64 s[100:101], s[28:29]
	global_load_lds_dwordx4 v132, s[56:57]
	s_waitcnt vmcnt(5)
	s_waitcnt lgkmcnt(0)
	s_barrier
	s_waitcnt lgkmcnt(0)
	v_mfma_f32_16x16x32_bf16 v[60:63], v[144:147], v[184:187], v[60:63]
	v_mfma_f32_16x16x32_bf16 v[56:59], v[160:163], v[184:187], v[56:59]
	v_mfma_f32_16x16x32_bf16 v[44:47], v[144:147], v[192:195], v[44:47]
	v_mfma_f32_16x16x32_bf16 v[40:43], v[160:163], v[192:195], v[40:43]
	v_mfma_f32_16x16x32_bf16 v[28:31], v[144:147], v[200:203], v[28:31]
	v_mfma_f32_16x16x32_bf16 v[24:27], v[160:163], v[200:203], v[24:27]
	v_mfma_f32_16x16x32_bf16 v[12:15], v[144:147], v[212:215], v[12:15]
	v_mfma_f32_16x16x32_bf16 v[8:11], v[160:163], v[212:215], v[8:11]
	v_mfma_f32_16x16x32_bf16 v[60:63], v[156:159], v[188:191], v[60:63]
	v_mfma_f32_16x16x32_bf16 v[56:59], v[164:167], v[188:191], v[56:59]
	v_mfma_f32_16x16x32_bf16 v[44:47], v[156:159], v[196:199], v[44:47]
	v_mfma_f32_16x16x32_bf16 v[40:43], v[164:167], v[196:199], v[40:43]
	v_mfma_f32_16x16x32_bf16 v[28:31], v[156:159], v[208:211], v[28:31]
	v_mfma_f32_16x16x32_bf16 v[24:27], v[164:167], v[208:211], v[24:27]
	v_mfma_f32_16x16x32_bf16 v[12:15], v[156:159], v[216:219], v[12:15]
	v_mfma_f32_16x16x32_bf16 v[8:11], v[164:167], v[216:219], v[8:11]
	v_mfma_f32_16x16x32_bf16 v[52:55], v[168:171], v[184:187], v[52:55]
	v_mfma_f32_16x16x32_bf16 v[48:51], v[176:179], v[184:187], v[48:51]
	v_mfma_f32_16x16x32_bf16 v[36:39], v[168:171], v[192:195], v[36:39]
	v_mfma_f32_16x16x32_bf16 v[32:35], v[176:179], v[192:195], v[32:35]
	v_mfma_f32_16x16x32_bf16 v[20:23], v[168:171], v[200:203], v[20:23]
	v_mfma_f32_16x16x32_bf16 v[16:19], v[176:179], v[200:203], v[16:19]
	v_mfma_f32_16x16x32_bf16 v[4:7], v[168:171], v[212:215], v[4:7]
	v_mfma_f32_16x16x32_bf16 v[0:3], v[176:179], v[212:215], v[0:3]
	v_mfma_f32_16x16x32_bf16 v[52:55], v[172:175], v[188:191], v[52:55]
	v_mfma_f32_16x16x32_bf16 v[48:51], v[180:183], v[188:191], v[48:51]
	v_mfma_f32_16x16x32_bf16 v[36:39], v[172:175], v[196:199], v[36:39]
	v_mfma_f32_16x16x32_bf16 v[32:35], v[180:183], v[196:199], v[32:35]
	v_mfma_f32_16x16x32_bf16 v[20:23], v[172:175], v[208:211], v[20:23]
	v_mfma_f32_16x16x32_bf16 v[16:19], v[180:183], v[208:211], v[16:19]
	v_mfma_f32_16x16x32_bf16 v[4:7], v[172:175], v[216:219], v[4:7]
	v_mfma_f32_16x16x32_bf16 v[0:3], v[180:183], v[216:219], v[0:3]
	s_barrier
	s_add_i32 m0, s58, 0x2000
	s_nop 0
	global_load_lds_dwordx4 v128, s[56:57]
	s_mov_b32 m0, s38
	s_nop 0
	global_load_lds_dwordx4 v134, s[28:29]
	s_mov_b32 m0, s39
	s_nop 0
	global_load_lds_dwordx4 v130, s[28:29]
	s_add_i32 s56, 0, 0x18000
	s_add_i32 s57, 0, 0x1c000
	v_add_u32_e32 v164, s56, v149
	v_add_u32_e32 v180, s57, v149
	ds_read_b128 v[144:147], v164
	ds_read_b128 v[156:159], v164 offset:1024
	ds_read_b128 v[160:163], v164 offset:2048
	ds_read_b128 v[164:167], v164 offset:3072
	ds_read_b128 v[168:171], v180
	ds_read_b128 v[172:175], v180 offset:1024
	ds_read_b128 v[176:179], v180 offset:2048
	ds_read_b128 v[180:183], v180 offset:3072
	s_add_u32 s28, s28, 0x40000
	s_addc_u32 s29, s29, 0
	s_mov_b32 m0, s40
	ds_read_b128 v[184:187], v153 offset:32768
	ds_read_b128 v[188:191], v153 offset:33792
	ds_read_b128 v[192:195], v153 offset:34816
	ds_read_b128 v[196:199], v153 offset:35840
	ds_read_b128 v[200:203], v153 offset:36864
	ds_read_b128 v[208:211], v153 offset:37888
	ds_read_b128 v[212:215], v153 offset:38912
	ds_read_b128 v[216:219], v153 offset:39936
	global_load_lds_dwordx4 v134, s[28:29]
	s_mov_b32 m0, s41
	s_nop 0
	global_load_lds_dwordx4 v130, s[28:29]
	s_waitcnt vmcnt(8)
	s_waitcnt lgkmcnt(0)
	s_barrier
	s_waitcnt lgkmcnt(0)
	v_mfma_f32_16x16x32_bf16 v[124:127], v[144:147], v[184:187], v[124:127]
	v_mfma_f32_16x16x32_bf16 v[120:123], v[160:163], v[184:187], v[120:123]
	v_mfma_f32_16x16x32_bf16 v[108:111], v[144:147], v[192:195], v[108:111]
	v_mfma_f32_16x16x32_bf16 v[104:107], v[160:163], v[192:195], v[104:107]
	v_mfma_f32_16x16x32_bf16 v[92:95], v[144:147], v[200:203], v[92:95]
	v_mfma_f32_16x16x32_bf16 v[88:91], v[160:163], v[200:203], v[88:91]
	v_mfma_f32_16x16x32_bf16 v[76:79], v[144:147], v[212:215], v[76:79]
	v_mfma_f32_16x16x32_bf16 v[72:75], v[160:163], v[212:215], v[72:75]
	v_mfma_f32_16x16x32_bf16 v[124:127], v[156:159], v[188:191], v[124:127]
	v_mfma_f32_16x16x32_bf16 v[120:123], v[164:167], v[188:191], v[120:123]
	v_mfma_f32_16x16x32_bf16 v[108:111], v[156:159], v[196:199], v[108:111]
	v_mfma_f32_16x16x32_bf16 v[104:107], v[164:167], v[196:199], v[104:107]
	v_mfma_f32_16x16x32_bf16 v[92:95], v[156:159], v[208:211], v[92:95]
	v_mfma_f32_16x16x32_bf16 v[88:91], v[164:167], v[208:211], v[88:91]
	v_mfma_f32_16x16x32_bf16 v[76:79], v[156:159], v[216:219], v[76:79]
	v_mfma_f32_16x16x32_bf16 v[72:75], v[164:167], v[216:219], v[72:75]
	v_mfma_f32_16x16x32_bf16 v[116:119], v[168:171], v[184:187], v[116:119]
	v_mfma_f32_16x16x32_bf16 v[112:115], v[176:179], v[184:187], v[112:115]
	v_mfma_f32_16x16x32_bf16 v[100:103], v[168:171], v[192:195], v[100:103]
	v_mfma_f32_16x16x32_bf16 v[96:99], v[176:179], v[192:195], v[96:99]
	v_mfma_f32_16x16x32_bf16 v[84:87], v[168:171], v[200:203], v[84:87]
	v_mfma_f32_16x16x32_bf16 v[80:83], v[176:179], v[200:203], v[80:83]
	v_mfma_f32_16x16x32_bf16 v[68:71], v[168:171], v[212:215], v[68:71]
	v_mfma_f32_16x16x32_bf16 v[64:67], v[176:179], v[212:215], v[64:67]
	v_mfma_f32_16x16x32_bf16 v[116:119], v[172:175], v[188:191], v[116:119]
	v_mfma_f32_16x16x32_bf16 v[112:115], v[180:183], v[188:191], v[112:115]
	v_mfma_f32_16x16x32_bf16 v[100:103], v[172:175], v[196:199], v[100:103]
	v_mfma_f32_16x16x32_bf16 v[96:99], v[180:183], v[196:199], v[96:99]
	v_mfma_f32_16x16x32_bf16 v[84:87], v[172:175], v[208:211], v[84:87]
	v_mfma_f32_16x16x32_bf16 v[80:83], v[180:183], v[208:211], v[80:83]
	v_mfma_f32_16x16x32_bf16 v[68:71], v[172:175], v[216:219], v[68:71]
	v_mfma_f32_16x16x32_bf16 v[64:67], v[180:183], v[216:219], v[64:67]
	s_barrier
	s_add_i32 s28, s56, s35
	s_mov_b32 m0, s28
	ds_read_b128 v[184:187], v153 offset:49152
	ds_read_b128 v[188:191], v153 offset:50176
	ds_read_b128 v[192:195], v153 offset:51200
	ds_read_b128 v[196:199], v153 offset:52224
	ds_read_b128 v[200:203], v153 offset:53248
	ds_read_b128 v[208:211], v153 offset:54272
	ds_read_b128 v[212:215], v153 offset:55296
	ds_read_b128 v[216:219], v153 offset:56320
	global_load_lds_dwordx4 v220, s[26:27]
	s_add_i32 m0, s28, 0x2000
	s_add_u32 s26, s26, 0x40080
	s_addc_u32 s27, s27, 0
	s_add_i32 s28, s57, s35
	global_load_lds_dwordx4 v204, s[98:99]
	s_mov_b32 m0, s28
	s_nop 0
	global_load_lds_dwordx4 v132, s[26:27]
	s_add_i32 m0, s28, 0x2000
	s_nop 0
	global_load_lds_dwordx4 v128, s[26:27]
	s_mov_b32 m0, s45
	s_nop 0
	global_load_lds_dwordx4 v221, s[100:101]
	s_mov_b32 m0, s46
	s_nop 0
	global_load_lds_dwordx4 v205, s[100:101]
	s_waitcnt vmcnt(8)
	s_waitcnt lgkmcnt(0)
	s_barrier
	s_waitcnt lgkmcnt(0)
	v_mfma_f32_16x16x32_bf16 v[60:63], v[144:147], v[184:187], v[60:63]
	v_mfma_f32_16x16x32_bf16 v[56:59], v[160:163], v[184:187], v[56:59]
	v_mfma_f32_16x16x32_bf16 v[44:47], v[144:147], v[192:195], v[44:47]
	v_mfma_f32_16x16x32_bf16 v[40:43], v[160:163], v[192:195], v[40:43]
	v_mfma_f32_16x16x32_bf16 v[28:31], v[144:147], v[200:203], v[28:31]
	v_mfma_f32_16x16x32_bf16 v[24:27], v[160:163], v[200:203], v[24:27]
	v_mfma_f32_16x16x32_bf16 v[12:15], v[144:147], v[212:215], v[12:15]
	v_mfma_f32_16x16x32_bf16 v[8:11], v[160:163], v[212:215], v[8:11]
	v_mfma_f32_16x16x32_bf16 v[60:63], v[156:159], v[188:191], v[60:63]
	v_mfma_f32_16x16x32_bf16 v[56:59], v[164:167], v[188:191], v[56:59]
	v_mfma_f32_16x16x32_bf16 v[44:47], v[156:159], v[196:199], v[44:47]
	v_mfma_f32_16x16x32_bf16 v[40:43], v[164:167], v[196:199], v[40:43]
	v_mfma_f32_16x16x32_bf16 v[28:31], v[156:159], v[208:211], v[28:31]
	v_mfma_f32_16x16x32_bf16 v[24:27], v[164:167], v[208:211], v[24:27]
	v_mfma_f32_16x16x32_bf16 v[12:15], v[156:159], v[216:219], v[12:15]
	v_mfma_f32_16x16x32_bf16 v[8:11], v[164:167], v[216:219], v[8:11]
	v_mfma_f32_16x16x32_bf16 v[52:55], v[168:171], v[184:187], v[52:55]
	v_mfma_f32_16x16x32_bf16 v[48:51], v[176:179], v[184:187], v[48:51]
	v_mfma_f32_16x16x32_bf16 v[36:39], v[168:171], v[192:195], v[36:39]
	v_mfma_f32_16x16x32_bf16 v[32:35], v[176:179], v[192:195], v[32:35]
	v_mfma_f32_16x16x32_bf16 v[20:23], v[168:171], v[200:203], v[20:23]
	v_mfma_f32_16x16x32_bf16 v[16:19], v[176:179], v[200:203], v[16:19]
	v_mfma_f32_16x16x32_bf16 v[4:7], v[168:171], v[212:215], v[4:7]
	v_mfma_f32_16x16x32_bf16 v[0:3], v[176:179], v[212:215], v[0:3]
	v_mfma_f32_16x16x32_bf16 v[52:55], v[172:175], v[188:191], v[52:55]
	v_mfma_f32_16x16x32_bf16 v[48:51], v[180:183], v[188:191], v[48:51]
	v_mfma_f32_16x16x32_bf16 v[36:39], v[172:175], v[196:199], v[36:39]
	v_mfma_f32_16x16x32_bf16 v[32:35], v[180:183], v[196:199], v[32:35]
	v_mfma_f32_16x16x32_bf16 v[20:23], v[172:175], v[208:211], v[20:23]
	v_mfma_f32_16x16x32_bf16 v[16:19], v[180:183], v[208:211], v[16:19]
	v_mfma_f32_16x16x32_bf16 v[4:7], v[172:175], v[216:219], v[4:7]
	v_mfma_f32_16x16x32_bf16 v[0:3], v[180:183], v[216:219], v[0:3]
	s_barrier
	s_add_i32 s55, s55, 2
	s_add_u32 s53, s53, 0x100
	s_addc_u32 s54, s54, 0
	s_add_u32 s24, s24, 0x100
	s_addc_u32 s25, s25, 0
	s_cmp_gt_u32 s55, 13
	s_cbranch_scc0 .LBB0_163
	s_setprio 0
	s_and_b64 vcc, exec, s[14:15]
	s_cbranch_vccz .LBB0_166
	s_barrier

.LBB0_606:
	ds_read_b128 v[140:143], v147
	ds_read_b128 v[150:153], v147 offset:1024
	ds_read_b128 v[154:157], v147 offset:2048
	ds_read_b128 v[158:161], v147 offset:3072
	ds_read_b128 v[162:165], v148
	ds_read_b128 v[166:169], v148 offset:1024
	ds_read_b128 v[170:173], v148 offset:2048
	ds_read_b128 v[174:177], v148 offset:3072
	s_add_u32 s30, s28, 0x100
	s_addc_u32 s31, s29, 0
	s_cmp_eq_u32 s58, 12
	s_cselect_b32 s37, s21, s31
	s_cselect_b32 s36, s27, s30
	s_cselect_b32 s35, s19, s57
	s_cselect_b32 s34, s55, s56
	s_add_i32 m0, s44, 0xc000
	ds_read_b128 v[178:181], v149
	ds_read_b128 v[182:185], v149 offset:1024
	ds_read_b128 v[186:189], v149 offset:2048
	ds_read_b128 v[190:193], v149 offset:3072
	ds_read_b128 v[194:197], v149 offset:4096
	ds_read_b128 v[198:201], v149 offset:5120
	ds_read_b128 v[202:205], v149 offset:6144
	ds_read_b128 v[208:211], v149 offset:7168
	global_load_lds_dwordx4 v134, s[28:29]
	s_add_i32 m0, s44, 0xe000
	s_nop 0
	global_load_lds_dwordx4 v132, s[28:29]
	s_waitcnt vmcnt(8)
	s_waitcnt lgkmcnt(0)
	s_barrier
	s_waitcnt lgkmcnt(0)
	v_mfma_f32_16x16x32_bf16 v[124:127], v[140:143], v[178:181], v[124:127]
	v_mfma_f32_16x16x32_bf16 v[120:123], v[154:157], v[178:181], v[120:123]
	v_mfma_f32_16x16x32_bf16 v[108:111], v[140:143], v[186:189], v[108:111]
	v_mfma_f32_16x16x32_bf16 v[104:107], v[154:157], v[186:189], v[104:107]
	v_mfma_f32_16x16x32_bf16 v[92:95], v[140:143], v[194:197], v[92:95]
	v_mfma_f32_16x16x32_bf16 v[88:91], v[154:157], v[194:197], v[88:91]
	v_mfma_f32_16x16x32_bf16 v[76:79], v[140:143], v[202:205], v[76:79]
	v_mfma_f32_16x16x32_bf16 v[72:75], v[154:157], v[202:205], v[72:75]
	v_mfma_f32_16x16x32_bf16 v[124:127], v[150:153], v[182:185], v[124:127]
	v_mfma_f32_16x16x32_bf16 v[120:123], v[158:161], v[182:185], v[120:123]
	v_mfma_f32_16x16x32_bf16 v[108:111], v[150:153], v[190:193], v[108:111]
	v_mfma_f32_16x16x32_bf16 v[104:107], v[158:161], v[190:193], v[104:107]
	v_mfma_f32_16x16x32_bf16 v[92:95], v[150:153], v[198:201], v[92:95]
	v_mfma_f32_16x16x32_bf16 v[88:91], v[158:161], v[198:201], v[88:91]
	v_mfma_f32_16x16x32_bf16 v[76:79], v[150:153], v[208:211], v[76:79]
	v_mfma_f32_16x16x32_bf16 v[72:75], v[158:161], v[208:211], v[72:75]
	v_mfma_f32_16x16x32_bf16 v[116:119], v[162:165], v[178:181], v[116:119]
	v_mfma_f32_16x16x32_bf16 v[112:115], v[170:173], v[178:181], v[112:115]
	v_mfma_f32_16x16x32_bf16 v[100:103], v[162:165], v[186:189], v[100:103]
	v_mfma_f32_16x16x32_bf16 v[96:99], v[170:173], v[186:189], v[96:99]
	v_mfma_f32_16x16x32_bf16 v[84:87], v[162:165], v[194:197], v[84:87]
	v_mfma_f32_16x16x32_bf16 v[80:83], v[170:173], v[194:197], v[80:83]
	v_mfma_f32_16x16x32_bf16 v[68:71], v[162:165], v[202:205], v[68:71]
	v_mfma_f32_16x16x32_bf16 v[64:67], v[170:173], v[202:205], v[64:67]
	v_mfma_f32_16x16x32_bf16 v[116:119], v[166:169], v[182:185], v[116:119]
	v_mfma_f32_16x16x32_bf16 v[112:115], v[174:177], v[182:185], v[112:115]
	v_mfma_f32_16x16x32_bf16 v[100:103], v[166:169], v[190:193], v[100:103]
	v_mfma_f32_16x16x32_bf16 v[96:99], v[174:177], v[190:193], v[96:99]
	v_mfma_f32_16x16x32_bf16 v[84:87], v[166:169], v[198:201], v[84:87]
	v_mfma_f32_16x16x32_bf16 v[80:83], v[174:177], v[198:201], v[80:83]
	v_mfma_f32_16x16x32_bf16 v[68:71], v[166:169], v[208:211], v[68:71]
	v_mfma_f32_16x16x32_bf16 v[64:67], v[174:177], v[208:211], v[64:67]
	s_barrier
	s_add_i32 s28, s52, s43
	s_mov_b32 m0, s28
	ds_read_b128 v[178:181], v149 offset:16384
	ds_read_b128 v[182:185], v149 offset:17408
	ds_read_b128 v[186:189], v149 offset:18432
	ds_read_b128 v[190:193], v149 offset:19456
	ds_read_b128 v[194:197], v149 offset:20480
	ds_read_b128 v[198:201], v149 offset:21504
	ds_read_b128 v[202:205], v149 offset:22528
	ds_read_b128 v[208:211], v149 offset:23552
	global_load_lds_dwordx4 v128, s[34:35]
	s_add_i32 m0, s28, 0x2000
	s_add_u32 s28, s34, 0x40000
	s_mov_b64 s[98:99], s[34:35]
	s_addc_u32 s29, s35, 0
	s_add_i32 s59, s53, s43
	global_load_lds_dwordx4 v130, s[34:35]
	s_mov_b32 m0, s59
	s_nop 0
	global_load_lds_dwordx4 v128, s[28:29]
	s_waitcnt vmcnt(5)
	s_waitcnt lgkmcnt(0)
	s_barrier
	s_waitcnt lgkmcnt(0)
	v_mfma_f32_16x16x32_bf16 v[60:63], v[140:143], v[178:181], v[60:63]
	v_mfma_f32_16x16x32_bf16 v[56:59], v[154:157], v[178:181], v[56:59]
	v_mfma_f32_16x16x32_bf16 v[44:47], v[140:143], v[186:189], v[44:47]
	v_mfma_f32_16x16x32_bf16 v[40:43], v[154:157], v[186:189], v[40:43]
	v_mfma_f32_16x16x32_bf16 v[28:31], v[140:143], v[194:197], v[28:31]
	v_mfma_f32_16x16x32_bf16 v[24:27], v[154:157], v[194:197], v[24:27]
	v_mfma_f32_16x16x32_bf16 v[12:15], v[140:143], v[202:205], v[12:15]
	v_mfma_f32_16x16x32_bf16 v[8:11], v[154:157], v[202:205], v[8:11]
	v_mfma_f32_16x16x32_bf16 v[60:63], v[150:153], v[182:185], v[60:63]
	v_mfma_f32_16x16x32_bf16 v[56:59], v[158:161], v[182:185], v[56:59]
	v_mfma_f32_16x16x32_bf16 v[44:47], v[150:153], v[190:193], v[44:47]
	v_mfma_f32_16x16x32_bf16 v[40:43], v[158:161], v[190:193], v[40:43]
	v_mfma_f32_16x16x32_bf16 v[28:31], v[150:153], v[198:201], v[28:31]
	v_mfma_f32_16x16x32_bf16 v[24:27], v[158:161], v[198:201], v[24:27]
	v_mfma_f32_16x16x32_bf16 v[12:15], v[150:153], v[208:211], v[12:15]
	v_mfma_f32_16x16x32_bf16 v[8:11], v[158:161], v[208:211], v[8:11]
	v_mfma_f32_16x16x32_bf16 v[52:55], v[162:165], v[178:181], v[52:55]
	v_mfma_f32_16x16x32_bf16 v[48:51], v[170:173], v[178:181], v[48:51]
	v_mfma_f32_16x16x32_bf16 v[36:39], v[162:165], v[186:189], v[36:39]
	v_mfma_f32_16x16x32_bf16 v[32:35], v[170:173], v[186:189], v[32:35]
	v_mfma_f32_16x16x32_bf16 v[20:23], v[162:165], v[194:197], v[20:23]
	v_mfma_f32_16x16x32_bf16 v[16:19], v[170:173], v[194:197], v[16:19]
	v_mfma_f32_16x16x32_bf16 v[4:7], v[162:165], v[202:205], v[4:7]
	v_mfma_f32_16x16x32_bf16 v[0:3], v[170:173], v[202:205], v[0:3]
	v_mfma_f32_16x16x32_bf16 v[52:55], v[166:169], v[182:185], v[52:55]
	v_mfma_f32_16x16x32_bf16 v[48:51], v[174:177], v[182:185], v[48:51]
	v_mfma_f32_16x16x32_bf16 v[36:39], v[166:169], v[190:193], v[36:39]
	v_mfma_f32_16x16x32_bf16 v[32:35], v[174:177], v[190:193], v[32:35]
	v_mfma_f32_16x16x32_bf16 v[20:23], v[166:169], v[198:201], v[20:23]
	v_mfma_f32_16x16x32_bf16 v[16:19], v[174:177], v[198:201], v[16:19]
	v_mfma_f32_16x16x32_bf16 v[4:7], v[166:169], v[208:211], v[4:7]
	v_mfma_f32_16x16x32_bf16 v[0:3], v[174:177], v[208:211], v[0:3]
	s_barrier
	s_add_i32 m0, s59, 0x2000
	s_nop 0
	global_load_lds_dwordx4 v130, s[28:29]
	s_mov_b32 m0, s44
	s_nop 0
	global_load_lds_dwordx4 v128, s[36:37]
	s_mov_b32 m0, s45
	s_nop 0
	global_load_lds_dwordx4 v130, s[36:37]
	s_add_i32 s59, 0, 0x18000
	s_add_i32 s60, 0, 0x1c000
	v_add_u32_e32 v158, s59, v145
	v_add_u32_e32 v174, s60, v145
	ds_read_b128 v[140:143], v158
	ds_read_b128 v[150:153], v158 offset:1024
	ds_read_b128 v[154:157], v158 offset:2048
	ds_read_b128 v[158:161], v158 offset:3072
	ds_read_b128 v[162:165], v174
	ds_read_b128 v[166:169], v174 offset:1024
	ds_read_b128 v[170:173], v174 offset:2048
	ds_read_b128 v[174:177], v174 offset:3072
	s_add_u32 s28, s36, 0x40000
	s_addc_u32 s29, s37, 0
	s_mov_b32 m0, s46
	ds_read_b128 v[178:181], v149 offset:32768
	ds_read_b128 v[182:185], v149 offset:33792
	ds_read_b128 v[186:189], v149 offset:34816
	ds_read_b128 v[190:193], v149 offset:35840
	ds_read_b128 v[194:197], v149 offset:36864
	ds_read_b128 v[198:201], v149 offset:37888
	ds_read_b128 v[202:205], v149 offset:38912
	ds_read_b128 v[208:211], v149 offset:39936
	global_load_lds_dwordx4 v128, s[28:29]
	s_mov_b32 m0, s47
	s_nop 0
	global_load_lds_dwordx4 v130, s[28:29]
	s_waitcnt vmcnt(8)
	s_waitcnt lgkmcnt(0)
	s_barrier
	s_waitcnt lgkmcnt(0)
	v_mfma_f32_16x16x32_bf16 v[124:127], v[140:143], v[178:181], v[124:127]
	v_mfma_f32_16x16x32_bf16 v[120:123], v[154:157], v[178:181], v[120:123]
	v_mfma_f32_16x16x32_bf16 v[108:111], v[140:143], v[186:189], v[108:111]
	v_mfma_f32_16x16x32_bf16 v[104:107], v[154:157], v[186:189], v[104:107]
	v_mfma_f32_16x16x32_bf16 v[92:95], v[140:143], v[194:197], v[92:95]
	v_mfma_f32_16x16x32_bf16 v[88:91], v[154:157], v[194:197], v[88:91]
	v_mfma_f32_16x16x32_bf16 v[76:79], v[140:143], v[202:205], v[76:79]
	v_mfma_f32_16x16x32_bf16 v[72:75], v[154:157], v[202:205], v[72:75]
	v_mfma_f32_16x16x32_bf16 v[124:127], v[150:153], v[182:185], v[124:127]
	v_mfma_f32_16x16x32_bf16 v[120:123], v[158:161], v[182:185], v[120:123]
	v_mfma_f32_16x16x32_bf16 v[108:111], v[150:153], v[190:193], v[108:111]
	v_mfma_f32_16x16x32_bf16 v[104:107], v[158:161], v[190:193], v[104:107]
	v_mfma_f32_16x16x32_bf16 v[92:95], v[150:153], v[198:201], v[92:95]
	v_mfma_f32_16x16x32_bf16 v[88:91], v[158:161], v[198:201], v[88:91]
	v_mfma_f32_16x16x32_bf16 v[76:79], v[150:153], v[208:211], v[76:79]
	v_mfma_f32_16x16x32_bf16 v[72:75], v[158:161], v[208:211], v[72:75]
	v_mfma_f32_16x16x32_bf16 v[116:119], v[162:165], v[178:181], v[116:119]
	v_mfma_f32_16x16x32_bf16 v[112:115], v[170:173], v[178:181], v[112:115]
	v_mfma_f32_16x16x32_bf16 v[100:103], v[162:165], v[186:189], v[100:103]
	v_mfma_f32_16x16x32_bf16 v[96:99], v[170:173], v[186:189], v[96:99]
	v_mfma_f32_16x16x32_bf16 v[84:87], v[162:165], v[194:197], v[84:87]
	v_mfma_f32_16x16x32_bf16 v[80:83], v[170:173], v[194:197], v[80:83]
	v_mfma_f32_16x16x32_bf16 v[68:71], v[162:165], v[202:205], v[68:71]
	v_mfma_f32_16x16x32_bf16 v[64:67], v[170:173], v[202:205], v[64:67]
	v_mfma_f32_16x16x32_bf16 v[116:119], v[166:169], v[182:185], v[116:119]
	v_mfma_f32_16x16x32_bf16 v[112:115], v[174:177], v[182:185], v[112:115]
	v_mfma_f32_16x16x32_bf16 v[100:103], v[166:169], v[190:193], v[100:103]
	v_mfma_f32_16x16x32_bf16 v[96:99], v[174:177], v[190:193], v[96:99]
	v_mfma_f32_16x16x32_bf16 v[84:87], v[166:169], v[198:201], v[84:87]
	v_mfma_f32_16x16x32_bf16 v[80:83], v[174:177], v[198:201], v[80:83]
	v_mfma_f32_16x16x32_bf16 v[68:71], v[166:169], v[208:211], v[68:71]
	v_mfma_f32_16x16x32_bf16 v[64:67], v[174:177], v[208:211], v[64:67]
	s_barrier
	s_add_i32 s28, s59, s43
	s_mov_b32 m0, s28
	ds_read_b128 v[178:181], v149 offset:49152
	ds_read_b128 v[182:185], v149 offset:50176
	ds_read_b128 v[186:189], v149 offset:51200
	ds_read_b128 v[190:193], v149 offset:52224
	ds_read_b128 v[194:197], v149 offset:53248
	ds_read_b128 v[198:201], v149 offset:54272
	ds_read_b128 v[202:205], v149 offset:55296
	ds_read_b128 v[208:211], v149 offset:56320
	global_load_lds_dwordx4 v212, s[34:35]
	s_add_i32 m0, s28, 0x2000
	s_add_u32 s28, s34, 0x40080
	s_addc_u32 s29, s35, 0
	s_add_i32 s34, s60, s43
	global_load_lds_dwordx4 v213, s[98:99]
	s_mov_b32 m0, s34
	s_nop 0
	global_load_lds_dwordx4 v128, s[28:29]
	s_add_i32 m0, s34, 0x2000
	s_nop 0
	global_load_lds_dwordx4 v130, s[28:29]
	s_mov_b32 m0, s49
	s_nop 0
	global_load_lds_dwordx4 v212, s[36:37]
	s_mov_b32 m0, s50
	s_nop 0
	global_load_lds_dwordx4 v213, s[36:37]
	s_waitcnt vmcnt(8)
	s_waitcnt lgkmcnt(0)
	s_barrier
	s_waitcnt lgkmcnt(0)
	v_mfma_f32_16x16x32_bf16 v[60:63], v[140:143], v[178:181], v[60:63]
	v_mfma_f32_16x16x32_bf16 v[56:59], v[154:157], v[178:181], v[56:59]
	v_mfma_f32_16x16x32_bf16 v[44:47], v[140:143], v[186:189], v[44:47]
	v_mfma_f32_16x16x32_bf16 v[40:43], v[154:157], v[186:189], v[40:43]
	v_mfma_f32_16x16x32_bf16 v[28:31], v[140:143], v[194:197], v[28:31]
	v_mfma_f32_16x16x32_bf16 v[24:27], v[154:157], v[194:197], v[24:27]
	v_mfma_f32_16x16x32_bf16 v[12:15], v[140:143], v[202:205], v[12:15]
	v_mfma_f32_16x16x32_bf16 v[8:11], v[154:157], v[202:205], v[8:11]
	v_mfma_f32_16x16x32_bf16 v[60:63], v[150:153], v[182:185], v[60:63]
	v_mfma_f32_16x16x32_bf16 v[56:59], v[158:161], v[182:185], v[56:59]
	v_mfma_f32_16x16x32_bf16 v[44:47], v[150:153], v[190:193], v[44:47]
	v_mfma_f32_16x16x32_bf16 v[40:43], v[158:161], v[190:193], v[40:43]
	v_mfma_f32_16x16x32_bf16 v[28:31], v[150:153], v[198:201], v[28:31]
	v_mfma_f32_16x16x32_bf16 v[24:27], v[158:161], v[198:201], v[24:27]
	v_mfma_f32_16x16x32_bf16 v[12:15], v[150:153], v[208:211], v[12:15]
	v_mfma_f32_16x16x32_bf16 v[8:11], v[158:161], v[208:211], v[8:11]
	v_mfma_f32_16x16x32_bf16 v[52:55], v[162:165], v[178:181], v[52:55]
	v_mfma_f32_16x16x32_bf16 v[48:51], v[170:173], v[178:181], v[48:51]
	v_mfma_f32_16x16x32_bf16 v[36:39], v[162:165], v[186:189], v[36:39]
	v_mfma_f32_16x16x32_bf16 v[32:35], v[170:173], v[186:189], v[32:35]
	v_mfma_f32_16x16x32_bf16 v[20:23], v[162:165], v[194:197], v[20:23]
	v_mfma_f32_16x16x32_bf16 v[16:19], v[170:173], v[194:197], v[16:19]
	v_mfma_f32_16x16x32_bf16 v[4:7], v[162:165], v[202:205], v[4:7]
	v_mfma_f32_16x16x32_bf16 v[0:3], v[170:173], v[202:205], v[0:3]
	v_mfma_f32_16x16x32_bf16 v[52:55], v[166:169], v[182:185], v[52:55]
	v_mfma_f32_16x16x32_bf16 v[48:51], v[174:177], v[182:185], v[48:51]
	v_mfma_f32_16x16x32_bf16 v[36:39], v[166:169], v[190:193], v[36:39]
	v_mfma_f32_16x16x32_bf16 v[32:35], v[174:177], v[190:193], v[32:35]
	v_mfma_f32_16x16x32_bf16 v[20:23], v[166:169], v[198:201], v[20:23]
	v_mfma_f32_16x16x32_bf16 v[16:19], v[174:177], v[198:201], v[16:19]
	v_mfma_f32_16x16x32_bf16 v[4:7], v[166:169], v[208:211], v[4:7]
	v_mfma_f32_16x16x32_bf16 v[0:3], v[174:177], v[208:211], v[0:3]
	s_barrier
	s_add_i32 s58, s58, 2
	s_add_u32 s56, s56, 0x100
	s_addc_u32 s57, s57, 0
	s_cmp_gt_u32 s58, 13
	s_mov_b64 s[28:29], s[30:31]
	s_cbranch_scc0 .LBB0_606
	s_setprio 0
	s_and_b64 vcc, exec, s[16:17]
	s_cbranch_vccz .LBB0_609
	s_barrier

.LBB0_699:
	ds_read_b128 v[144:147], v151
	ds_read_b128 v[156:159], v151 offset:1024
	ds_read_b128 v[160:163], v151 offset:2048
	ds_read_b128 v[164:167], v151 offset:3072
	ds_read_b128 v[168:171], v152
	ds_read_b128 v[172:175], v152 offset:1024
	ds_read_b128 v[176:179], v152 offset:2048
	ds_read_b128 v[180:183], v152 offset:3072
	s_add_u32 s28, s26, 0xfffc0080
	s_addc_u32 s29, s27, -1
	s_cmp_eq_u32 s53, 12
	s_cselect_b32 s31, s21, s29
	s_cselect_b32 s30, s49, s28
	s_cselect_b32 s29, s19, s52
	s_cselect_b32 s28, s50, s51
	s_add_i32 m0, s39, 0xc000
	ds_read_b128 v[184:187], v153
	ds_read_b128 v[188:191], v153 offset:1024
	ds_read_b128 v[192:195], v153 offset:2048
	ds_read_b128 v[196:199], v153 offset:3072
	ds_read_b128 v[200:203], v153 offset:4096
	ds_read_b128 v[208:211], v153 offset:5120
	ds_read_b128 v[212:215], v153 offset:6144
	ds_read_b128 v[216:219], v153 offset:7168
	global_load_lds_dwordx4 v138, s[26:27]
	s_add_i32 m0, s39, 0xe000
	s_nop 0
	global_load_lds_dwordx4 v136, s[26:27]
	s_waitcnt vmcnt(8)
	s_waitcnt lgkmcnt(0)
	s_barrier
	s_waitcnt lgkmcnt(0)
	v_mfma_f32_16x16x32_bf16 v[124:127], v[144:147], v[184:187], v[124:127]
	v_mfma_f32_16x16x32_bf16 v[120:123], v[160:163], v[184:187], v[120:123]
	v_mfma_f32_16x16x32_bf16 v[108:111], v[144:147], v[192:195], v[108:111]
	v_mfma_f32_16x16x32_bf16 v[104:107], v[160:163], v[192:195], v[104:107]
	v_mfma_f32_16x16x32_bf16 v[92:95], v[144:147], v[200:203], v[92:95]
	v_mfma_f32_16x16x32_bf16 v[88:91], v[160:163], v[200:203], v[88:91]
	v_mfma_f32_16x16x32_bf16 v[76:79], v[144:147], v[212:215], v[76:79]
	v_mfma_f32_16x16x32_bf16 v[72:75], v[160:163], v[212:215], v[72:75]
	v_mfma_f32_16x16x32_bf16 v[124:127], v[156:159], v[188:191], v[124:127]
	v_mfma_f32_16x16x32_bf16 v[120:123], v[164:167], v[188:191], v[120:123]
	v_mfma_f32_16x16x32_bf16 v[108:111], v[156:159], v[196:199], v[108:111]
	v_mfma_f32_16x16x32_bf16 v[104:107], v[164:167], v[196:199], v[104:107]
	v_mfma_f32_16x16x32_bf16 v[92:95], v[156:159], v[208:211], v[92:95]
	v_mfma_f32_16x16x32_bf16 v[88:91], v[164:167], v[208:211], v[88:91]
	v_mfma_f32_16x16x32_bf16 v[76:79], v[156:159], v[216:219], v[76:79]
	v_mfma_f32_16x16x32_bf16 v[72:75], v[164:167], v[216:219], v[72:75]
	v_mfma_f32_16x16x32_bf16 v[116:119], v[168:171], v[184:187], v[116:119]
	v_mfma_f32_16x16x32_bf16 v[112:115], v[176:179], v[184:187], v[112:115]
	v_mfma_f32_16x16x32_bf16 v[100:103], v[168:171], v[192:195], v[100:103]
	v_mfma_f32_16x16x32_bf16 v[96:99], v[176:179], v[192:195], v[96:99]
	v_mfma_f32_16x16x32_bf16 v[84:87], v[168:171], v[200:203], v[84:87]
	v_mfma_f32_16x16x32_bf16 v[80:83], v[176:179], v[200:203], v[80:83]
	v_mfma_f32_16x16x32_bf16 v[68:71], v[168:171], v[212:215], v[68:71]
	v_mfma_f32_16x16x32_bf16 v[64:67], v[176:179], v[212:215], v[64:67]
	v_mfma_f32_16x16x32_bf16 v[116:119], v[172:175], v[188:191], v[116:119]
	v_mfma_f32_16x16x32_bf16 v[112:115], v[180:183], v[188:191], v[112:115]
	v_mfma_f32_16x16x32_bf16 v[100:103], v[172:175], v[196:199], v[100:103]
	v_mfma_f32_16x16x32_bf16 v[96:99], v[180:183], v[196:199], v[96:99]
	v_mfma_f32_16x16x32_bf16 v[84:87], v[172:175], v[208:211], v[84:87]
	v_mfma_f32_16x16x32_bf16 v[80:83], v[180:183], v[208:211], v[80:83]
	v_mfma_f32_16x16x32_bf16 v[68:71], v[172:175], v[216:219], v[68:71]
	v_mfma_f32_16x16x32_bf16 v[64:67], v[180:183], v[216:219], v[64:67]
	s_barrier
	s_add_i32 s54, s46, s38
	s_mov_b32 m0, s54
	ds_read_b128 v[184:187], v153 offset:16384
	ds_read_b128 v[188:191], v153 offset:17408
	ds_read_b128 v[192:195], v153 offset:18432
	ds_read_b128 v[196:199], v153 offset:19456
	ds_read_b128 v[200:203], v153 offset:20480
	ds_read_b128 v[208:211], v153 offset:21504
	ds_read_b128 v[212:215], v153 offset:22528
	ds_read_b128 v[216:219], v153 offset:23552
	global_load_lds_dwordx4 v130, s[28:29]
	s_add_i32 m0, s54, 0x2000
	s_add_u32 s54, s28, 0x40000
	s_mov_b64 s[98:99], s[28:29]
	s_addc_u32 s55, s29, 0
	s_add_i32 s56, s47, s38
	global_load_lds_dwordx4 v134, s[28:29]
	s_mov_b32 m0, s56
	s_mov_b64 s[100:101], s[30:31]
	global_load_lds_dwordx4 v130, s[54:55]
	s_waitcnt vmcnt(5)
	s_waitcnt lgkmcnt(0)
	s_barrier
	s_waitcnt lgkmcnt(0)
	v_mfma_f32_16x16x32_bf16 v[60:63], v[144:147], v[184:187], v[60:63]
	v_mfma_f32_16x16x32_bf16 v[56:59], v[160:163], v[184:187], v[56:59]
	v_mfma_f32_16x16x32_bf16 v[44:47], v[144:147], v[192:195], v[44:47]
	v_mfma_f32_16x16x32_bf16 v[40:43], v[160:163], v[192:195], v[40:43]
	v_mfma_f32_16x16x32_bf16 v[28:31], v[144:147], v[200:203], v[28:31]
	v_mfma_f32_16x16x32_bf16 v[24:27], v[160:163], v[200:203], v[24:27]
	v_mfma_f32_16x16x32_bf16 v[12:15], v[144:147], v[212:215], v[12:15]
	v_mfma_f32_16x16x32_bf16 v[8:11], v[160:163], v[212:215], v[8:11]
	v_mfma_f32_16x16x32_bf16 v[60:63], v[156:159], v[188:191], v[60:63]
	v_mfma_f32_16x16x32_bf16 v[56:59], v[164:167], v[188:191], v[56:59]
	v_mfma_f32_16x16x32_bf16 v[44:47], v[156:159], v[196:199], v[44:47]
	v_mfma_f32_16x16x32_bf16 v[40:43], v[164:167], v[196:199], v[40:43]
	v_mfma_f32_16x16x32_bf16 v[28:31], v[156:159], v[208:211], v[28:31]
	v_mfma_f32_16x16x32_bf16 v[24:27], v[164:167], v[208:211], v[24:27]
	v_mfma_f32_16x16x32_bf16 v[12:15], v[156:159], v[216:219], v[12:15]
	v_mfma_f32_16x16x32_bf16 v[8:11], v[164:167], v[216:219], v[8:11]
	v_mfma_f32_16x16x32_bf16 v[52:55], v[168:171], v[184:187], v[52:55]
	v_mfma_f32_16x16x32_bf16 v[48:51], v[176:179], v[184:187], v[48:51]
	v_mfma_f32_16x16x32_bf16 v[36:39], v[168:171], v[192:195], v[36:39]
	v_mfma_f32_16x16x32_bf16 v[32:35], v[176:179], v[192:195], v[32:35]
	v_mfma_f32_16x16x32_bf16 v[20:23], v[168:171], v[200:203], v[20:23]
	v_mfma_f32_16x16x32_bf16 v[16:19], v[176:179], v[200:203], v[16:19]
	v_mfma_f32_16x16x32_bf16 v[4:7], v[168:171], v[212:215], v[4:7]
	v_mfma_f32_16x16x32_bf16 v[0:3], v[176:179], v[212:215], v[0:3]
	v_mfma_f32_16x16x32_bf16 v[52:55], v[172:175], v[188:191], v[52:55]
	v_mfma_f32_16x16x32_bf16 v[48:51], v[180:183], v[188:191], v[48:51]
	v_mfma_f32_16x16x32_bf16 v[36:39], v[172:175], v[196:199], v[36:39]
	v_mfma_f32_16x16x32_bf16 v[32:35], v[180:183], v[196:199], v[32:35]
	v_mfma_f32_16x16x32_bf16 v[20:23], v[172:175], v[208:211], v[20:23]
	v_mfma_f32_16x16x32_bf16 v[16:19], v[180:183], v[208:211], v[16:19]
	v_mfma_f32_16x16x32_bf16 v[4:7], v[172:175], v[216:219], v[4:7]
	v_mfma_f32_16x16x32_bf16 v[0:3], v[180:183], v[216:219], v[0:3]
	s_barrier
	s_add_i32 m0, s56, 0x2000
	s_nop 0
	global_load_lds_dwordx4 v134, s[54:55]
	s_mov_b32 m0, s39
	s_nop 0
	global_load_lds_dwordx4 v128, s[30:31]
	s_mov_b32 m0, s40
	s_nop 0
	global_load_lds_dwordx4 v132, s[30:31]
	s_add_i32 s54, 0, 0x18000
	v_add_u32_e32 v155, s54, v149
	s_add_i32 s55, 0, 0x1c000
	ds_read_b128 v[144:147], v155
	ds_read_b128 v[156:159], v155 offset:1024
	ds_read_b128 v[160:163], v155 offset:2048
	ds_read_b128 v[164:167], v155 offset:3072
	v_add_u32_e32 v155, s55, v149
	ds_read_b128 v[168:171], v155
	ds_read_b128 v[172:175], v155 offset:1024
	ds_read_b128 v[176:179], v155 offset:2048
	ds_read_b128 v[180:183], v155 offset:3072
	s_add_u32 s30, s30, 0x40000
	s_addc_u32 s31, s31, 0
	s_mov_b32 m0, s41
	ds_read_b128 v[184:187], v153 offset:32768
	ds_read_b128 v[188:191], v153 offset:33792
	ds_read_b128 v[192:195], v153 offset:34816
	ds_read_b128 v[196:199], v153 offset:35840
	ds_read_b128 v[200:203], v153 offset:36864
	ds_read_b128 v[208:211], v153 offset:37888
	ds_read_b128 v[212:215], v153 offset:38912
	ds_read_b128 v[216:219], v153 offset:39936
	global_load_lds_dwordx4 v128, s[30:31]
	s_mov_b32 m0, s42
	s_nop 0
	global_load_lds_dwordx4 v132, s[30:31]
	s_waitcnt vmcnt(8)
	s_waitcnt lgkmcnt(0)
	s_barrier
	s_waitcnt lgkmcnt(0)
	v_mfma_f32_16x16x32_bf16 v[124:127], v[144:147], v[184:187], v[124:127]
	v_mfma_f32_16x16x32_bf16 v[120:123], v[160:163], v[184:187], v[120:123]
	v_mfma_f32_16x16x32_bf16 v[108:111], v[144:147], v[192:195], v[108:111]
	v_mfma_f32_16x16x32_bf16 v[104:107], v[160:163], v[192:195], v[104:107]
	v_mfma_f32_16x16x32_bf16 v[92:95], v[144:147], v[200:203], v[92:95]
	v_mfma_f32_16x16x32_bf16 v[88:91], v[160:163], v[200:203], v[88:91]
	v_mfma_f32_16x16x32_bf16 v[76:79], v[144:147], v[212:215], v[76:79]
	v_mfma_f32_16x16x32_bf16 v[72:75], v[160:163], v[212:215], v[72:75]
	v_mfma_f32_16x16x32_bf16 v[124:127], v[156:159], v[188:191], v[124:127]
	v_mfma_f32_16x16x32_bf16 v[120:123], v[164:167], v[188:191], v[120:123]
	v_mfma_f32_16x16x32_bf16 v[108:111], v[156:159], v[196:199], v[108:111]
	v_mfma_f32_16x16x32_bf16 v[104:107], v[164:167], v[196:199], v[104:107]
	v_mfma_f32_16x16x32_bf16 v[92:95], v[156:159], v[208:211], v[92:95]
	v_mfma_f32_16x16x32_bf16 v[88:91], v[164:167], v[208:211], v[88:91]
	v_mfma_f32_16x16x32_bf16 v[76:79], v[156:159], v[216:219], v[76:79]
	v_mfma_f32_16x16x32_bf16 v[72:75], v[164:167], v[216:219], v[72:75]
	v_mfma_f32_16x16x32_bf16 v[116:119], v[168:171], v[184:187], v[116:119]
	v_mfma_f32_16x16x32_bf16 v[112:115], v[176:179], v[184:187], v[112:115]
	v_mfma_f32_16x16x32_bf16 v[100:103], v[168:171], v[192:195], v[100:103]
	v_mfma_f32_16x16x32_bf16 v[96:99], v[176:179], v[192:195], v[96:99]
	v_mfma_f32_16x16x32_bf16 v[84:87], v[168:171], v[200:203], v[84:87]
	v_mfma_f32_16x16x32_bf16 v[80:83], v[176:179], v[200:203], v[80:83]
	v_mfma_f32_16x16x32_bf16 v[68:71], v[168:171], v[212:215], v[68:71]
	v_mfma_f32_16x16x32_bf16 v[64:67], v[176:179], v[212:215], v[64:67]
	v_mfma_f32_16x16x32_bf16 v[116:119], v[172:175], v[188:191], v[116:119]
	v_mfma_f32_16x16x32_bf16 v[112:115], v[180:183], v[188:191], v[112:115]
	v_mfma_f32_16x16x32_bf16 v[100:103], v[172:175], v[196:199], v[100:103]
	v_mfma_f32_16x16x32_bf16 v[96:99], v[180:183], v[196:199], v[96:99]
	v_mfma_f32_16x16x32_bf16 v[84:87], v[172:175], v[208:211], v[84:87]
	v_mfma_f32_16x16x32_bf16 v[80:83], v[180:183], v[208:211], v[80:83]
	v_mfma_f32_16x16x32_bf16 v[68:71], v[172:175], v[216:219], v[68:71]
	v_mfma_f32_16x16x32_bf16 v[64:67], v[180:183], v[216:219], v[64:67]
	s_barrier
	s_add_i32 s30, s54, s38
	s_mov_b32 m0, s30
	ds_read_b128 v[184:187], v153 offset:49152
	ds_read_b128 v[188:191], v153 offset:50176
	ds_read_b128 v[192:195], v153 offset:51200
	ds_read_b128 v[196:199], v153 offset:52224
	ds_read_b128 v[200:203], v153 offset:53248
	ds_read_b128 v[208:211], v153 offset:54272
	ds_read_b128 v[212:215], v153 offset:55296
	ds_read_b128 v[216:219], v153 offset:56320
	global_load_lds_dwordx4 v205, s[28:29]
	s_add_i32 m0, s30, 0x2000
	s_add_u32 s28, s28, 0x40080
	s_addc_u32 s29, s29, 0
	s_add_i32 s30, s55, s38
	global_load_lds_dwordx4 v221, s[98:99]
	s_mov_b32 m0, s30
	s_nop 0
	global_load_lds_dwordx4 v130, s[28:29]
	s_add_i32 m0, s30, 0x2000
	s_nop 0
	global_load_lds_dwordx4 v134, s[28:29]
	s_mov_b32 m0, s44
	s_nop 0
	global_load_lds_dwordx4 v204, s[100:101]
	s_mov_b32 m0, s45
	s_nop 0
	global_load_lds_dwordx4 v220, s[100:101]
	s_waitcnt vmcnt(8)
	s_waitcnt lgkmcnt(0)
	s_barrier
	s_waitcnt lgkmcnt(0)
	v_mfma_f32_16x16x32_bf16 v[60:63], v[144:147], v[184:187], v[60:63]
	v_mfma_f32_16x16x32_bf16 v[56:59], v[160:163], v[184:187], v[56:59]
	v_mfma_f32_16x16x32_bf16 v[44:47], v[144:147], v[192:195], v[44:47]
	v_mfma_f32_16x16x32_bf16 v[40:43], v[160:163], v[192:195], v[40:43]
	v_mfma_f32_16x16x32_bf16 v[28:31], v[144:147], v[200:203], v[28:31]
	v_mfma_f32_16x16x32_bf16 v[24:27], v[160:163], v[200:203], v[24:27]
	v_mfma_f32_16x16x32_bf16 v[12:15], v[144:147], v[212:215], v[12:15]
	v_mfma_f32_16x16x32_bf16 v[8:11], v[160:163], v[212:215], v[8:11]
	v_mfma_f32_16x16x32_bf16 v[60:63], v[156:159], v[188:191], v[60:63]
	v_mfma_f32_16x16x32_bf16 v[56:59], v[164:167], v[188:191], v[56:59]
	v_mfma_f32_16x16x32_bf16 v[44:47], v[156:159], v[196:199], v[44:47]
	v_mfma_f32_16x16x32_bf16 v[40:43], v[164:167], v[196:199], v[40:43]
	v_mfma_f32_16x16x32_bf16 v[28:31], v[156:159], v[208:211], v[28:31]
	v_mfma_f32_16x16x32_bf16 v[24:27], v[164:167], v[208:211], v[24:27]
	v_mfma_f32_16x16x32_bf16 v[12:15], v[156:159], v[216:219], v[12:15]
	v_mfma_f32_16x16x32_bf16 v[8:11], v[164:167], v[216:219], v[8:11]
	v_mfma_f32_16x16x32_bf16 v[52:55], v[168:171], v[184:187], v[52:55]
	v_mfma_f32_16x16x32_bf16 v[48:51], v[176:179], v[184:187], v[48:51]
	v_mfma_f32_16x16x32_bf16 v[36:39], v[168:171], v[192:195], v[36:39]
	v_mfma_f32_16x16x32_bf16 v[32:35], v[176:179], v[192:195], v[32:35]
	v_mfma_f32_16x16x32_bf16 v[20:23], v[168:171], v[200:203], v[20:23]
	v_mfma_f32_16x16x32_bf16 v[16:19], v[176:179], v[200:203], v[16:19]
	v_mfma_f32_16x16x32_bf16 v[4:7], v[168:171], v[212:215], v[4:7]
	v_mfma_f32_16x16x32_bf16 v[0:3], v[176:179], v[212:215], v[0:3]
	v_mfma_f32_16x16x32_bf16 v[52:55], v[172:175], v[188:191], v[52:55]
	v_mfma_f32_16x16x32_bf16 v[48:51], v[180:183], v[188:191], v[48:51]
	v_mfma_f32_16x16x32_bf16 v[36:39], v[172:175], v[196:199], v[36:39]
	v_mfma_f32_16x16x32_bf16 v[32:35], v[180:183], v[196:199], v[32:35]
	v_mfma_f32_16x16x32_bf16 v[20:23], v[172:175], v[208:211], v[20:23]
	v_mfma_f32_16x16x32_bf16 v[16:19], v[180:183], v[208:211], v[16:19]
	v_mfma_f32_16x16x32_bf16 v[4:7], v[172:175], v[216:219], v[4:7]
	v_mfma_f32_16x16x32_bf16 v[0:3], v[180:183], v[216:219], v[0:3]
	s_barrier
	s_add_i32 s53, s53, 2
	s_add_u32 s51, s51, 0x100
	s_addc_u32 s52, s52, 0
	s_add_u32 s26, s26, 0x100
	s_addc_u32 s27, s27, 0
	s_cmp_gt_u32 s53, 13
	s_cbranch_scc0 .LBB0_699
	s_setprio 0
	s_and_b64 vcc, exec, s[16:17]
	s_cbranch_vccz .LBB0_702
	s_barrier

.LBB0_778:
	ds_read_b128 v[140:143], v147
	ds_read_b128 v[150:153], v147 offset:1024
	ds_read_b128 v[154:157], v147 offset:2048
	ds_read_b128 v[158:161], v147 offset:3072
	ds_read_b128 v[162:165], v148
	ds_read_b128 v[166:169], v148 offset:1024
	ds_read_b128 v[170:173], v148 offset:2048
	ds_read_b128 v[174:177], v148 offset:3072
	s_add_u32 s30, s28, 0x100
	s_addc_u32 s31, s29, 0
	s_cmp_eq_u32 s58, 60
	s_cselect_b32 s37, s21, s31
	s_cselect_b32 s36, s27, s30
	s_cselect_b32 s35, s19, s57
	s_cselect_b32 s34, s55, s56
	s_add_i32 m0, s44, 0xc000
	ds_read_b128 v[178:181], v149
	ds_read_b128 v[182:185], v149 offset:1024
	ds_read_b128 v[186:189], v149 offset:2048
	ds_read_b128 v[190:193], v149 offset:3072
	ds_read_b128 v[194:197], v149 offset:4096
	ds_read_b128 v[198:201], v149 offset:5120
	ds_read_b128 v[202:205], v149 offset:6144
	ds_read_b128 v[208:211], v149 offset:7168
	global_load_lds_dwordx4 v134, s[28:29]
	s_add_i32 m0, s44, 0xe000
	s_nop 0
	global_load_lds_dwordx4 v132, s[28:29]
	s_waitcnt vmcnt(8)
	s_waitcnt lgkmcnt(0)
	s_barrier
	s_waitcnt lgkmcnt(0)
	v_mfma_f32_16x16x32_bf16 v[124:127], v[140:143], v[178:181], v[124:127]
	v_mfma_f32_16x16x32_bf16 v[120:123], v[154:157], v[178:181], v[120:123]
	v_mfma_f32_16x16x32_bf16 v[108:111], v[140:143], v[186:189], v[108:111]
	v_mfma_f32_16x16x32_bf16 v[104:107], v[154:157], v[186:189], v[104:107]
	v_mfma_f32_16x16x32_bf16 v[92:95], v[140:143], v[194:197], v[92:95]
	v_mfma_f32_16x16x32_bf16 v[88:91], v[154:157], v[194:197], v[88:91]
	v_mfma_f32_16x16x32_bf16 v[76:79], v[140:143], v[202:205], v[76:79]
	v_mfma_f32_16x16x32_bf16 v[72:75], v[154:157], v[202:205], v[72:75]
	v_mfma_f32_16x16x32_bf16 v[124:127], v[150:153], v[182:185], v[124:127]
	v_mfma_f32_16x16x32_bf16 v[120:123], v[158:161], v[182:185], v[120:123]
	v_mfma_f32_16x16x32_bf16 v[108:111], v[150:153], v[190:193], v[108:111]
	v_mfma_f32_16x16x32_bf16 v[104:107], v[158:161], v[190:193], v[104:107]
	v_mfma_f32_16x16x32_bf16 v[92:95], v[150:153], v[198:201], v[92:95]
	v_mfma_f32_16x16x32_bf16 v[88:91], v[158:161], v[198:201], v[88:91]
	v_mfma_f32_16x16x32_bf16 v[76:79], v[150:153], v[208:211], v[76:79]
	v_mfma_f32_16x16x32_bf16 v[72:75], v[158:161], v[208:211], v[72:75]
	v_mfma_f32_16x16x32_bf16 v[116:119], v[162:165], v[178:181], v[116:119]
	v_mfma_f32_16x16x32_bf16 v[112:115], v[170:173], v[178:181], v[112:115]
	v_mfma_f32_16x16x32_bf16 v[100:103], v[162:165], v[186:189], v[100:103]
	v_mfma_f32_16x16x32_bf16 v[96:99], v[170:173], v[186:189], v[96:99]
	v_mfma_f32_16x16x32_bf16 v[84:87], v[162:165], v[194:197], v[84:87]
	v_mfma_f32_16x16x32_bf16 v[80:83], v[170:173], v[194:197], v[80:83]
	v_mfma_f32_16x16x32_bf16 v[68:71], v[162:165], v[202:205], v[68:71]
	v_mfma_f32_16x16x32_bf16 v[64:67], v[170:173], v[202:205], v[64:67]
	v_mfma_f32_16x16x32_bf16 v[116:119], v[166:169], v[182:185], v[116:119]
	v_mfma_f32_16x16x32_bf16 v[112:115], v[174:177], v[182:185], v[112:115]
	v_mfma_f32_16x16x32_bf16 v[100:103], v[166:169], v[190:193], v[100:103]
	v_mfma_f32_16x16x32_bf16 v[96:99], v[174:177], v[190:193], v[96:99]
	v_mfma_f32_16x16x32_bf16 v[84:87], v[166:169], v[198:201], v[84:87]
	v_mfma_f32_16x16x32_bf16 v[80:83], v[174:177], v[198:201], v[80:83]
	v_mfma_f32_16x16x32_bf16 v[68:71], v[166:169], v[208:211], v[68:71]
	v_mfma_f32_16x16x32_bf16 v[64:67], v[174:177], v[208:211], v[64:67]
	s_barrier
	s_add_i32 s28, s52, s43
	s_mov_b32 m0, s28
	ds_read_b128 v[178:181], v149 offset:16384
	ds_read_b128 v[182:185], v149 offset:17408
	ds_read_b128 v[186:189], v149 offset:18432
	ds_read_b128 v[190:193], v149 offset:19456
	ds_read_b128 v[194:197], v149 offset:20480
	ds_read_b128 v[198:201], v149 offset:21504
	ds_read_b128 v[202:205], v149 offset:22528
	ds_read_b128 v[208:211], v149 offset:23552
	global_load_lds_dwordx4 v128, s[34:35]
	s_add_i32 m0, s28, 0x2000
	s_add_u32 s28, s34, 0x100000
	s_mov_b64 s[98:99], s[34:35]
	s_addc_u32 s29, s35, 0
	s_add_i32 s59, s53, s43
	global_load_lds_dwordx4 v130, s[34:35]
	s_mov_b32 m0, s59
	s_nop 0
	global_load_lds_dwordx4 v128, s[28:29]
	s_waitcnt vmcnt(5)
	s_waitcnt lgkmcnt(0)
	s_barrier
	s_waitcnt lgkmcnt(0)
	v_mfma_f32_16x16x32_bf16 v[60:63], v[140:143], v[178:181], v[60:63]
	v_mfma_f32_16x16x32_bf16 v[56:59], v[154:157], v[178:181], v[56:59]
	v_mfma_f32_16x16x32_bf16 v[44:47], v[140:143], v[186:189], v[44:47]
	v_mfma_f32_16x16x32_bf16 v[40:43], v[154:157], v[186:189], v[40:43]
	v_mfma_f32_16x16x32_bf16 v[28:31], v[140:143], v[194:197], v[28:31]
	v_mfma_f32_16x16x32_bf16 v[24:27], v[154:157], v[194:197], v[24:27]
	v_mfma_f32_16x16x32_bf16 v[12:15], v[140:143], v[202:205], v[12:15]
	v_mfma_f32_16x16x32_bf16 v[8:11], v[154:157], v[202:205], v[8:11]
	v_mfma_f32_16x16x32_bf16 v[60:63], v[150:153], v[182:185], v[60:63]
	v_mfma_f32_16x16x32_bf16 v[56:59], v[158:161], v[182:185], v[56:59]
	v_mfma_f32_16x16x32_bf16 v[44:47], v[150:153], v[190:193], v[44:47]
	v_mfma_f32_16x16x32_bf16 v[40:43], v[158:161], v[190:193], v[40:43]
	v_mfma_f32_16x16x32_bf16 v[28:31], v[150:153], v[198:201], v[28:31]
	v_mfma_f32_16x16x32_bf16 v[24:27], v[158:161], v[198:201], v[24:27]
	v_mfma_f32_16x16x32_bf16 v[12:15], v[150:153], v[208:211], v[12:15]
	v_mfma_f32_16x16x32_bf16 v[8:11], v[158:161], v[208:211], v[8:11]
	v_mfma_f32_16x16x32_bf16 v[52:55], v[162:165], v[178:181], v[52:55]
	v_mfma_f32_16x16x32_bf16 v[48:51], v[170:173], v[178:181], v[48:51]
	v_mfma_f32_16x16x32_bf16 v[36:39], v[162:165], v[186:189], v[36:39]
	v_mfma_f32_16x16x32_bf16 v[32:35], v[170:173], v[186:189], v[32:35]
	v_mfma_f32_16x16x32_bf16 v[20:23], v[162:165], v[194:197], v[20:23]
	v_mfma_f32_16x16x32_bf16 v[16:19], v[170:173], v[194:197], v[16:19]
	v_mfma_f32_16x16x32_bf16 v[4:7], v[162:165], v[202:205], v[4:7]
	v_mfma_f32_16x16x32_bf16 v[0:3], v[170:173], v[202:205], v[0:3]
	v_mfma_f32_16x16x32_bf16 v[52:55], v[166:169], v[182:185], v[52:55]
	v_mfma_f32_16x16x32_bf16 v[48:51], v[174:177], v[182:185], v[48:51]
	v_mfma_f32_16x16x32_bf16 v[36:39], v[166:169], v[190:193], v[36:39]
	v_mfma_f32_16x16x32_bf16 v[32:35], v[174:177], v[190:193], v[32:35]
	v_mfma_f32_16x16x32_bf16 v[20:23], v[166:169], v[198:201], v[20:23]
	v_mfma_f32_16x16x32_bf16 v[16:19], v[174:177], v[198:201], v[16:19]
	v_mfma_f32_16x16x32_bf16 v[4:7], v[166:169], v[208:211], v[4:7]
	v_mfma_f32_16x16x32_bf16 v[0:3], v[174:177], v[208:211], v[0:3]
	s_barrier
	s_add_i32 m0, s59, 0x2000
	s_nop 0
	global_load_lds_dwordx4 v130, s[28:29]
	s_mov_b32 m0, s44
	s_nop 0
	global_load_lds_dwordx4 v128, s[36:37]
	s_mov_b32 m0, s45
	s_nop 0
	global_load_lds_dwordx4 v130, s[36:37]
	s_add_i32 s59, 0, 0x18000
	s_add_i32 s60, 0, 0x1c000
	v_add_u32_e32 v158, s59, v145
	v_add_u32_e32 v174, s60, v145
	ds_read_b128 v[140:143], v158
	ds_read_b128 v[150:153], v158 offset:1024
	ds_read_b128 v[154:157], v158 offset:2048
	ds_read_b128 v[158:161], v158 offset:3072
	ds_read_b128 v[162:165], v174
	ds_read_b128 v[166:169], v174 offset:1024
	ds_read_b128 v[170:173], v174 offset:2048
	ds_read_b128 v[174:177], v174 offset:3072
	s_add_u32 s28, s36, 0x100000
	s_addc_u32 s29, s37, 0
	s_mov_b32 m0, s46
	ds_read_b128 v[178:181], v149 offset:32768
	ds_read_b128 v[182:185], v149 offset:33792
	ds_read_b128 v[186:189], v149 offset:34816
	ds_read_b128 v[190:193], v149 offset:35840
	ds_read_b128 v[194:197], v149 offset:36864
	ds_read_b128 v[198:201], v149 offset:37888
	ds_read_b128 v[202:205], v149 offset:38912
	ds_read_b128 v[208:211], v149 offset:39936
	global_load_lds_dwordx4 v128, s[28:29]
	s_mov_b32 m0, s47
	s_nop 0
	global_load_lds_dwordx4 v130, s[28:29]
	s_waitcnt vmcnt(8)
	s_waitcnt lgkmcnt(0)
	s_barrier
	s_waitcnt lgkmcnt(0)
	v_mfma_f32_16x16x32_bf16 v[124:127], v[140:143], v[178:181], v[124:127]
	v_mfma_f32_16x16x32_bf16 v[120:123], v[154:157], v[178:181], v[120:123]
	v_mfma_f32_16x16x32_bf16 v[108:111], v[140:143], v[186:189], v[108:111]
	v_mfma_f32_16x16x32_bf16 v[104:107], v[154:157], v[186:189], v[104:107]
	v_mfma_f32_16x16x32_bf16 v[92:95], v[140:143], v[194:197], v[92:95]
	v_mfma_f32_16x16x32_bf16 v[88:91], v[154:157], v[194:197], v[88:91]
	v_mfma_f32_16x16x32_bf16 v[76:79], v[140:143], v[202:205], v[76:79]
	v_mfma_f32_16x16x32_bf16 v[72:75], v[154:157], v[202:205], v[72:75]
	v_mfma_f32_16x16x32_bf16 v[124:127], v[150:153], v[182:185], v[124:127]
	v_mfma_f32_16x16x32_bf16 v[120:123], v[158:161], v[182:185], v[120:123]
	v_mfma_f32_16x16x32_bf16 v[108:111], v[150:153], v[190:193], v[108:111]
	v_mfma_f32_16x16x32_bf16 v[104:107], v[158:161], v[190:193], v[104:107]
	v_mfma_f32_16x16x32_bf16 v[92:95], v[150:153], v[198:201], v[92:95]
	v_mfma_f32_16x16x32_bf16 v[88:91], v[158:161], v[198:201], v[88:91]
	v_mfma_f32_16x16x32_bf16 v[76:79], v[150:153], v[208:211], v[76:79]
	v_mfma_f32_16x16x32_bf16 v[72:75], v[158:161], v[208:211], v[72:75]
	v_mfma_f32_16x16x32_bf16 v[116:119], v[162:165], v[178:181], v[116:119]
	v_mfma_f32_16x16x32_bf16 v[112:115], v[170:173], v[178:181], v[112:115]
	v_mfma_f32_16x16x32_bf16 v[100:103], v[162:165], v[186:189], v[100:103]
	v_mfma_f32_16x16x32_bf16 v[96:99], v[170:173], v[186:189], v[96:99]
	v_mfma_f32_16x16x32_bf16 v[84:87], v[162:165], v[194:197], v[84:87]
	v_mfma_f32_16x16x32_bf16 v[80:83], v[170:173], v[194:197], v[80:83]
	v_mfma_f32_16x16x32_bf16 v[68:71], v[162:165], v[202:205], v[68:71]
	v_mfma_f32_16x16x32_bf16 v[64:67], v[170:173], v[202:205], v[64:67]
	v_mfma_f32_16x16x32_bf16 v[116:119], v[166:169], v[182:185], v[116:119]
	v_mfma_f32_16x16x32_bf16 v[112:115], v[174:177], v[182:185], v[112:115]
	v_mfma_f32_16x16x32_bf16 v[100:103], v[166:169], v[190:193], v[100:103]
	v_mfma_f32_16x16x32_bf16 v[96:99], v[174:177], v[190:193], v[96:99]
	v_mfma_f32_16x16x32_bf16 v[84:87], v[166:169], v[198:201], v[84:87]
	v_mfma_f32_16x16x32_bf16 v[80:83], v[174:177], v[198:201], v[80:83]
	v_mfma_f32_16x16x32_bf16 v[68:71], v[166:169], v[208:211], v[68:71]
	v_mfma_f32_16x16x32_bf16 v[64:67], v[174:177], v[208:211], v[64:67]
	s_barrier
	s_add_i32 s28, s59, s43
	s_mov_b32 m0, s28
	ds_read_b128 v[178:181], v149 offset:49152
	ds_read_b128 v[182:185], v149 offset:50176
	ds_read_b128 v[186:189], v149 offset:51200
	ds_read_b128 v[190:193], v149 offset:52224
	ds_read_b128 v[194:197], v149 offset:53248
	ds_read_b128 v[198:201], v149 offset:54272
	ds_read_b128 v[202:205], v149 offset:55296
	ds_read_b128 v[208:211], v149 offset:56320
	global_load_lds_dwordx4 v212, s[34:35]
	s_add_i32 m0, s28, 0x2000
	s_add_u32 s28, s34, 0x100080
	s_addc_u32 s29, s35, 0
	s_add_i32 s34, s60, s43
	global_load_lds_dwordx4 v213, s[98:99]
	s_mov_b32 m0, s34
	s_nop 0
	global_load_lds_dwordx4 v128, s[28:29]
	s_add_i32 m0, s34, 0x2000
	s_nop 0
	global_load_lds_dwordx4 v130, s[28:29]
	s_mov_b32 m0, s49
	s_nop 0
	global_load_lds_dwordx4 v212, s[36:37]
	s_mov_b32 m0, s50
	s_nop 0
	global_load_lds_dwordx4 v213, s[36:37]
	s_waitcnt vmcnt(8)
	s_waitcnt lgkmcnt(0)
	s_barrier
	s_waitcnt lgkmcnt(0)
	v_mfma_f32_16x16x32_bf16 v[60:63], v[140:143], v[178:181], v[60:63]
	v_mfma_f32_16x16x32_bf16 v[56:59], v[154:157], v[178:181], v[56:59]
	v_mfma_f32_16x16x32_bf16 v[44:47], v[140:143], v[186:189], v[44:47]
	v_mfma_f32_16x16x32_bf16 v[40:43], v[154:157], v[186:189], v[40:43]
	v_mfma_f32_16x16x32_bf16 v[28:31], v[140:143], v[194:197], v[28:31]
	v_mfma_f32_16x16x32_bf16 v[24:27], v[154:157], v[194:197], v[24:27]
	v_mfma_f32_16x16x32_bf16 v[12:15], v[140:143], v[202:205], v[12:15]
	v_mfma_f32_16x16x32_bf16 v[8:11], v[154:157], v[202:205], v[8:11]
	v_mfma_f32_16x16x32_bf16 v[60:63], v[150:153], v[182:185], v[60:63]
	v_mfma_f32_16x16x32_bf16 v[56:59], v[158:161], v[182:185], v[56:59]
	v_mfma_f32_16x16x32_bf16 v[44:47], v[150:153], v[190:193], v[44:47]
	v_mfma_f32_16x16x32_bf16 v[40:43], v[158:161], v[190:193], v[40:43]
	v_mfma_f32_16x16x32_bf16 v[28:31], v[150:153], v[198:201], v[28:31]
	v_mfma_f32_16x16x32_bf16 v[24:27], v[158:161], v[198:201], v[24:27]
	v_mfma_f32_16x16x32_bf16 v[12:15], v[150:153], v[208:211], v[12:15]
	v_mfma_f32_16x16x32_bf16 v[8:11], v[158:161], v[208:211], v[8:11]
	v_mfma_f32_16x16x32_bf16 v[52:55], v[162:165], v[178:181], v[52:55]
	v_mfma_f32_16x16x32_bf16 v[48:51], v[170:173], v[178:181], v[48:51]
	v_mfma_f32_16x16x32_bf16 v[36:39], v[162:165], v[186:189], v[36:39]
	v_mfma_f32_16x16x32_bf16 v[32:35], v[170:173], v[186:189], v[32:35]
	v_mfma_f32_16x16x32_bf16 v[20:23], v[162:165], v[194:197], v[20:23]
	v_mfma_f32_16x16x32_bf16 v[16:19], v[170:173], v[194:197], v[16:19]
	v_mfma_f32_16x16x32_bf16 v[4:7], v[162:165], v[202:205], v[4:7]
	v_mfma_f32_16x16x32_bf16 v[0:3], v[170:173], v[202:205], v[0:3]
	v_mfma_f32_16x16x32_bf16 v[52:55], v[166:169], v[182:185], v[52:55]
	v_mfma_f32_16x16x32_bf16 v[48:51], v[174:177], v[182:185], v[48:51]
	v_mfma_f32_16x16x32_bf16 v[36:39], v[166:169], v[190:193], v[36:39]
	v_mfma_f32_16x16x32_bf16 v[32:35], v[174:177], v[190:193], v[32:35]
	v_mfma_f32_16x16x32_bf16 v[20:23], v[166:169], v[198:201], v[20:23]
	v_mfma_f32_16x16x32_bf16 v[16:19], v[174:177], v[198:201], v[16:19]
	v_mfma_f32_16x16x32_bf16 v[4:7], v[166:169], v[208:211], v[4:7]
	v_mfma_f32_16x16x32_bf16 v[0:3], v[174:177], v[208:211], v[0:3]
	s_barrier
	s_add_i32 s58, s58, 2
	s_add_u32 s56, s56, 0x100
	s_addc_u32 s57, s57, 0
	s_cmp_gt_u32 s58, 61
	s_mov_b64 s[28:29], s[30:31]
	s_cbranch_scc0 .LBB0_778
	s_setprio 0
	s_and_b64 vcc, exec, s[16:17]
	s_cbranch_vccz .LBB0_781
	s_barrier

.LBB0_895:
	ds_read_b128 v[140:143], v153
	ds_read_b128 v[144:147], v153 offset:1024
	ds_read_b128 v[158:161], v153 offset:2048
	ds_read_b128 v[162:165], v153 offset:3072
	ds_read_b128 v[166:169], v154
	ds_read_b128 v[170:173], v154 offset:1024
	ds_read_b128 v[174:177], v154 offset:2048
	ds_read_b128 v[178:181], v154 offset:3072
	s_add_u32 s38, s36, 0xfffc0080
	s_addc_u32 s39, s37, -1
	s_cmp_eq_u32 s61, 12
	s_cselect_b32 s41, s3, s39
	s_cselect_b32 s40, s29, s38
	s_cselect_b32 s39, s27, s60
	s_cselect_b32 s38, s58, s59
	s_add_i32 m0, s46, 0xc000
	ds_read_b128 v[182:185], v155
	ds_read_b128 v[186:189], v155 offset:1024
	ds_read_b128 v[190:193], v155 offset:2048
	ds_read_b128 v[194:197], v155 offset:3072
	ds_read_b128 v[198:201], v155 offset:4096
	ds_read_b128 v[202:205], v155 offset:5120
	ds_read_b128 v[208:211], v155 offset:6144
	ds_read_b128 v[212:215], v155 offset:7168
	global_load_lds_dwordx4 v134, s[36:37]
	s_add_i32 m0, s46, 0xe000
	s_nop 0
	global_load_lds_dwordx4 v132, s[36:37]
	s_waitcnt vmcnt(8)
	s_waitcnt lgkmcnt(0)
	s_barrier
	s_waitcnt lgkmcnt(0)
	v_mfma_f32_16x16x32_bf16 v[124:127], v[140:143], v[182:185], v[124:127]
	v_mfma_f32_16x16x32_bf16 v[120:123], v[158:161], v[182:185], v[120:123]
	v_mfma_f32_16x16x32_bf16 v[108:111], v[140:143], v[190:193], v[108:111]
	v_mfma_f32_16x16x32_bf16 v[104:107], v[158:161], v[190:193], v[104:107]
	v_mfma_f32_16x16x32_bf16 v[92:95], v[140:143], v[198:201], v[92:95]
	v_mfma_f32_16x16x32_bf16 v[88:91], v[158:161], v[198:201], v[88:91]
	v_mfma_f32_16x16x32_bf16 v[76:79], v[140:143], v[208:211], v[76:79]
	v_mfma_f32_16x16x32_bf16 v[72:75], v[158:161], v[208:211], v[72:75]
	v_mfma_f32_16x16x32_bf16 v[124:127], v[144:147], v[186:189], v[124:127]
	v_mfma_f32_16x16x32_bf16 v[120:123], v[162:165], v[186:189], v[120:123]
	v_mfma_f32_16x16x32_bf16 v[108:111], v[144:147], v[194:197], v[108:111]
	v_mfma_f32_16x16x32_bf16 v[104:107], v[162:165], v[194:197], v[104:107]
	v_mfma_f32_16x16x32_bf16 v[92:95], v[144:147], v[202:205], v[92:95]
	v_mfma_f32_16x16x32_bf16 v[88:91], v[162:165], v[202:205], v[88:91]
	v_mfma_f32_16x16x32_bf16 v[76:79], v[144:147], v[212:215], v[76:79]
	v_mfma_f32_16x16x32_bf16 v[72:75], v[162:165], v[212:215], v[72:75]
	v_mfma_f32_16x16x32_bf16 v[116:119], v[166:169], v[182:185], v[116:119]
	v_mfma_f32_16x16x32_bf16 v[112:115], v[174:177], v[182:185], v[112:115]
	v_mfma_f32_16x16x32_bf16 v[100:103], v[166:169], v[190:193], v[100:103]
	v_mfma_f32_16x16x32_bf16 v[96:99], v[174:177], v[190:193], v[96:99]
	v_mfma_f32_16x16x32_bf16 v[84:87], v[166:169], v[198:201], v[84:87]
	v_mfma_f32_16x16x32_bf16 v[80:83], v[174:177], v[198:201], v[80:83]
	v_mfma_f32_16x16x32_bf16 v[68:71], v[166:169], v[208:211], v[68:71]
	v_mfma_f32_16x16x32_bf16 v[64:67], v[174:177], v[208:211], v[64:67]
	v_mfma_f32_16x16x32_bf16 v[116:119], v[170:173], v[186:189], v[116:119]
	v_mfma_f32_16x16x32_bf16 v[112:115], v[178:181], v[186:189], v[112:115]
	v_mfma_f32_16x16x32_bf16 v[100:103], v[170:173], v[194:197], v[100:103]
	v_mfma_f32_16x16x32_bf16 v[96:99], v[178:181], v[194:197], v[96:99]
	v_mfma_f32_16x16x32_bf16 v[84:87], v[170:173], v[202:205], v[84:87]
	v_mfma_f32_16x16x32_bf16 v[80:83], v[178:181], v[202:205], v[80:83]
	v_mfma_f32_16x16x32_bf16 v[68:71], v[170:173], v[212:215], v[68:71]
	v_mfma_f32_16x16x32_bf16 v[64:67], v[178:181], v[212:215], v[64:67]
	s_barrier
	s_add_i32 s62, s54, s45
	s_mov_b32 m0, s62
	ds_read_b128 v[182:185], v155 offset:16384
	ds_read_b128 v[186:189], v155 offset:17408
	ds_read_b128 v[190:193], v155 offset:18432
	ds_read_b128 v[194:197], v155 offset:19456
	ds_read_b128 v[198:201], v155 offset:20480
	ds_read_b128 v[202:205], v155 offset:21504
	ds_read_b128 v[208:211], v155 offset:22528
	ds_read_b128 v[212:215], v155 offset:23552
	global_load_lds_dwordx4 v128, s[38:39]
	s_add_i32 m0, s62, 0x2000
	s_add_u32 s62, s38, 0x40000
	s_mov_b64 s[98:99], s[38:39]
	s_addc_u32 s63, s39, 0
	s_add_i32 s64, s55, s45
	global_load_lds_dwordx4 v130, s[38:39]
	s_mov_b32 m0, s64
	s_mov_b64 s[100:101], s[40:41]
	global_load_lds_dwordx4 v128, s[62:63]
	s_waitcnt vmcnt(5)
	s_waitcnt lgkmcnt(0)
	s_barrier
	s_waitcnt lgkmcnt(0)
	v_mfma_f32_16x16x32_bf16 v[60:63], v[140:143], v[182:185], v[60:63]
	v_mfma_f32_16x16x32_bf16 v[56:59], v[158:161], v[182:185], v[56:59]
	v_mfma_f32_16x16x32_bf16 v[44:47], v[140:143], v[190:193], v[44:47]
	v_mfma_f32_16x16x32_bf16 v[40:43], v[158:161], v[190:193], v[40:43]
	v_mfma_f32_16x16x32_bf16 v[28:31], v[140:143], v[198:201], v[28:31]
	v_mfma_f32_16x16x32_bf16 v[24:27], v[158:161], v[198:201], v[24:27]
	v_mfma_f32_16x16x32_bf16 v[12:15], v[140:143], v[208:211], v[12:15]
	v_mfma_f32_16x16x32_bf16 v[8:11], v[158:161], v[208:211], v[8:11]
	v_mfma_f32_16x16x32_bf16 v[60:63], v[144:147], v[186:189], v[60:63]
	v_mfma_f32_16x16x32_bf16 v[56:59], v[162:165], v[186:189], v[56:59]
	v_mfma_f32_16x16x32_bf16 v[44:47], v[144:147], v[194:197], v[44:47]
	v_mfma_f32_16x16x32_bf16 v[40:43], v[162:165], v[194:197], v[40:43]
	v_mfma_f32_16x16x32_bf16 v[28:31], v[144:147], v[202:205], v[28:31]
	v_mfma_f32_16x16x32_bf16 v[24:27], v[162:165], v[202:205], v[24:27]
	v_mfma_f32_16x16x32_bf16 v[12:15], v[144:147], v[212:215], v[12:15]
	v_mfma_f32_16x16x32_bf16 v[8:11], v[162:165], v[212:215], v[8:11]
	v_mfma_f32_16x16x32_bf16 v[52:55], v[166:169], v[182:185], v[52:55]
	v_mfma_f32_16x16x32_bf16 v[48:51], v[174:177], v[182:185], v[48:51]
	v_mfma_f32_16x16x32_bf16 v[36:39], v[166:169], v[190:193], v[36:39]
	v_mfma_f32_16x16x32_bf16 v[32:35], v[174:177], v[190:193], v[32:35]
	v_mfma_f32_16x16x32_bf16 v[20:23], v[166:169], v[198:201], v[20:23]
	v_mfma_f32_16x16x32_bf16 v[16:19], v[174:177], v[198:201], v[16:19]
	v_mfma_f32_16x16x32_bf16 v[4:7], v[166:169], v[208:211], v[4:7]
	v_mfma_f32_16x16x32_bf16 v[0:3], v[174:177], v[208:211], v[0:3]
	v_mfma_f32_16x16x32_bf16 v[52:55], v[170:173], v[186:189], v[52:55]
	v_mfma_f32_16x16x32_bf16 v[48:51], v[178:181], v[186:189], v[48:51]
	v_mfma_f32_16x16x32_bf16 v[36:39], v[170:173], v[194:197], v[36:39]
	v_mfma_f32_16x16x32_bf16 v[32:35], v[178:181], v[194:197], v[32:35]
	v_mfma_f32_16x16x32_bf16 v[20:23], v[170:173], v[202:205], v[20:23]
	v_mfma_f32_16x16x32_bf16 v[16:19], v[178:181], v[202:205], v[16:19]
	v_mfma_f32_16x16x32_bf16 v[4:7], v[170:173], v[212:215], v[4:7]
	v_mfma_f32_16x16x32_bf16 v[0:3], v[178:181], v[212:215], v[0:3]
	s_barrier
	s_add_i32 m0, s64, 0x2000
	s_nop 0
	global_load_lds_dwordx4 v130, s[62:63]
	s_mov_b32 m0, s46
	s_nop 0
	global_load_lds_dwordx4 v128, s[40:41]
	s_mov_b32 m0, s47
	s_nop 0
	global_load_lds_dwordx4 v130, s[40:41]
	s_add_i32 s62, 0, 0x18000
	v_add_u32_e32 v157, s62, v151
	s_add_i32 s63, 0, 0x1c000
	ds_read_b128 v[140:143], v157
	ds_read_b128 v[144:147], v157 offset:1024
	ds_read_b128 v[158:161], v157 offset:2048
	ds_read_b128 v[162:165], v157 offset:3072
	v_add_u32_e32 v157, s63, v151
	ds_read_b128 v[166:169], v157
	ds_read_b128 v[170:173], v157 offset:1024
	ds_read_b128 v[174:177], v157 offset:2048
	ds_read_b128 v[178:181], v157 offset:3072
	s_add_u32 s40, s40, 0x40000
	s_addc_u32 s41, s41, 0
	s_mov_b32 m0, s48
	ds_read_b128 v[182:185], v155 offset:32768
	ds_read_b128 v[186:189], v155 offset:33792
	ds_read_b128 v[190:193], v155 offset:34816
	ds_read_b128 v[194:197], v155 offset:35840
	ds_read_b128 v[198:201], v155 offset:36864
	ds_read_b128 v[202:205], v155 offset:37888
	ds_read_b128 v[208:211], v155 offset:38912
	ds_read_b128 v[212:215], v155 offset:39936
	global_load_lds_dwordx4 v128, s[40:41]
	s_mov_b32 m0, s49
	s_nop 0
	global_load_lds_dwordx4 v130, s[40:41]
	s_waitcnt vmcnt(8)
	s_waitcnt lgkmcnt(0)
	s_barrier
	s_waitcnt lgkmcnt(0)
	v_mfma_f32_16x16x32_bf16 v[124:127], v[140:143], v[182:185], v[124:127]
	v_mfma_f32_16x16x32_bf16 v[120:123], v[158:161], v[182:185], v[120:123]
	v_mfma_f32_16x16x32_bf16 v[108:111], v[140:143], v[190:193], v[108:111]
	v_mfma_f32_16x16x32_bf16 v[104:107], v[158:161], v[190:193], v[104:107]
	v_mfma_f32_16x16x32_bf16 v[92:95], v[140:143], v[198:201], v[92:95]
	v_mfma_f32_16x16x32_bf16 v[88:91], v[158:161], v[198:201], v[88:91]
	v_mfma_f32_16x16x32_bf16 v[76:79], v[140:143], v[208:211], v[76:79]
	v_mfma_f32_16x16x32_bf16 v[72:75], v[158:161], v[208:211], v[72:75]
	v_mfma_f32_16x16x32_bf16 v[124:127], v[144:147], v[186:189], v[124:127]
	v_mfma_f32_16x16x32_bf16 v[120:123], v[162:165], v[186:189], v[120:123]
	v_mfma_f32_16x16x32_bf16 v[108:111], v[144:147], v[194:197], v[108:111]
	v_mfma_f32_16x16x32_bf16 v[104:107], v[162:165], v[194:197], v[104:107]
	v_mfma_f32_16x16x32_bf16 v[92:95], v[144:147], v[202:205], v[92:95]
	v_mfma_f32_16x16x32_bf16 v[88:91], v[162:165], v[202:205], v[88:91]
	v_mfma_f32_16x16x32_bf16 v[76:79], v[144:147], v[212:215], v[76:79]
	v_mfma_f32_16x16x32_bf16 v[72:75], v[162:165], v[212:215], v[72:75]
	v_mfma_f32_16x16x32_bf16 v[116:119], v[166:169], v[182:185], v[116:119]
	v_mfma_f32_16x16x32_bf16 v[112:115], v[174:177], v[182:185], v[112:115]
	v_mfma_f32_16x16x32_bf16 v[100:103], v[166:169], v[190:193], v[100:103]
	v_mfma_f32_16x16x32_bf16 v[96:99], v[174:177], v[190:193], v[96:99]
	v_mfma_f32_16x16x32_bf16 v[84:87], v[166:169], v[198:201], v[84:87]
	v_mfma_f32_16x16x32_bf16 v[80:83], v[174:177], v[198:201], v[80:83]
	v_mfma_f32_16x16x32_bf16 v[68:71], v[166:169], v[208:211], v[68:71]
	v_mfma_f32_16x16x32_bf16 v[64:67], v[174:177], v[208:211], v[64:67]
	v_mfma_f32_16x16x32_bf16 v[116:119], v[170:173], v[186:189], v[116:119]
	v_mfma_f32_16x16x32_bf16 v[112:115], v[178:181], v[186:189], v[112:115]
	v_mfma_f32_16x16x32_bf16 v[100:103], v[170:173], v[194:197], v[100:103]
	v_mfma_f32_16x16x32_bf16 v[96:99], v[178:181], v[194:197], v[96:99]
	v_mfma_f32_16x16x32_bf16 v[84:87], v[170:173], v[202:205], v[84:87]
	v_mfma_f32_16x16x32_bf16 v[80:83], v[178:181], v[202:205], v[80:83]
	v_mfma_f32_16x16x32_bf16 v[68:71], v[170:173], v[212:215], v[68:71]
	v_mfma_f32_16x16x32_bf16 v[64:67], v[178:181], v[212:215], v[64:67]
	s_barrier
	s_add_i32 s40, s62, s45
	s_mov_b32 m0, s40
	ds_read_b128 v[182:185], v155 offset:49152
	ds_read_b128 v[186:189], v155 offset:50176
	ds_read_b128 v[190:193], v155 offset:51200
	ds_read_b128 v[194:197], v155 offset:52224
	ds_read_b128 v[198:201], v155 offset:53248
	ds_read_b128 v[202:205], v155 offset:54272
	ds_read_b128 v[208:211], v155 offset:55296
	ds_read_b128 v[212:215], v155 offset:56320
	global_load_lds_dwordx4 v148, s[38:39]
	s_add_i32 m0, s40, 0x2000
	s_add_u32 s38, s38, 0x40080
	s_addc_u32 s39, s39, 0
	s_add_i32 s40, s63, s45
	global_load_lds_dwordx4 v149, s[98:99]
	s_mov_b32 m0, s40
	s_nop 0
	global_load_lds_dwordx4 v128, s[38:39]
	s_add_i32 m0, s40, 0x2000
	s_nop 0
	global_load_lds_dwordx4 v130, s[38:39]
	s_mov_b32 m0, s51
	s_nop 0
	global_load_lds_dwordx4 v148, s[100:101]
	s_mov_b32 m0, s52
	s_nop 0
	global_load_lds_dwordx4 v149, s[100:101]
	s_waitcnt vmcnt(8)
	s_waitcnt lgkmcnt(0)
	s_barrier
	s_waitcnt lgkmcnt(0)
	v_mfma_f32_16x16x32_bf16 v[60:63], v[140:143], v[182:185], v[60:63]
	v_mfma_f32_16x16x32_bf16 v[56:59], v[158:161], v[182:185], v[56:59]
	v_mfma_f32_16x16x32_bf16 v[44:47], v[140:143], v[190:193], v[44:47]
	v_mfma_f32_16x16x32_bf16 v[40:43], v[158:161], v[190:193], v[40:43]
	v_mfma_f32_16x16x32_bf16 v[28:31], v[140:143], v[198:201], v[28:31]
	v_mfma_f32_16x16x32_bf16 v[24:27], v[158:161], v[198:201], v[24:27]
	v_mfma_f32_16x16x32_bf16 v[12:15], v[140:143], v[208:211], v[12:15]
	v_mfma_f32_16x16x32_bf16 v[8:11], v[158:161], v[208:211], v[8:11]
	v_mfma_f32_16x16x32_bf16 v[60:63], v[144:147], v[186:189], v[60:63]
	v_mfma_f32_16x16x32_bf16 v[56:59], v[162:165], v[186:189], v[56:59]
	v_mfma_f32_16x16x32_bf16 v[44:47], v[144:147], v[194:197], v[44:47]
	v_mfma_f32_16x16x32_bf16 v[40:43], v[162:165], v[194:197], v[40:43]
	v_mfma_f32_16x16x32_bf16 v[28:31], v[144:147], v[202:205], v[28:31]
	v_mfma_f32_16x16x32_bf16 v[24:27], v[162:165], v[202:205], v[24:27]
	v_mfma_f32_16x16x32_bf16 v[12:15], v[144:147], v[212:215], v[12:15]
	v_mfma_f32_16x16x32_bf16 v[8:11], v[162:165], v[212:215], v[8:11]
	v_mfma_f32_16x16x32_bf16 v[52:55], v[166:169], v[182:185], v[52:55]
	v_mfma_f32_16x16x32_bf16 v[48:51], v[174:177], v[182:185], v[48:51]
	v_mfma_f32_16x16x32_bf16 v[36:39], v[166:169], v[190:193], v[36:39]
	v_mfma_f32_16x16x32_bf16 v[32:35], v[174:177], v[190:193], v[32:35]
	v_mfma_f32_16x16x32_bf16 v[20:23], v[166:169], v[198:201], v[20:23]
	v_mfma_f32_16x16x32_bf16 v[16:19], v[174:177], v[198:201], v[16:19]
	v_mfma_f32_16x16x32_bf16 v[4:7], v[166:169], v[208:211], v[4:7]
	v_mfma_f32_16x16x32_bf16 v[0:3], v[174:177], v[208:211], v[0:3]
	v_mfma_f32_16x16x32_bf16 v[52:55], v[170:173], v[186:189], v[52:55]
	v_mfma_f32_16x16x32_bf16 v[48:51], v[178:181], v[186:189], v[48:51]
	v_mfma_f32_16x16x32_bf16 v[36:39], v[170:173], v[194:197], v[36:39]
	v_mfma_f32_16x16x32_bf16 v[32:35], v[178:181], v[194:197], v[32:35]
	v_mfma_f32_16x16x32_bf16 v[20:23], v[170:173], v[202:205], v[20:23]
	v_mfma_f32_16x16x32_bf16 v[16:19], v[178:181], v[202:205], v[16:19]
	v_mfma_f32_16x16x32_bf16 v[4:7], v[170:173], v[212:215], v[4:7]
	v_mfma_f32_16x16x32_bf16 v[0:3], v[178:181], v[212:215], v[0:3]
	s_barrier
	s_add_i32 s61, s61, 2
	s_add_u32 s59, s59, 0x100
	s_addc_u32 s60, s60, 0
	s_add_u32 s36, s36, 0x100
	s_addc_u32 s37, s37, 0
	s_cmp_gt_u32 s61, 13
	s_cbranch_scc0 .LBB0_895
	s_setprio 0
	s_and_b64 vcc, exec, s[24:25]
	s_cbranch_vccz .LBB0_898
	s_barrier

.LBB0_988:
	ds_read_b128 v[144:147], v151
	ds_read_b128 v[156:159], v151 offset:1024
	ds_read_b128 v[160:163], v151 offset:2048
	ds_read_b128 v[164:167], v151 offset:3072
	ds_read_b128 v[168:171], v152
	ds_read_b128 v[172:175], v152 offset:1024
	ds_read_b128 v[176:179], v152 offset:2048
	ds_read_b128 v[180:183], v152 offset:3072
	s_add_u32 s26, s6, 0xfffc0080
	s_addc_u32 s27, s7, -1
	s_cmp_eq_u32 s53, 12
	s_cselect_b32 s29, s19, s27
	s_cselect_b32 s28, s49, s26
	s_cselect_b32 s27, s17, s52
	s_cselect_b32 s26, s50, s51
	s_add_i32 m0, s25, 0xc000
	ds_read_b128 v[184:187], v153
	ds_read_b128 v[188:191], v153 offset:1024
	ds_read_b128 v[192:195], v153 offset:2048
	ds_read_b128 v[196:199], v153 offset:3072
	ds_read_b128 v[200:203], v153 offset:4096
	ds_read_b128 v[208:211], v153 offset:5120
	ds_read_b128 v[212:215], v153 offset:6144
	ds_read_b128 v[216:219], v153 offset:7168
	global_load_lds_dwordx4 v138, s[6:7]
	s_add_i32 m0, s25, 0xe000
	s_nop 0
	global_load_lds_dwordx4 v136, s[6:7]
	s_waitcnt vmcnt(8)
	s_waitcnt lgkmcnt(0)
	s_barrier
	s_waitcnt lgkmcnt(0)
	v_mfma_f32_16x16x32_bf16 v[124:127], v[144:147], v[184:187], v[124:127]
	v_mfma_f32_16x16x32_bf16 v[120:123], v[160:163], v[184:187], v[120:123]
	v_mfma_f32_16x16x32_bf16 v[108:111], v[144:147], v[192:195], v[108:111]
	v_mfma_f32_16x16x32_bf16 v[104:107], v[160:163], v[192:195], v[104:107]
	v_mfma_f32_16x16x32_bf16 v[92:95], v[144:147], v[200:203], v[92:95]
	v_mfma_f32_16x16x32_bf16 v[88:91], v[160:163], v[200:203], v[88:91]
	v_mfma_f32_16x16x32_bf16 v[76:79], v[144:147], v[212:215], v[76:79]
	v_mfma_f32_16x16x32_bf16 v[72:75], v[160:163], v[212:215], v[72:75]
	v_mfma_f32_16x16x32_bf16 v[124:127], v[156:159], v[188:191], v[124:127]
	v_mfma_f32_16x16x32_bf16 v[120:123], v[164:167], v[188:191], v[120:123]
	v_mfma_f32_16x16x32_bf16 v[108:111], v[156:159], v[196:199], v[108:111]
	v_mfma_f32_16x16x32_bf16 v[104:107], v[164:167], v[196:199], v[104:107]
	v_mfma_f32_16x16x32_bf16 v[92:95], v[156:159], v[208:211], v[92:95]
	v_mfma_f32_16x16x32_bf16 v[88:91], v[164:167], v[208:211], v[88:91]
	v_mfma_f32_16x16x32_bf16 v[76:79], v[156:159], v[216:219], v[76:79]
	v_mfma_f32_16x16x32_bf16 v[72:75], v[164:167], v[216:219], v[72:75]
	v_mfma_f32_16x16x32_bf16 v[116:119], v[168:171], v[184:187], v[116:119]
	v_mfma_f32_16x16x32_bf16 v[112:115], v[176:179], v[184:187], v[112:115]
	v_mfma_f32_16x16x32_bf16 v[100:103], v[168:171], v[192:195], v[100:103]
	v_mfma_f32_16x16x32_bf16 v[96:99], v[176:179], v[192:195], v[96:99]
	v_mfma_f32_16x16x32_bf16 v[84:87], v[168:171], v[200:203], v[84:87]
	v_mfma_f32_16x16x32_bf16 v[80:83], v[176:179], v[200:203], v[80:83]
	v_mfma_f32_16x16x32_bf16 v[68:71], v[168:171], v[212:215], v[68:71]
	v_mfma_f32_16x16x32_bf16 v[64:67], v[176:179], v[212:215], v[64:67]
	v_mfma_f32_16x16x32_bf16 v[116:119], v[172:175], v[188:191], v[116:119]
	v_mfma_f32_16x16x32_bf16 v[112:115], v[180:183], v[188:191], v[112:115]
	v_mfma_f32_16x16x32_bf16 v[100:103], v[172:175], v[196:199], v[100:103]
	v_mfma_f32_16x16x32_bf16 v[96:99], v[180:183], v[196:199], v[96:99]
	v_mfma_f32_16x16x32_bf16 v[84:87], v[172:175], v[208:211], v[84:87]
	v_mfma_f32_16x16x32_bf16 v[80:83], v[180:183], v[208:211], v[80:83]
	v_mfma_f32_16x16x32_bf16 v[68:71], v[172:175], v[216:219], v[68:71]
	v_mfma_f32_16x16x32_bf16 v[64:67], v[180:183], v[216:219], v[64:67]
	s_barrier
	s_add_i32 s54, s45, s38
	s_mov_b32 m0, s54
	ds_read_b128 v[184:187], v153 offset:16384
	ds_read_b128 v[188:191], v153 offset:17408
	ds_read_b128 v[192:195], v153 offset:18432
	ds_read_b128 v[196:199], v153 offset:19456
	ds_read_b128 v[200:203], v153 offset:20480
	ds_read_b128 v[208:211], v153 offset:21504
	ds_read_b128 v[212:215], v153 offset:22528
	ds_read_b128 v[216:219], v153 offset:23552
	global_load_lds_dwordx4 v130, s[26:27]
	s_add_i32 m0, s54, 0x2000
	s_add_u32 s54, s26, 0x40000
	s_mov_b64 s[98:99], s[26:27]
	s_addc_u32 s55, s27, 0
	s_add_i32 s56, s46, s38
	global_load_lds_dwordx4 v134, s[26:27]
	s_mov_b32 m0, s56
	s_mov_b64 s[100:101], s[28:29]
	global_load_lds_dwordx4 v130, s[54:55]
	s_waitcnt vmcnt(5)
	s_waitcnt lgkmcnt(0)
	s_barrier
	s_waitcnt lgkmcnt(0)
	v_mfma_f32_16x16x32_bf16 v[60:63], v[144:147], v[184:187], v[60:63]
	v_mfma_f32_16x16x32_bf16 v[56:59], v[160:163], v[184:187], v[56:59]
	v_mfma_f32_16x16x32_bf16 v[44:47], v[144:147], v[192:195], v[44:47]
	v_mfma_f32_16x16x32_bf16 v[40:43], v[160:163], v[192:195], v[40:43]
	v_mfma_f32_16x16x32_bf16 v[28:31], v[144:147], v[200:203], v[28:31]
	v_mfma_f32_16x16x32_bf16 v[24:27], v[160:163], v[200:203], v[24:27]
	v_mfma_f32_16x16x32_bf16 v[12:15], v[144:147], v[212:215], v[12:15]
	v_mfma_f32_16x16x32_bf16 v[8:11], v[160:163], v[212:215], v[8:11]
	v_mfma_f32_16x16x32_bf16 v[60:63], v[156:159], v[188:191], v[60:63]
	v_mfma_f32_16x16x32_bf16 v[56:59], v[164:167], v[188:191], v[56:59]
	v_mfma_f32_16x16x32_bf16 v[44:47], v[156:159], v[196:199], v[44:47]
	v_mfma_f32_16x16x32_bf16 v[40:43], v[164:167], v[196:199], v[40:43]
	v_mfma_f32_16x16x32_bf16 v[28:31], v[156:159], v[208:211], v[28:31]
	v_mfma_f32_16x16x32_bf16 v[24:27], v[164:167], v[208:211], v[24:27]
	v_mfma_f32_16x16x32_bf16 v[12:15], v[156:159], v[216:219], v[12:15]
	v_mfma_f32_16x16x32_bf16 v[8:11], v[164:167], v[216:219], v[8:11]
	v_mfma_f32_16x16x32_bf16 v[52:55], v[168:171], v[184:187], v[52:55]
	v_mfma_f32_16x16x32_bf16 v[48:51], v[176:179], v[184:187], v[48:51]
	v_mfma_f32_16x16x32_bf16 v[36:39], v[168:171], v[192:195], v[36:39]
	v_mfma_f32_16x16x32_bf16 v[32:35], v[176:179], v[192:195], v[32:35]
	v_mfma_f32_16x16x32_bf16 v[20:23], v[168:171], v[200:203], v[20:23]
	v_mfma_f32_16x16x32_bf16 v[16:19], v[176:179], v[200:203], v[16:19]
	v_mfma_f32_16x16x32_bf16 v[4:7], v[168:171], v[212:215], v[4:7]
	v_mfma_f32_16x16x32_bf16 v[0:3], v[176:179], v[212:215], v[0:3]
	v_mfma_f32_16x16x32_bf16 v[52:55], v[172:175], v[188:191], v[52:55]
	v_mfma_f32_16x16x32_bf16 v[48:51], v[180:183], v[188:191], v[48:51]
	v_mfma_f32_16x16x32_bf16 v[36:39], v[172:175], v[196:199], v[36:39]
	v_mfma_f32_16x16x32_bf16 v[32:35], v[180:183], v[196:199], v[32:35]
	v_mfma_f32_16x16x32_bf16 v[20:23], v[172:175], v[208:211], v[20:23]
	v_mfma_f32_16x16x32_bf16 v[16:19], v[180:183], v[208:211], v[16:19]
	v_mfma_f32_16x16x32_bf16 v[4:7], v[172:175], v[216:219], v[4:7]
	v_mfma_f32_16x16x32_bf16 v[0:3], v[180:183], v[216:219], v[0:3]
	s_barrier
	s_add_i32 m0, s56, 0x2000
	s_nop 0
	global_load_lds_dwordx4 v134, s[54:55]
	s_mov_b32 m0, s25
	s_nop 0
	global_load_lds_dwordx4 v128, s[28:29]
	s_mov_b32 m0, s39
	s_nop 0
	global_load_lds_dwordx4 v132, s[28:29]
	s_add_i32 s54, 0, 0x18000
	v_add_u32_e32 v155, s54, v149
	s_add_i32 s55, 0, 0x1c000
	ds_read_b128 v[144:147], v155
	ds_read_b128 v[156:159], v155 offset:1024
	ds_read_b128 v[160:163], v155 offset:2048
	ds_read_b128 v[164:167], v155 offset:3072
	v_add_u32_e32 v155, s55, v149
	ds_read_b128 v[168:171], v155
	ds_read_b128 v[172:175], v155 offset:1024
	ds_read_b128 v[176:179], v155 offset:2048
	ds_read_b128 v[180:183], v155 offset:3072
	s_add_u32 s28, s28, 0x40000
	s_addc_u32 s29, s29, 0
	s_mov_b32 m0, s40
	ds_read_b128 v[184:187], v153 offset:32768
	ds_read_b128 v[188:191], v153 offset:33792
	ds_read_b128 v[192:195], v153 offset:34816
	ds_read_b128 v[196:199], v153 offset:35840
	ds_read_b128 v[200:203], v153 offset:36864
	ds_read_b128 v[208:211], v153 offset:37888
	ds_read_b128 v[212:215], v153 offset:38912
	ds_read_b128 v[216:219], v153 offset:39936
	global_load_lds_dwordx4 v128, s[28:29]
	s_mov_b32 m0, s41
	s_nop 0
	global_load_lds_dwordx4 v132, s[28:29]
	s_waitcnt vmcnt(8)
	s_waitcnt lgkmcnt(0)
	s_barrier
	s_waitcnt lgkmcnt(0)
	v_mfma_f32_16x16x32_bf16 v[124:127], v[144:147], v[184:187], v[124:127]
	v_mfma_f32_16x16x32_bf16 v[120:123], v[160:163], v[184:187], v[120:123]
	v_mfma_f32_16x16x32_bf16 v[108:111], v[144:147], v[192:195], v[108:111]
	v_mfma_f32_16x16x32_bf16 v[104:107], v[160:163], v[192:195], v[104:107]
	v_mfma_f32_16x16x32_bf16 v[92:95], v[144:147], v[200:203], v[92:95]
	v_mfma_f32_16x16x32_bf16 v[88:91], v[160:163], v[200:203], v[88:91]
	v_mfma_f32_16x16x32_bf16 v[76:79], v[144:147], v[212:215], v[76:79]
	v_mfma_f32_16x16x32_bf16 v[72:75], v[160:163], v[212:215], v[72:75]
	v_mfma_f32_16x16x32_bf16 v[124:127], v[156:159], v[188:191], v[124:127]
	v_mfma_f32_16x16x32_bf16 v[120:123], v[164:167], v[188:191], v[120:123]
	v_mfma_f32_16x16x32_bf16 v[108:111], v[156:159], v[196:199], v[108:111]
	v_mfma_f32_16x16x32_bf16 v[104:107], v[164:167], v[196:199], v[104:107]
	v_mfma_f32_16x16x32_bf16 v[92:95], v[156:159], v[208:211], v[92:95]
	v_mfma_f32_16x16x32_bf16 v[88:91], v[164:167], v[208:211], v[88:91]
	v_mfma_f32_16x16x32_bf16 v[76:79], v[156:159], v[216:219], v[76:79]
	v_mfma_f32_16x16x32_bf16 v[72:75], v[164:167], v[216:219], v[72:75]
	v_mfma_f32_16x16x32_bf16 v[116:119], v[168:171], v[184:187], v[116:119]
	v_mfma_f32_16x16x32_bf16 v[112:115], v[176:179], v[184:187], v[112:115]
	v_mfma_f32_16x16x32_bf16 v[100:103], v[168:171], v[192:195], v[100:103]
	v_mfma_f32_16x16x32_bf16 v[96:99], v[176:179], v[192:195], v[96:99]
	v_mfma_f32_16x16x32_bf16 v[84:87], v[168:171], v[200:203], v[84:87]
	v_mfma_f32_16x16x32_bf16 v[80:83], v[176:179], v[200:203], v[80:83]
	v_mfma_f32_16x16x32_bf16 v[68:71], v[168:171], v[212:215], v[68:71]
	v_mfma_f32_16x16x32_bf16 v[64:67], v[176:179], v[212:215], v[64:67]
	v_mfma_f32_16x16x32_bf16 v[116:119], v[172:175], v[188:191], v[116:119]
	v_mfma_f32_16x16x32_bf16 v[112:115], v[180:183], v[188:191], v[112:115]
	v_mfma_f32_16x16x32_bf16 v[100:103], v[172:175], v[196:199], v[100:103]
	v_mfma_f32_16x16x32_bf16 v[96:99], v[180:183], v[196:199], v[96:99]
	v_mfma_f32_16x16x32_bf16 v[84:87], v[172:175], v[208:211], v[84:87]
	v_mfma_f32_16x16x32_bf16 v[80:83], v[180:183], v[208:211], v[80:83]
	v_mfma_f32_16x16x32_bf16 v[68:71], v[172:175], v[216:219], v[68:71]
	v_mfma_f32_16x16x32_bf16 v[64:67], v[180:183], v[216:219], v[64:67]
	s_barrier
	s_add_i32 s28, s54, s38
	s_mov_b32 m0, s28
	ds_read_b128 v[184:187], v153 offset:49152
	ds_read_b128 v[188:191], v153 offset:50176
	ds_read_b128 v[192:195], v153 offset:51200
	ds_read_b128 v[196:199], v153 offset:52224
	ds_read_b128 v[200:203], v153 offset:53248
	ds_read_b128 v[208:211], v153 offset:54272
	ds_read_b128 v[212:215], v153 offset:55296
	ds_read_b128 v[216:219], v153 offset:56320
	global_load_lds_dwordx4 v205, s[26:27]
	s_add_i32 m0, s28, 0x2000
	s_add_u32 s26, s26, 0x40080
	s_addc_u32 s27, s27, 0
	s_add_i32 s28, s55, s38
	global_load_lds_dwordx4 v221, s[98:99]
	s_mov_b32 m0, s28
	s_nop 0
	global_load_lds_dwordx4 v130, s[26:27]
	s_add_i32 m0, s28, 0x2000
	s_nop 0
	global_load_lds_dwordx4 v134, s[26:27]
	s_mov_b32 m0, s43
	s_nop 0
	global_load_lds_dwordx4 v204, s[100:101]
	s_mov_b32 m0, s44
	s_nop 0
	global_load_lds_dwordx4 v220, s[100:101]
	s_waitcnt vmcnt(8)
	s_waitcnt lgkmcnt(0)
	s_barrier
	s_waitcnt lgkmcnt(0)
	v_mfma_f32_16x16x32_bf16 v[60:63], v[144:147], v[184:187], v[60:63]
	v_mfma_f32_16x16x32_bf16 v[56:59], v[160:163], v[184:187], v[56:59]
	v_mfma_f32_16x16x32_bf16 v[44:47], v[144:147], v[192:195], v[44:47]
	v_mfma_f32_16x16x32_bf16 v[40:43], v[160:163], v[192:195], v[40:43]
	v_mfma_f32_16x16x32_bf16 v[28:31], v[144:147], v[200:203], v[28:31]
	v_mfma_f32_16x16x32_bf16 v[24:27], v[160:163], v[200:203], v[24:27]
	v_mfma_f32_16x16x32_bf16 v[12:15], v[144:147], v[212:215], v[12:15]
	v_mfma_f32_16x16x32_bf16 v[8:11], v[160:163], v[212:215], v[8:11]
	v_mfma_f32_16x16x32_bf16 v[60:63], v[156:159], v[188:191], v[60:63]
	v_mfma_f32_16x16x32_bf16 v[56:59], v[164:167], v[188:191], v[56:59]
	v_mfma_f32_16x16x32_bf16 v[44:47], v[156:159], v[196:199], v[44:47]
	v_mfma_f32_16x16x32_bf16 v[40:43], v[164:167], v[196:199], v[40:43]
	v_mfma_f32_16x16x32_bf16 v[28:31], v[156:159], v[208:211], v[28:31]
	v_mfma_f32_16x16x32_bf16 v[24:27], v[164:167], v[208:211], v[24:27]
	v_mfma_f32_16x16x32_bf16 v[12:15], v[156:159], v[216:219], v[12:15]
	v_mfma_f32_16x16x32_bf16 v[8:11], v[164:167], v[216:219], v[8:11]
	v_mfma_f32_16x16x32_bf16 v[52:55], v[168:171], v[184:187], v[52:55]
	v_mfma_f32_16x16x32_bf16 v[48:51], v[176:179], v[184:187], v[48:51]
	v_mfma_f32_16x16x32_bf16 v[36:39], v[168:171], v[192:195], v[36:39]
	v_mfma_f32_16x16x32_bf16 v[32:35], v[176:179], v[192:195], v[32:35]
	v_mfma_f32_16x16x32_bf16 v[20:23], v[168:171], v[200:203], v[20:23]
	v_mfma_f32_16x16x32_bf16 v[16:19], v[176:179], v[200:203], v[16:19]
	v_mfma_f32_16x16x32_bf16 v[4:7], v[168:171], v[212:215], v[4:7]
	v_mfma_f32_16x16x32_bf16 v[0:3], v[176:179], v[212:215], v[0:3]
	v_mfma_f32_16x16x32_bf16 v[52:55], v[172:175], v[188:191], v[52:55]
	v_mfma_f32_16x16x32_bf16 v[48:51], v[180:183], v[188:191], v[48:51]
	v_mfma_f32_16x16x32_bf16 v[36:39], v[172:175], v[196:199], v[36:39]
	v_mfma_f32_16x16x32_bf16 v[32:35], v[180:183], v[196:199], v[32:35]
	v_mfma_f32_16x16x32_bf16 v[20:23], v[172:175], v[208:211], v[20:23]
	v_mfma_f32_16x16x32_bf16 v[16:19], v[180:183], v[208:211], v[16:19]
	v_mfma_f32_16x16x32_bf16 v[4:7], v[172:175], v[216:219], v[4:7]
	v_mfma_f32_16x16x32_bf16 v[0:3], v[180:183], v[216:219], v[0:3]
	s_barrier
	s_add_i32 s53, s53, 2
	s_add_u32 s51, s51, 0x100
	s_addc_u32 s52, s52, 0
	s_add_u32 s6, s6, 0x100
	s_addc_u32 s7, s7, 0
	s_cmp_gt_u32 s53, 13
	s_cbranch_scc0 .LBB0_988
	s_setprio 0
	s_and_b64 vcc, exec, s[14:15]
	s_cbranch_vccz .LBB0_991
	s_barrier

.LBB0_1193:
	ds_read_b128 v[144:147], v151
	ds_read_b128 v[154:157], v151 offset:1024
	ds_read_b128 v[158:161], v151 offset:2048
	ds_read_b128 v[162:165], v151 offset:3072
	ds_read_b128 v[166:169], v152
	ds_read_b128 v[170:173], v152 offset:1024
	ds_read_b128 v[174:177], v152 offset:2048
	ds_read_b128 v[178:181], v152 offset:3072
	s_add_u32 s26, s24, 0xfffe0080
	s_addc_u32 s27, s25, -1
	s_cmp_eq_u32 s50, 4
	s_cselect_b32 s29, s17, s27
	s_cselect_b32 s28, s46, s26
	s_cselect_b32 s27, s15, s49
	s_cselect_b32 s26, s47, s48
	s_add_i32 m0, s23, 0xc000
	ds_read_b128 v[182:185], v153
	ds_read_b128 v[186:189], v153 offset:1024
	ds_read_b128 v[190:193], v153 offset:2048
	ds_read_b128 v[194:197], v153 offset:3072
	ds_read_b128 v[198:201], v153 offset:4096
	ds_read_b128 v[202:205], v153 offset:5120
	ds_read_b128 v[208:211], v153 offset:6144
	ds_read_b128 v[212:215], v153 offset:7168
	global_load_lds_dwordx4 v138, s[24:25]
	s_add_i32 m0, s23, 0xe000
	s_nop 0
	global_load_lds_dwordx4 v136, s[24:25]
	s_waitcnt vmcnt(8)
	s_waitcnt lgkmcnt(0)
	s_barrier
	s_waitcnt lgkmcnt(0)
	v_mfma_f32_16x16x32_bf16 v[124:127], v[144:147], v[182:185], v[124:127]
	v_mfma_f32_16x16x32_bf16 v[120:123], v[158:161], v[182:185], v[120:123]
	v_mfma_f32_16x16x32_bf16 v[108:111], v[144:147], v[190:193], v[108:111]
	v_mfma_f32_16x16x32_bf16 v[104:107], v[158:161], v[190:193], v[104:107]
	v_mfma_f32_16x16x32_bf16 v[92:95], v[144:147], v[198:201], v[92:95]
	v_mfma_f32_16x16x32_bf16 v[88:91], v[158:161], v[198:201], v[88:91]
	v_mfma_f32_16x16x32_bf16 v[76:79], v[144:147], v[208:211], v[76:79]
	v_mfma_f32_16x16x32_bf16 v[72:75], v[158:161], v[208:211], v[72:75]
	v_mfma_f32_16x16x32_bf16 v[124:127], v[154:157], v[186:189], v[124:127]
	v_mfma_f32_16x16x32_bf16 v[120:123], v[162:165], v[186:189], v[120:123]
	v_mfma_f32_16x16x32_bf16 v[108:111], v[154:157], v[194:197], v[108:111]
	v_mfma_f32_16x16x32_bf16 v[104:107], v[162:165], v[194:197], v[104:107]
	v_mfma_f32_16x16x32_bf16 v[92:95], v[154:157], v[202:205], v[92:95]
	v_mfma_f32_16x16x32_bf16 v[88:91], v[162:165], v[202:205], v[88:91]
	v_mfma_f32_16x16x32_bf16 v[76:79], v[154:157], v[212:215], v[76:79]
	v_mfma_f32_16x16x32_bf16 v[72:75], v[162:165], v[212:215], v[72:75]
	v_mfma_f32_16x16x32_bf16 v[116:119], v[166:169], v[182:185], v[116:119]
	v_mfma_f32_16x16x32_bf16 v[112:115], v[174:177], v[182:185], v[112:115]
	v_mfma_f32_16x16x32_bf16 v[100:103], v[166:169], v[190:193], v[100:103]
	v_mfma_f32_16x16x32_bf16 v[96:99], v[174:177], v[190:193], v[96:99]
	v_mfma_f32_16x16x32_bf16 v[84:87], v[166:169], v[198:201], v[84:87]
	v_mfma_f32_16x16x32_bf16 v[80:83], v[174:177], v[198:201], v[80:83]
	v_mfma_f32_16x16x32_bf16 v[68:71], v[166:169], v[208:211], v[68:71]
	v_mfma_f32_16x16x32_bf16 v[64:67], v[174:177], v[208:211], v[64:67]
	v_mfma_f32_16x16x32_bf16 v[116:119], v[170:173], v[186:189], v[116:119]
	v_mfma_f32_16x16x32_bf16 v[112:115], v[178:181], v[186:189], v[112:115]
	v_mfma_f32_16x16x32_bf16 v[100:103], v[170:173], v[194:197], v[100:103]
	v_mfma_f32_16x16x32_bf16 v[96:99], v[178:181], v[194:197], v[96:99]
	v_mfma_f32_16x16x32_bf16 v[84:87], v[170:173], v[202:205], v[84:87]
	v_mfma_f32_16x16x32_bf16 v[80:83], v[178:181], v[202:205], v[80:83]
	v_mfma_f32_16x16x32_bf16 v[68:71], v[170:173], v[212:215], v[68:71]
	v_mfma_f32_16x16x32_bf16 v[64:67], v[178:181], v[212:215], v[64:67]
	s_barrier
	s_add_i32 s51, s43, s36
	s_mov_b32 m0, s51
	ds_read_b128 v[182:185], v153 offset:16384
	ds_read_b128 v[186:189], v153 offset:17408
	ds_read_b128 v[190:193], v153 offset:18432
	ds_read_b128 v[194:197], v153 offset:19456
	ds_read_b128 v[198:201], v153 offset:20480
	ds_read_b128 v[202:205], v153 offset:21504
	ds_read_b128 v[208:211], v153 offset:22528
	ds_read_b128 v[212:215], v153 offset:23552
	global_load_lds_dwordx4 v130, s[26:27]
	s_add_i32 m0, s51, 0x2000
	s_add_u32 s52, s26, 0x20000
	s_mov_b64 s[98:99], s[26:27]
	s_addc_u32 s53, s27, 0
	s_add_i32 s51, s44, s36
	global_load_lds_dwordx4 v134, s[26:27]
	s_mov_b32 m0, s51
	s_mov_b64 s[100:101], s[28:29]
	global_load_lds_dwordx4 v130, s[52:53]
	s_waitcnt vmcnt(5)
	s_waitcnt lgkmcnt(0)
	s_barrier
	s_waitcnt lgkmcnt(0)
	v_mfma_f32_16x16x32_bf16 v[60:63], v[144:147], v[182:185], v[60:63]
	v_mfma_f32_16x16x32_bf16 v[56:59], v[158:161], v[182:185], v[56:59]
	v_mfma_f32_16x16x32_bf16 v[44:47], v[144:147], v[190:193], v[44:47]
	v_mfma_f32_16x16x32_bf16 v[40:43], v[158:161], v[190:193], v[40:43]
	v_mfma_f32_16x16x32_bf16 v[28:31], v[144:147], v[198:201], v[28:31]
	v_mfma_f32_16x16x32_bf16 v[24:27], v[158:161], v[198:201], v[24:27]
	v_mfma_f32_16x16x32_bf16 v[12:15], v[144:147], v[208:211], v[12:15]
	v_mfma_f32_16x16x32_bf16 v[8:11], v[158:161], v[208:211], v[8:11]
	v_mfma_f32_16x16x32_bf16 v[60:63], v[154:157], v[186:189], v[60:63]
	v_mfma_f32_16x16x32_bf16 v[56:59], v[162:165], v[186:189], v[56:59]
	v_mfma_f32_16x16x32_bf16 v[44:47], v[154:157], v[194:197], v[44:47]
	v_mfma_f32_16x16x32_bf16 v[40:43], v[162:165], v[194:197], v[40:43]
	v_mfma_f32_16x16x32_bf16 v[28:31], v[154:157], v[202:205], v[28:31]
	v_mfma_f32_16x16x32_bf16 v[24:27], v[162:165], v[202:205], v[24:27]
	v_mfma_f32_16x16x32_bf16 v[12:15], v[154:157], v[212:215], v[12:15]
	v_mfma_f32_16x16x32_bf16 v[8:11], v[162:165], v[212:215], v[8:11]
	v_mfma_f32_16x16x32_bf16 v[52:55], v[166:169], v[182:185], v[52:55]
	v_mfma_f32_16x16x32_bf16 v[48:51], v[174:177], v[182:185], v[48:51]
	v_mfma_f32_16x16x32_bf16 v[36:39], v[166:169], v[190:193], v[36:39]
	v_mfma_f32_16x16x32_bf16 v[32:35], v[174:177], v[190:193], v[32:35]
	v_mfma_f32_16x16x32_bf16 v[20:23], v[166:169], v[198:201], v[20:23]
	v_mfma_f32_16x16x32_bf16 v[16:19], v[174:177], v[198:201], v[16:19]
	v_mfma_f32_16x16x32_bf16 v[4:7], v[166:169], v[208:211], v[4:7]
	v_mfma_f32_16x16x32_bf16 v[0:3], v[174:177], v[208:211], v[0:3]
	v_mfma_f32_16x16x32_bf16 v[52:55], v[170:173], v[186:189], v[52:55]
	v_mfma_f32_16x16x32_bf16 v[48:51], v[178:181], v[186:189], v[48:51]
	v_mfma_f32_16x16x32_bf16 v[36:39], v[170:173], v[194:197], v[36:39]
	v_mfma_f32_16x16x32_bf16 v[32:35], v[178:181], v[194:197], v[32:35]
	v_mfma_f32_16x16x32_bf16 v[20:23], v[170:173], v[202:205], v[20:23]
	v_mfma_f32_16x16x32_bf16 v[16:19], v[178:181], v[202:205], v[16:19]
	v_mfma_f32_16x16x32_bf16 v[4:7], v[170:173], v[212:215], v[4:7]
	v_mfma_f32_16x16x32_bf16 v[0:3], v[178:181], v[212:215], v[0:3]
	s_barrier
	s_add_i32 m0, s51, 0x2000
	s_nop 0
	global_load_lds_dwordx4 v134, s[52:53]
	s_mov_b32 m0, s23
	s_nop 0
	global_load_lds_dwordx4 v128, s[28:29]
	s_mov_b32 m0, s37
	s_nop 0
	global_load_lds_dwordx4 v132, s[28:29]
	s_add_i32 s51, 0, 0x18000
	s_add_i32 s52, 0, 0x1c000
	v_add_u32_e32 v162, s51, v149
	v_add_u32_e32 v178, s52, v149
	ds_read_b128 v[144:147], v162
	ds_read_b128 v[154:157], v162 offset:1024
	ds_read_b128 v[158:161], v162 offset:2048
	ds_read_b128 v[162:165], v162 offset:3072
	ds_read_b128 v[166:169], v178
	ds_read_b128 v[170:173], v178 offset:1024
	ds_read_b128 v[174:177], v178 offset:2048
	ds_read_b128 v[178:181], v178 offset:3072
	s_add_u32 s28, s28, 0x20000
	s_addc_u32 s29, s29, 0
	s_mov_b32 m0, s38
	ds_read_b128 v[182:185], v153 offset:32768
	ds_read_b128 v[186:189], v153 offset:33792
	ds_read_b128 v[190:193], v153 offset:34816
	ds_read_b128 v[194:197], v153 offset:35840
	ds_read_b128 v[198:201], v153 offset:36864
	ds_read_b128 v[202:205], v153 offset:37888
	ds_read_b128 v[208:211], v153 offset:38912
	ds_read_b128 v[212:215], v153 offset:39936
	global_load_lds_dwordx4 v128, s[28:29]
	s_mov_b32 m0, s39
	s_nop 0
	global_load_lds_dwordx4 v132, s[28:29]
	s_waitcnt vmcnt(8)
	s_waitcnt lgkmcnt(0)
	s_barrier
	s_waitcnt lgkmcnt(0)
	v_mfma_f32_16x16x32_bf16 v[124:127], v[144:147], v[182:185], v[124:127]
	v_mfma_f32_16x16x32_bf16 v[120:123], v[158:161], v[182:185], v[120:123]
	v_mfma_f32_16x16x32_bf16 v[108:111], v[144:147], v[190:193], v[108:111]
	v_mfma_f32_16x16x32_bf16 v[104:107], v[158:161], v[190:193], v[104:107]
	v_mfma_f32_16x16x32_bf16 v[92:95], v[144:147], v[198:201], v[92:95]
	v_mfma_f32_16x16x32_bf16 v[88:91], v[158:161], v[198:201], v[88:91]
	v_mfma_f32_16x16x32_bf16 v[76:79], v[144:147], v[208:211], v[76:79]
	v_mfma_f32_16x16x32_bf16 v[72:75], v[158:161], v[208:211], v[72:75]
	v_mfma_f32_16x16x32_bf16 v[124:127], v[154:157], v[186:189], v[124:127]
	v_mfma_f32_16x16x32_bf16 v[120:123], v[162:165], v[186:189], v[120:123]
	v_mfma_f32_16x16x32_bf16 v[108:111], v[154:157], v[194:197], v[108:111]
	v_mfma_f32_16x16x32_bf16 v[104:107], v[162:165], v[194:197], v[104:107]
	v_mfma_f32_16x16x32_bf16 v[92:95], v[154:157], v[202:205], v[92:95]
	v_mfma_f32_16x16x32_bf16 v[88:91], v[162:165], v[202:205], v[88:91]
	v_mfma_f32_16x16x32_bf16 v[76:79], v[154:157], v[212:215], v[76:79]
	v_mfma_f32_16x16x32_bf16 v[72:75], v[162:165], v[212:215], v[72:75]
	v_mfma_f32_16x16x32_bf16 v[116:119], v[166:169], v[182:185], v[116:119]
	v_mfma_f32_16x16x32_bf16 v[112:115], v[174:177], v[182:185], v[112:115]
	v_mfma_f32_16x16x32_bf16 v[100:103], v[166:169], v[190:193], v[100:103]
	v_mfma_f32_16x16x32_bf16 v[96:99], v[174:177], v[190:193], v[96:99]
	v_mfma_f32_16x16x32_bf16 v[84:87], v[166:169], v[198:201], v[84:87]
	v_mfma_f32_16x16x32_bf16 v[80:83], v[174:177], v[198:201], v[80:83]
	v_mfma_f32_16x16x32_bf16 v[68:71], v[166:169], v[208:211], v[68:71]
	v_mfma_f32_16x16x32_bf16 v[64:67], v[174:177], v[208:211], v[64:67]
	v_mfma_f32_16x16x32_bf16 v[116:119], v[170:173], v[186:189], v[116:119]
	v_mfma_f32_16x16x32_bf16 v[112:115], v[178:181], v[186:189], v[112:115]
	v_mfma_f32_16x16x32_bf16 v[100:103], v[170:173], v[194:197], v[100:103]
	v_mfma_f32_16x16x32_bf16 v[96:99], v[178:181], v[194:197], v[96:99]
	v_mfma_f32_16x16x32_bf16 v[84:87], v[170:173], v[202:205], v[84:87]
	v_mfma_f32_16x16x32_bf16 v[80:83], v[178:181], v[202:205], v[80:83]
	v_mfma_f32_16x16x32_bf16 v[68:71], v[170:173], v[212:215], v[68:71]
	v_mfma_f32_16x16x32_bf16 v[64:67], v[178:181], v[212:215], v[64:67]
	s_barrier
	s_add_i32 s28, s51, s36
	s_mov_b32 m0, s28
	ds_read_b128 v[182:185], v153 offset:49152
	ds_read_b128 v[186:189], v153 offset:50176
	ds_read_b128 v[190:193], v153 offset:51200
	ds_read_b128 v[194:197], v153 offset:52224
	ds_read_b128 v[198:201], v153 offset:53248
	ds_read_b128 v[202:205], v153 offset:54272
	ds_read_b128 v[208:211], v153 offset:55296
	ds_read_b128 v[212:215], v153 offset:56320
	global_load_lds_dwordx4 v217, s[26:27]
	s_add_i32 m0, s28, 0x2000
	s_add_u32 s26, s26, 0x20080
	s_addc_u32 s27, s27, 0
	s_add_i32 s28, s52, s36
	global_load_lds_dwordx4 v219, s[98:99]
	s_mov_b32 m0, s28
	s_nop 0
	global_load_lds_dwordx4 v130, s[26:27]
	s_add_i32 m0, s28, 0x2000
	s_nop 0
	global_load_lds_dwordx4 v134, s[26:27]
	s_mov_b32 m0, s41
	s_nop 0
	global_load_lds_dwordx4 v216, s[100:101]
	s_mov_b32 m0, s42
	s_nop 0
	global_load_lds_dwordx4 v218, s[100:101]
	s_waitcnt vmcnt(8)
	s_waitcnt lgkmcnt(0)
	s_barrier
	s_waitcnt lgkmcnt(0)
	v_mfma_f32_16x16x32_bf16 v[60:63], v[144:147], v[182:185], v[60:63]
	v_mfma_f32_16x16x32_bf16 v[56:59], v[158:161], v[182:185], v[56:59]
	v_mfma_f32_16x16x32_bf16 v[44:47], v[144:147], v[190:193], v[44:47]
	v_mfma_f32_16x16x32_bf16 v[40:43], v[158:161], v[190:193], v[40:43]
	v_mfma_f32_16x16x32_bf16 v[28:31], v[144:147], v[198:201], v[28:31]
	v_mfma_f32_16x16x32_bf16 v[24:27], v[158:161], v[198:201], v[24:27]
	v_mfma_f32_16x16x32_bf16 v[12:15], v[144:147], v[208:211], v[12:15]
	v_mfma_f32_16x16x32_bf16 v[8:11], v[158:161], v[208:211], v[8:11]
	v_mfma_f32_16x16x32_bf16 v[60:63], v[154:157], v[186:189], v[60:63]
	v_mfma_f32_16x16x32_bf16 v[56:59], v[162:165], v[186:189], v[56:59]
	v_mfma_f32_16x16x32_bf16 v[44:47], v[154:157], v[194:197], v[44:47]
	v_mfma_f32_16x16x32_bf16 v[40:43], v[162:165], v[194:197], v[40:43]
	v_mfma_f32_16x16x32_bf16 v[28:31], v[154:157], v[202:205], v[28:31]
	v_mfma_f32_16x16x32_bf16 v[24:27], v[162:165], v[202:205], v[24:27]
	v_mfma_f32_16x16x32_bf16 v[12:15], v[154:157], v[212:215], v[12:15]
	v_mfma_f32_16x16x32_bf16 v[8:11], v[162:165], v[212:215], v[8:11]
	v_mfma_f32_16x16x32_bf16 v[52:55], v[166:169], v[182:185], v[52:55]
	v_mfma_f32_16x16x32_bf16 v[48:51], v[174:177], v[182:185], v[48:51]
	v_mfma_f32_16x16x32_bf16 v[36:39], v[166:169], v[190:193], v[36:39]
	v_mfma_f32_16x16x32_bf16 v[32:35], v[174:177], v[190:193], v[32:35]
	v_mfma_f32_16x16x32_bf16 v[20:23], v[166:169], v[198:201], v[20:23]
	v_mfma_f32_16x16x32_bf16 v[16:19], v[174:177], v[198:201], v[16:19]
	v_mfma_f32_16x16x32_bf16 v[4:7], v[166:169], v[208:211], v[4:7]
	v_mfma_f32_16x16x32_bf16 v[0:3], v[174:177], v[208:211], v[0:3]
	v_mfma_f32_16x16x32_bf16 v[52:55], v[170:173], v[186:189], v[52:55]
	v_mfma_f32_16x16x32_bf16 v[48:51], v[178:181], v[186:189], v[48:51]
	v_mfma_f32_16x16x32_bf16 v[36:39], v[170:173], v[194:197], v[36:39]
	v_mfma_f32_16x16x32_bf16 v[32:35], v[178:181], v[194:197], v[32:35]
	v_mfma_f32_16x16x32_bf16 v[20:23], v[170:173], v[202:205], v[20:23]
	v_mfma_f32_16x16x32_bf16 v[16:19], v[178:181], v[202:205], v[16:19]
	v_mfma_f32_16x16x32_bf16 v[4:7], v[170:173], v[212:215], v[4:7]
	v_mfma_f32_16x16x32_bf16 v[0:3], v[178:181], v[212:215], v[0:3]
	s_barrier
	s_add_i32 s50, s50, 2
	s_add_u32 s48, s48, 0x100
	s_addc_u32 s49, s49, 0
	s_add_u32 s24, s24, 0x100
	s_addc_u32 s25, s25, 0
	s_cmp_gt_u32 s50, 5
	s_cbranch_scc0 .LBB0_1193
	s_setprio 0
	s_and_b64 vcc, exec, s[12:13]
	s_cbranch_vccz .LBB0_1196
	s_barrier

.LBB0_1365:
	ds_read_b128 v[144:147], v151
	ds_read_b128 v[156:159], v151 offset:1024
	ds_read_b128 v[160:163], v151 offset:2048
	ds_read_b128 v[164:167], v151 offset:3072
	ds_read_b128 v[168:171], v152
	ds_read_b128 v[172:175], v152 offset:1024
	ds_read_b128 v[176:179], v152 offset:2048
	ds_read_b128 v[180:183], v152 offset:3072
	s_add_u32 s26, s24, 0xfffc0080
	s_addc_u32 s27, s25, -1
	s_cmp_eq_u32 s53, 12
	s_cselect_b32 s29, s19, s27
	s_cselect_b32 s28, s49, s26
	s_cselect_b32 s27, s17, s52
	s_cselect_b32 s26, s50, s51
	s_add_i32 m0, s39, 0xc000
	ds_read_b128 v[184:187], v153
	ds_read_b128 v[188:191], v153 offset:1024
	ds_read_b128 v[192:195], v153 offset:2048
	ds_read_b128 v[196:199], v153 offset:3072
	ds_read_b128 v[200:203], v153 offset:4096
	ds_read_b128 v[208:211], v153 offset:5120
	ds_read_b128 v[212:215], v153 offset:6144
	ds_read_b128 v[216:219], v153 offset:7168
	global_load_lds_dwordx4 v138, s[24:25]
	s_add_i32 m0, s39, 0xe000
	s_nop 0
	global_load_lds_dwordx4 v136, s[24:25]
	s_waitcnt vmcnt(8)
	s_waitcnt lgkmcnt(0)
	s_barrier
	s_waitcnt lgkmcnt(0)
	v_mfma_f32_16x16x32_bf16 v[124:127], v[144:147], v[184:187], v[124:127]
	v_mfma_f32_16x16x32_bf16 v[120:123], v[160:163], v[184:187], v[120:123]
	v_mfma_f32_16x16x32_bf16 v[108:111], v[144:147], v[192:195], v[108:111]
	v_mfma_f32_16x16x32_bf16 v[104:107], v[160:163], v[192:195], v[104:107]
	v_mfma_f32_16x16x32_bf16 v[92:95], v[144:147], v[200:203], v[92:95]
	v_mfma_f32_16x16x32_bf16 v[88:91], v[160:163], v[200:203], v[88:91]
	v_mfma_f32_16x16x32_bf16 v[76:79], v[144:147], v[212:215], v[76:79]
	v_mfma_f32_16x16x32_bf16 v[72:75], v[160:163], v[212:215], v[72:75]
	v_mfma_f32_16x16x32_bf16 v[124:127], v[156:159], v[188:191], v[124:127]
	v_mfma_f32_16x16x32_bf16 v[120:123], v[164:167], v[188:191], v[120:123]
	v_mfma_f32_16x16x32_bf16 v[108:111], v[156:159], v[196:199], v[108:111]
	v_mfma_f32_16x16x32_bf16 v[104:107], v[164:167], v[196:199], v[104:107]
	v_mfma_f32_16x16x32_bf16 v[92:95], v[156:159], v[208:211], v[92:95]
	v_mfma_f32_16x16x32_bf16 v[88:91], v[164:167], v[208:211], v[88:91]
	v_mfma_f32_16x16x32_bf16 v[76:79], v[156:159], v[216:219], v[76:79]
	v_mfma_f32_16x16x32_bf16 v[72:75], v[164:167], v[216:219], v[72:75]
	v_mfma_f32_16x16x32_bf16 v[116:119], v[168:171], v[184:187], v[116:119]
	v_mfma_f32_16x16x32_bf16 v[112:115], v[176:179], v[184:187], v[112:115]
	v_mfma_f32_16x16x32_bf16 v[100:103], v[168:171], v[192:195], v[100:103]
	v_mfma_f32_16x16x32_bf16 v[96:99], v[176:179], v[192:195], v[96:99]
	v_mfma_f32_16x16x32_bf16 v[84:87], v[168:171], v[200:203], v[84:87]
	v_mfma_f32_16x16x32_bf16 v[80:83], v[176:179], v[200:203], v[80:83]
	v_mfma_f32_16x16x32_bf16 v[68:71], v[168:171], v[212:215], v[68:71]
	v_mfma_f32_16x16x32_bf16 v[64:67], v[176:179], v[212:215], v[64:67]
	v_mfma_f32_16x16x32_bf16 v[116:119], v[172:175], v[188:191], v[116:119]
	v_mfma_f32_16x16x32_bf16 v[112:115], v[180:183], v[188:191], v[112:115]
	v_mfma_f32_16x16x32_bf16 v[100:103], v[172:175], v[196:199], v[100:103]
	v_mfma_f32_16x16x32_bf16 v[96:99], v[180:183], v[196:199], v[96:99]
	v_mfma_f32_16x16x32_bf16 v[84:87], v[172:175], v[208:211], v[84:87]
	v_mfma_f32_16x16x32_bf16 v[80:83], v[180:183], v[208:211], v[80:83]
	v_mfma_f32_16x16x32_bf16 v[68:71], v[172:175], v[216:219], v[68:71]
	v_mfma_f32_16x16x32_bf16 v[64:67], v[180:183], v[216:219], v[64:67]
	s_barrier
	s_add_i32 s54, s46, s38
	s_mov_b32 m0, s54
	ds_read_b128 v[184:187], v153 offset:16384
	ds_read_b128 v[188:191], v153 offset:17408
	ds_read_b128 v[192:195], v153 offset:18432
	ds_read_b128 v[196:199], v153 offset:19456
	ds_read_b128 v[200:203], v153 offset:20480
	ds_read_b128 v[208:211], v153 offset:21504
	ds_read_b128 v[212:215], v153 offset:22528
	ds_read_b128 v[216:219], v153 offset:23552
	global_load_lds_dwordx4 v130, s[26:27]
	s_add_i32 m0, s54, 0x2000
	s_add_u32 s54, s26, 0x40000
	s_mov_b64 s[98:99], s[26:27]
	s_addc_u32 s55, s27, 0
	s_add_i32 s56, s47, s38
	global_load_lds_dwordx4 v134, s[26:27]
	s_mov_b32 m0, s56
	s_mov_b64 s[100:101], s[28:29]
	global_load_lds_dwordx4 v130, s[54:55]
	s_waitcnt vmcnt(5)
	s_waitcnt lgkmcnt(0)
	s_barrier
	s_waitcnt lgkmcnt(0)
	v_mfma_f32_16x16x32_bf16 v[60:63], v[144:147], v[184:187], v[60:63]
	v_mfma_f32_16x16x32_bf16 v[56:59], v[160:163], v[184:187], v[56:59]
	v_mfma_f32_16x16x32_bf16 v[44:47], v[144:147], v[192:195], v[44:47]
	v_mfma_f32_16x16x32_bf16 v[40:43], v[160:163], v[192:195], v[40:43]
	v_mfma_f32_16x16x32_bf16 v[28:31], v[144:147], v[200:203], v[28:31]
	v_mfma_f32_16x16x32_bf16 v[24:27], v[160:163], v[200:203], v[24:27]
	v_mfma_f32_16x16x32_bf16 v[12:15], v[144:147], v[212:215], v[12:15]
	v_mfma_f32_16x16x32_bf16 v[8:11], v[160:163], v[212:215], v[8:11]
	v_mfma_f32_16x16x32_bf16 v[60:63], v[156:159], v[188:191], v[60:63]
	v_mfma_f32_16x16x32_bf16 v[56:59], v[164:167], v[188:191], v[56:59]
	v_mfma_f32_16x16x32_bf16 v[44:47], v[156:159], v[196:199], v[44:47]
	v_mfma_f32_16x16x32_bf16 v[40:43], v[164:167], v[196:199], v[40:43]
	v_mfma_f32_16x16x32_bf16 v[28:31], v[156:159], v[208:211], v[28:31]
	v_mfma_f32_16x16x32_bf16 v[24:27], v[164:167], v[208:211], v[24:27]
	v_mfma_f32_16x16x32_bf16 v[12:15], v[156:159], v[216:219], v[12:15]
	v_mfma_f32_16x16x32_bf16 v[8:11], v[164:167], v[216:219], v[8:11]
	v_mfma_f32_16x16x32_bf16 v[52:55], v[168:171], v[184:187], v[52:55]
	v_mfma_f32_16x16x32_bf16 v[48:51], v[176:179], v[184:187], v[48:51]
	v_mfma_f32_16x16x32_bf16 v[36:39], v[168:171], v[192:195], v[36:39]
	v_mfma_f32_16x16x32_bf16 v[32:35], v[176:179], v[192:195], v[32:35]
	v_mfma_f32_16x16x32_bf16 v[20:23], v[168:171], v[200:203], v[20:23]
	v_mfma_f32_16x16x32_bf16 v[16:19], v[176:179], v[200:203], v[16:19]
	v_mfma_f32_16x16x32_bf16 v[4:7], v[168:171], v[212:215], v[4:7]
	v_mfma_f32_16x16x32_bf16 v[0:3], v[176:179], v[212:215], v[0:3]
	v_mfma_f32_16x16x32_bf16 v[52:55], v[172:175], v[188:191], v[52:55]
	v_mfma_f32_16x16x32_bf16 v[48:51], v[180:183], v[188:191], v[48:51]
	v_mfma_f32_16x16x32_bf16 v[36:39], v[172:175], v[196:199], v[36:39]
	v_mfma_f32_16x16x32_bf16 v[32:35], v[180:183], v[196:199], v[32:35]
	v_mfma_f32_16x16x32_bf16 v[20:23], v[172:175], v[208:211], v[20:23]
	v_mfma_f32_16x16x32_bf16 v[16:19], v[180:183], v[208:211], v[16:19]
	v_mfma_f32_16x16x32_bf16 v[4:7], v[172:175], v[216:219], v[4:7]
	v_mfma_f32_16x16x32_bf16 v[0:3], v[180:183], v[216:219], v[0:3]
	s_barrier
	s_add_i32 m0, s56, 0x2000
	s_nop 0
	global_load_lds_dwordx4 v134, s[54:55]
	s_mov_b32 m0, s39
	s_nop 0
	global_load_lds_dwordx4 v128, s[28:29]
	s_mov_b32 m0, s40
	s_nop 0
	global_load_lds_dwordx4 v132, s[28:29]
	s_add_i32 s54, 0, 0x18000
	v_add_u32_e32 v155, s54, v149
	s_add_i32 s55, 0, 0x1c000
	ds_read_b128 v[144:147], v155
	ds_read_b128 v[156:159], v155 offset:1024
	ds_read_b128 v[160:163], v155 offset:2048
	ds_read_b128 v[164:167], v155 offset:3072
	v_add_u32_e32 v155, s55, v149
	ds_read_b128 v[168:171], v155
	ds_read_b128 v[172:175], v155 offset:1024
	ds_read_b128 v[176:179], v155 offset:2048
	ds_read_b128 v[180:183], v155 offset:3072
	s_add_u32 s28, s28, 0x40000
	s_addc_u32 s29, s29, 0
	s_mov_b32 m0, s41
	ds_read_b128 v[184:187], v153 offset:32768
	ds_read_b128 v[188:191], v153 offset:33792
	ds_read_b128 v[192:195], v153 offset:34816
	ds_read_b128 v[196:199], v153 offset:35840
	ds_read_b128 v[200:203], v153 offset:36864
	ds_read_b128 v[208:211], v153 offset:37888
	ds_read_b128 v[212:215], v153 offset:38912
	ds_read_b128 v[216:219], v153 offset:39936
	global_load_lds_dwordx4 v128, s[28:29]
	s_mov_b32 m0, s42
	s_nop 0
	global_load_lds_dwordx4 v132, s[28:29]
	s_waitcnt vmcnt(8)
	s_waitcnt lgkmcnt(0)
	s_barrier
	s_waitcnt lgkmcnt(0)
	v_mfma_f32_16x16x32_bf16 v[124:127], v[144:147], v[184:187], v[124:127]
	v_mfma_f32_16x16x32_bf16 v[120:123], v[160:163], v[184:187], v[120:123]
	v_mfma_f32_16x16x32_bf16 v[108:111], v[144:147], v[192:195], v[108:111]
	v_mfma_f32_16x16x32_bf16 v[104:107], v[160:163], v[192:195], v[104:107]
	v_mfma_f32_16x16x32_bf16 v[92:95], v[144:147], v[200:203], v[92:95]
	v_mfma_f32_16x16x32_bf16 v[88:91], v[160:163], v[200:203], v[88:91]
	v_mfma_f32_16x16x32_bf16 v[76:79], v[144:147], v[212:215], v[76:79]
	v_mfma_f32_16x16x32_bf16 v[72:75], v[160:163], v[212:215], v[72:75]
	v_mfma_f32_16x16x32_bf16 v[124:127], v[156:159], v[188:191], v[124:127]
	v_mfma_f32_16x16x32_bf16 v[120:123], v[164:167], v[188:191], v[120:123]
	v_mfma_f32_16x16x32_bf16 v[108:111], v[156:159], v[196:199], v[108:111]
	v_mfma_f32_16x16x32_bf16 v[104:107], v[164:167], v[196:199], v[104:107]
	v_mfma_f32_16x16x32_bf16 v[92:95], v[156:159], v[208:211], v[92:95]
	v_mfma_f32_16x16x32_bf16 v[88:91], v[164:167], v[208:211], v[88:91]
	v_mfma_f32_16x16x32_bf16 v[76:79], v[156:159], v[216:219], v[76:79]
	v_mfma_f32_16x16x32_bf16 v[72:75], v[164:167], v[216:219], v[72:75]
	v_mfma_f32_16x16x32_bf16 v[116:119], v[168:171], v[184:187], v[116:119]
	v_mfma_f32_16x16x32_bf16 v[112:115], v[176:179], v[184:187], v[112:115]
	v_mfma_f32_16x16x32_bf16 v[100:103], v[168:171], v[192:195], v[100:103]
	v_mfma_f32_16x16x32_bf16 v[96:99], v[176:179], v[192:195], v[96:99]
	v_mfma_f32_16x16x32_bf16 v[84:87], v[168:171], v[200:203], v[84:87]
	v_mfma_f32_16x16x32_bf16 v[80:83], v[176:179], v[200:203], v[80:83]
	v_mfma_f32_16x16x32_bf16 v[68:71], v[168:171], v[212:215], v[68:71]
	v_mfma_f32_16x16x32_bf16 v[64:67], v[176:179], v[212:215], v[64:67]
	v_mfma_f32_16x16x32_bf16 v[116:119], v[172:175], v[188:191], v[116:119]
	v_mfma_f32_16x16x32_bf16 v[112:115], v[180:183], v[188:191], v[112:115]
	v_mfma_f32_16x16x32_bf16 v[100:103], v[172:175], v[196:199], v[100:103]
	v_mfma_f32_16x16x32_bf16 v[96:99], v[180:183], v[196:199], v[96:99]
	v_mfma_f32_16x16x32_bf16 v[84:87], v[172:175], v[208:211], v[84:87]
	v_mfma_f32_16x16x32_bf16 v[80:83], v[180:183], v[208:211], v[80:83]
	v_mfma_f32_16x16x32_bf16 v[68:71], v[172:175], v[216:219], v[68:71]
	v_mfma_f32_16x16x32_bf16 v[64:67], v[180:183], v[216:219], v[64:67]
	s_barrier
	s_add_i32 s28, s54, s38
	s_mov_b32 m0, s28
	ds_read_b128 v[184:187], v153 offset:49152
	ds_read_b128 v[188:191], v153 offset:50176
	ds_read_b128 v[192:195], v153 offset:51200
	ds_read_b128 v[196:199], v153 offset:52224
	ds_read_b128 v[200:203], v153 offset:53248
	ds_read_b128 v[208:211], v153 offset:54272
	ds_read_b128 v[212:215], v153 offset:55296
	ds_read_b128 v[216:219], v153 offset:56320
	global_load_lds_dwordx4 v205, s[26:27]
	s_add_i32 m0, s28, 0x2000
	s_add_u32 s26, s26, 0x40080
	s_addc_u32 s27, s27, 0
	s_add_i32 s28, s55, s38
	global_load_lds_dwordx4 v221, s[98:99]
	s_mov_b32 m0, s28
	s_nop 0
	global_load_lds_dwordx4 v130, s[26:27]
	s_add_i32 m0, s28, 0x2000
	s_nop 0
	global_load_lds_dwordx4 v134, s[26:27]
	s_mov_b32 m0, s44
	s_nop 0
	global_load_lds_dwordx4 v204, s[100:101]
	s_mov_b32 m0, s45
	s_nop 0
	global_load_lds_dwordx4 v220, s[100:101]
	s_waitcnt vmcnt(8)
	s_waitcnt lgkmcnt(0)
	s_barrier
	s_waitcnt lgkmcnt(0)
	v_mfma_f32_16x16x32_bf16 v[60:63], v[144:147], v[184:187], v[60:63]
	v_mfma_f32_16x16x32_bf16 v[56:59], v[160:163], v[184:187], v[56:59]
	v_mfma_f32_16x16x32_bf16 v[44:47], v[144:147], v[192:195], v[44:47]
	v_mfma_f32_16x16x32_bf16 v[40:43], v[160:163], v[192:195], v[40:43]
	v_mfma_f32_16x16x32_bf16 v[28:31], v[144:147], v[200:203], v[28:31]
	v_mfma_f32_16x16x32_bf16 v[24:27], v[160:163], v[200:203], v[24:27]
	v_mfma_f32_16x16x32_bf16 v[12:15], v[144:147], v[212:215], v[12:15]
	v_mfma_f32_16x16x32_bf16 v[8:11], v[160:163], v[212:215], v[8:11]
	v_mfma_f32_16x16x32_bf16 v[60:63], v[156:159], v[188:191], v[60:63]
	v_mfma_f32_16x16x32_bf16 v[56:59], v[164:167], v[188:191], v[56:59]
	v_mfma_f32_16x16x32_bf16 v[44:47], v[156:159], v[196:199], v[44:47]
	v_mfma_f32_16x16x32_bf16 v[40:43], v[164:167], v[196:199], v[40:43]
	v_mfma_f32_16x16x32_bf16 v[28:31], v[156:159], v[208:211], v[28:31]
	v_mfma_f32_16x16x32_bf16 v[24:27], v[164:167], v[208:211], v[24:27]
	v_mfma_f32_16x16x32_bf16 v[12:15], v[156:159], v[216:219], v[12:15]
	v_mfma_f32_16x16x32_bf16 v[8:11], v[164:167], v[216:219], v[8:11]
	v_mfma_f32_16x16x32_bf16 v[52:55], v[168:171], v[184:187], v[52:55]
	v_mfma_f32_16x16x32_bf16 v[48:51], v[176:179], v[184:187], v[48:51]
	v_mfma_f32_16x16x32_bf16 v[36:39], v[168:171], v[192:195], v[36:39]
	v_mfma_f32_16x16x32_bf16 v[32:35], v[176:179], v[192:195], v[32:35]
	v_mfma_f32_16x16x32_bf16 v[20:23], v[168:171], v[200:203], v[20:23]
	v_mfma_f32_16x16x32_bf16 v[16:19], v[176:179], v[200:203], v[16:19]
	v_mfma_f32_16x16x32_bf16 v[4:7], v[168:171], v[212:215], v[4:7]
	v_mfma_f32_16x16x32_bf16 v[0:3], v[176:179], v[212:215], v[0:3]
	v_mfma_f32_16x16x32_bf16 v[52:55], v[172:175], v[188:191], v[52:55]
	v_mfma_f32_16x16x32_bf16 v[48:51], v[180:183], v[188:191], v[48:51]
	v_mfma_f32_16x16x32_bf16 v[36:39], v[172:175], v[196:199], v[36:39]
	v_mfma_f32_16x16x32_bf16 v[32:35], v[180:183], v[196:199], v[32:35]
	v_mfma_f32_16x16x32_bf16 v[20:23], v[172:175], v[208:211], v[20:23]
	v_mfma_f32_16x16x32_bf16 v[16:19], v[180:183], v[208:211], v[16:19]
	v_mfma_f32_16x16x32_bf16 v[4:7], v[172:175], v[216:219], v[4:7]
	v_mfma_f32_16x16x32_bf16 v[0:3], v[180:183], v[216:219], v[0:3]
	s_barrier
	s_add_i32 s53, s53, 2
	s_add_u32 s51, s51, 0x100
	s_addc_u32 s52, s52, 0
	s_add_u32 s24, s24, 0x100
	s_addc_u32 s25, s25, 0
	s_cmp_gt_u32 s53, 13
	s_cbranch_scc0 .LBB0_1365
	s_setprio 0
	s_and_b64 vcc, exec, s[14:15]
	s_cbranch_vccz .LBB0_1368
	s_barrier

.LBB0_1561:
	ds_read_b128 v[140:143], v151
	ds_read_b128 v[144:147], v151 offset:1024
	ds_read_b128 v[156:159], v151 offset:2048
	ds_read_b128 v[160:163], v151 offset:3072
	ds_read_b128 v[164:167], v152
	ds_read_b128 v[168:171], v152 offset:1024
	ds_read_b128 v[172:175], v152 offset:2048
	ds_read_b128 v[176:179], v152 offset:3072
	s_add_u32 s38, s36, 0xfffc0080
	s_addc_u32 s39, s37, -1
	s_cmp_eq_u32 s61, 12
	s_cselect_b32 s41, s3, s39
	s_cselect_b32 s40, s29, s38
	s_cselect_b32 s39, s27, s60
	s_cselect_b32 s38, s58, s59
	s_add_i32 m0, s46, 0xc000
	ds_read_b128 v[180:183], v153
	ds_read_b128 v[184:187], v153 offset:1024
	ds_read_b128 v[188:191], v153 offset:2048
	ds_read_b128 v[192:195], v153 offset:3072
	ds_read_b128 v[196:199], v153 offset:4096
	ds_read_b128 v[200:203], v153 offset:5120
	ds_read_b128 v[208:211], v153 offset:6144
	ds_read_b128 v[212:215], v153 offset:7168
	global_load_lds_dwordx4 v134, s[36:37]
	s_add_i32 m0, s46, 0xe000
	s_nop 0
	global_load_lds_dwordx4 v132, s[36:37]
	s_waitcnt vmcnt(8)
	s_waitcnt lgkmcnt(0)
	s_barrier
	s_waitcnt lgkmcnt(0)
	v_mfma_f32_16x16x32_bf16 v[124:127], v[140:143], v[180:183], v[124:127]
	v_mfma_f32_16x16x32_bf16 v[120:123], v[156:159], v[180:183], v[120:123]
	v_mfma_f32_16x16x32_bf16 v[108:111], v[140:143], v[188:191], v[108:111]
	v_mfma_f32_16x16x32_bf16 v[104:107], v[156:159], v[188:191], v[104:107]
	v_mfma_f32_16x16x32_bf16 v[92:95], v[140:143], v[196:199], v[92:95]
	v_mfma_f32_16x16x32_bf16 v[88:91], v[156:159], v[196:199], v[88:91]
	v_mfma_f32_16x16x32_bf16 v[76:79], v[140:143], v[208:211], v[76:79]
	v_mfma_f32_16x16x32_bf16 v[72:75], v[156:159], v[208:211], v[72:75]
	v_mfma_f32_16x16x32_bf16 v[124:127], v[144:147], v[184:187], v[124:127]
	v_mfma_f32_16x16x32_bf16 v[120:123], v[160:163], v[184:187], v[120:123]
	v_mfma_f32_16x16x32_bf16 v[108:111], v[144:147], v[192:195], v[108:111]
	v_mfma_f32_16x16x32_bf16 v[104:107], v[160:163], v[192:195], v[104:107]
	v_mfma_f32_16x16x32_bf16 v[92:95], v[144:147], v[200:203], v[92:95]
	v_mfma_f32_16x16x32_bf16 v[88:91], v[160:163], v[200:203], v[88:91]
	v_mfma_f32_16x16x32_bf16 v[76:79], v[144:147], v[212:215], v[76:79]
	v_mfma_f32_16x16x32_bf16 v[72:75], v[160:163], v[212:215], v[72:75]
	v_mfma_f32_16x16x32_bf16 v[116:119], v[164:167], v[180:183], v[116:119]
	v_mfma_f32_16x16x32_bf16 v[112:115], v[172:175], v[180:183], v[112:115]
	v_mfma_f32_16x16x32_bf16 v[100:103], v[164:167], v[188:191], v[100:103]
	v_mfma_f32_16x16x32_bf16 v[96:99], v[172:175], v[188:191], v[96:99]
	v_mfma_f32_16x16x32_bf16 v[84:87], v[164:167], v[196:199], v[84:87]
	v_mfma_f32_16x16x32_bf16 v[80:83], v[172:175], v[196:199], v[80:83]
	v_mfma_f32_16x16x32_bf16 v[68:71], v[164:167], v[208:211], v[68:71]
	v_mfma_f32_16x16x32_bf16 v[64:67], v[172:175], v[208:211], v[64:67]
	v_mfma_f32_16x16x32_bf16 v[116:119], v[168:171], v[184:187], v[116:119]
	v_mfma_f32_16x16x32_bf16 v[112:115], v[176:179], v[184:187], v[112:115]
	v_mfma_f32_16x16x32_bf16 v[100:103], v[168:171], v[192:195], v[100:103]
	v_mfma_f32_16x16x32_bf16 v[96:99], v[176:179], v[192:195], v[96:99]
	v_mfma_f32_16x16x32_bf16 v[84:87], v[168:171], v[200:203], v[84:87]
	v_mfma_f32_16x16x32_bf16 v[80:83], v[176:179], v[200:203], v[80:83]
	v_mfma_f32_16x16x32_bf16 v[68:71], v[168:171], v[212:215], v[68:71]
	v_mfma_f32_16x16x32_bf16 v[64:67], v[176:179], v[212:215], v[64:67]
	s_barrier
	s_add_i32 s62, s54, s45
	s_mov_b32 m0, s62
	ds_read_b128 v[180:183], v153 offset:16384
	ds_read_b128 v[184:187], v153 offset:17408
	ds_read_b128 v[188:191], v153 offset:18432
	ds_read_b128 v[192:195], v153 offset:19456
	ds_read_b128 v[196:199], v153 offset:20480
	ds_read_b128 v[200:203], v153 offset:21504
	ds_read_b128 v[208:211], v153 offset:22528
	ds_read_b128 v[212:215], v153 offset:23552
	global_load_lds_dwordx4 v128, s[38:39]
	s_add_i32 m0, s62, 0x2000
	s_add_u32 s62, s38, 0x40000
	s_mov_b64 s[98:99], s[38:39]
	s_addc_u32 s63, s39, 0
	s_add_i32 s64, s55, s45
	global_load_lds_dwordx4 v130, s[38:39]
	s_mov_b32 m0, s64
	s_mov_b64 s[100:101], s[40:41]
	global_load_lds_dwordx4 v128, s[62:63]
	s_waitcnt vmcnt(5)
	s_waitcnt lgkmcnt(0)
	s_barrier
	s_waitcnt lgkmcnt(0)
	v_mfma_f32_16x16x32_bf16 v[60:63], v[140:143], v[180:183], v[60:63]
	v_mfma_f32_16x16x32_bf16 v[56:59], v[156:159], v[180:183], v[56:59]
	v_mfma_f32_16x16x32_bf16 v[44:47], v[140:143], v[188:191], v[44:47]
	v_mfma_f32_16x16x32_bf16 v[40:43], v[156:159], v[188:191], v[40:43]
	v_mfma_f32_16x16x32_bf16 v[28:31], v[140:143], v[196:199], v[28:31]
	v_mfma_f32_16x16x32_bf16 v[24:27], v[156:159], v[196:199], v[24:27]
	v_mfma_f32_16x16x32_bf16 v[12:15], v[140:143], v[208:211], v[12:15]
	v_mfma_f32_16x16x32_bf16 v[8:11], v[156:159], v[208:211], v[8:11]
	v_mfma_f32_16x16x32_bf16 v[60:63], v[144:147], v[184:187], v[60:63]
	v_mfma_f32_16x16x32_bf16 v[56:59], v[160:163], v[184:187], v[56:59]
	v_mfma_f32_16x16x32_bf16 v[44:47], v[144:147], v[192:195], v[44:47]
	v_mfma_f32_16x16x32_bf16 v[40:43], v[160:163], v[192:195], v[40:43]
	v_mfma_f32_16x16x32_bf16 v[28:31], v[144:147], v[200:203], v[28:31]
	v_mfma_f32_16x16x32_bf16 v[24:27], v[160:163], v[200:203], v[24:27]
	v_mfma_f32_16x16x32_bf16 v[12:15], v[144:147], v[212:215], v[12:15]
	v_mfma_f32_16x16x32_bf16 v[8:11], v[160:163], v[212:215], v[8:11]
	v_mfma_f32_16x16x32_bf16 v[52:55], v[164:167], v[180:183], v[52:55]
	v_mfma_f32_16x16x32_bf16 v[48:51], v[172:175], v[180:183], v[48:51]
	v_mfma_f32_16x16x32_bf16 v[36:39], v[164:167], v[188:191], v[36:39]
	v_mfma_f32_16x16x32_bf16 v[32:35], v[172:175], v[188:191], v[32:35]
	v_mfma_f32_16x16x32_bf16 v[20:23], v[164:167], v[196:199], v[20:23]
	v_mfma_f32_16x16x32_bf16 v[16:19], v[172:175], v[196:199], v[16:19]
	v_mfma_f32_16x16x32_bf16 v[4:7], v[164:167], v[208:211], v[4:7]
	v_mfma_f32_16x16x32_bf16 v[0:3], v[172:175], v[208:211], v[0:3]
	v_mfma_f32_16x16x32_bf16 v[52:55], v[168:171], v[184:187], v[52:55]
	v_mfma_f32_16x16x32_bf16 v[48:51], v[176:179], v[184:187], v[48:51]
	v_mfma_f32_16x16x32_bf16 v[36:39], v[168:171], v[192:195], v[36:39]
	v_mfma_f32_16x16x32_bf16 v[32:35], v[176:179], v[192:195], v[32:35]
	v_mfma_f32_16x16x32_bf16 v[20:23], v[168:171], v[200:203], v[20:23]
	v_mfma_f32_16x16x32_bf16 v[16:19], v[176:179], v[200:203], v[16:19]
	v_mfma_f32_16x16x32_bf16 v[4:7], v[168:171], v[212:215], v[4:7]
	v_mfma_f32_16x16x32_bf16 v[0:3], v[176:179], v[212:215], v[0:3]
	s_barrier
	s_add_i32 m0, s64, 0x2000
	s_nop 0
	global_load_lds_dwordx4 v130, s[62:63]
	s_mov_b32 m0, s46
	s_nop 0
	global_load_lds_dwordx4 v128, s[40:41]
	s_mov_b32 m0, s47
	s_nop 0
	global_load_lds_dwordx4 v130, s[40:41]
	s_add_i32 s62, 0, 0x18000
	v_add_u32_e32 v155, s62, v149
	s_add_i32 s63, 0, 0x1c000
	ds_read_b128 v[140:143], v155
	ds_read_b128 v[144:147], v155 offset:1024
	ds_read_b128 v[156:159], v155 offset:2048
	ds_read_b128 v[160:163], v155 offset:3072
	v_add_u32_e32 v155, s63, v149
	ds_read_b128 v[164:167], v155
	ds_read_b128 v[168:171], v155 offset:1024
	ds_read_b128 v[172:175], v155 offset:2048
	ds_read_b128 v[176:179], v155 offset:3072
	s_add_u32 s40, s40, 0x40000
	s_addc_u32 s41, s41, 0
	s_mov_b32 m0, s48
	ds_read_b128 v[180:183], v153 offset:32768
	ds_read_b128 v[184:187], v153 offset:33792
	ds_read_b128 v[188:191], v153 offset:34816
	ds_read_b128 v[192:195], v153 offset:35840
	ds_read_b128 v[196:199], v153 offset:36864
	ds_read_b128 v[200:203], v153 offset:37888
	ds_read_b128 v[208:211], v153 offset:38912
	ds_read_b128 v[212:215], v153 offset:39936
	global_load_lds_dwordx4 v128, s[40:41]
	s_mov_b32 m0, s49
	s_nop 0
	global_load_lds_dwordx4 v130, s[40:41]
	s_waitcnt vmcnt(8)
	s_waitcnt lgkmcnt(0)
	s_barrier
	s_waitcnt lgkmcnt(0)
	v_mfma_f32_16x16x32_bf16 v[124:127], v[140:143], v[180:183], v[124:127]
	v_mfma_f32_16x16x32_bf16 v[120:123], v[156:159], v[180:183], v[120:123]
	v_mfma_f32_16x16x32_bf16 v[108:111], v[140:143], v[188:191], v[108:111]
	v_mfma_f32_16x16x32_bf16 v[104:107], v[156:159], v[188:191], v[104:107]
	v_mfma_f32_16x16x32_bf16 v[92:95], v[140:143], v[196:199], v[92:95]
	v_mfma_f32_16x16x32_bf16 v[88:91], v[156:159], v[196:199], v[88:91]
	v_mfma_f32_16x16x32_bf16 v[76:79], v[140:143], v[208:211], v[76:79]
	v_mfma_f32_16x16x32_bf16 v[72:75], v[156:159], v[208:211], v[72:75]
	v_mfma_f32_16x16x32_bf16 v[124:127], v[144:147], v[184:187], v[124:127]
	v_mfma_f32_16x16x32_bf16 v[120:123], v[160:163], v[184:187], v[120:123]
	v_mfma_f32_16x16x32_bf16 v[108:111], v[144:147], v[192:195], v[108:111]
	v_mfma_f32_16x16x32_bf16 v[104:107], v[160:163], v[192:195], v[104:107]
	v_mfma_f32_16x16x32_bf16 v[92:95], v[144:147], v[200:203], v[92:95]
	v_mfma_f32_16x16x32_bf16 v[88:91], v[160:163], v[200:203], v[88:91]
	v_mfma_f32_16x16x32_bf16 v[76:79], v[144:147], v[212:215], v[76:79]
	v_mfma_f32_16x16x32_bf16 v[72:75], v[160:163], v[212:215], v[72:75]
	v_mfma_f32_16x16x32_bf16 v[116:119], v[164:167], v[180:183], v[116:119]
	v_mfma_f32_16x16x32_bf16 v[112:115], v[172:175], v[180:183], v[112:115]
	v_mfma_f32_16x16x32_bf16 v[100:103], v[164:167], v[188:191], v[100:103]
	v_mfma_f32_16x16x32_bf16 v[96:99], v[172:175], v[188:191], v[96:99]
	v_mfma_f32_16x16x32_bf16 v[84:87], v[164:167], v[196:199], v[84:87]
	v_mfma_f32_16x16x32_bf16 v[80:83], v[172:175], v[196:199], v[80:83]
	v_mfma_f32_16x16x32_bf16 v[68:71], v[164:167], v[208:211], v[68:71]
	v_mfma_f32_16x16x32_bf16 v[64:67], v[172:175], v[208:211], v[64:67]
	v_mfma_f32_16x16x32_bf16 v[116:119], v[168:171], v[184:187], v[116:119]
	v_mfma_f32_16x16x32_bf16 v[112:115], v[176:179], v[184:187], v[112:115]
	v_mfma_f32_16x16x32_bf16 v[100:103], v[168:171], v[192:195], v[100:103]
	v_mfma_f32_16x16x32_bf16 v[96:99], v[176:179], v[192:195], v[96:99]
	v_mfma_f32_16x16x32_bf16 v[84:87], v[168:171], v[200:203], v[84:87]
	v_mfma_f32_16x16x32_bf16 v[80:83], v[176:179], v[200:203], v[80:83]
	v_mfma_f32_16x16x32_bf16 v[68:71], v[168:171], v[212:215], v[68:71]
	v_mfma_f32_16x16x32_bf16 v[64:67], v[176:179], v[212:215], v[64:67]
	s_barrier
	s_add_i32 s40, s62, s45
	s_mov_b32 m0, s40
	ds_read_b128 v[180:183], v153 offset:49152
	ds_read_b128 v[184:187], v153 offset:50176
	ds_read_b128 v[188:191], v153 offset:51200
	ds_read_b128 v[192:195], v153 offset:52224
	ds_read_b128 v[196:199], v153 offset:53248
	ds_read_b128 v[200:203], v153 offset:54272
	ds_read_b128 v[208:211], v153 offset:55296
	ds_read_b128 v[212:215], v153 offset:56320
	global_load_lds_dwordx4 v204, s[38:39]
	s_add_i32 m0, s40, 0x2000
	s_add_u32 s38, s38, 0x40080
	s_addc_u32 s39, s39, 0
	s_add_i32 s40, s63, s45
	global_load_lds_dwordx4 v205, s[98:99]
	s_mov_b32 m0, s40
	s_nop 0
	global_load_lds_dwordx4 v128, s[38:39]
	s_add_i32 m0, s40, 0x2000
	s_nop 0
	global_load_lds_dwordx4 v130, s[38:39]
	s_mov_b32 m0, s51
	s_nop 0
	global_load_lds_dwordx4 v204, s[100:101]
	s_mov_b32 m0, s52
	s_nop 0
	global_load_lds_dwordx4 v205, s[100:101]
	s_waitcnt vmcnt(8)
	s_waitcnt lgkmcnt(0)
	s_barrier
	s_waitcnt lgkmcnt(0)
	v_mfma_f32_16x16x32_bf16 v[60:63], v[140:143], v[180:183], v[60:63]
	v_mfma_f32_16x16x32_bf16 v[56:59], v[156:159], v[180:183], v[56:59]
	v_mfma_f32_16x16x32_bf16 v[44:47], v[140:143], v[188:191], v[44:47]
	v_mfma_f32_16x16x32_bf16 v[40:43], v[156:159], v[188:191], v[40:43]
	v_mfma_f32_16x16x32_bf16 v[28:31], v[140:143], v[196:199], v[28:31]
	v_mfma_f32_16x16x32_bf16 v[24:27], v[156:159], v[196:199], v[24:27]
	v_mfma_f32_16x16x32_bf16 v[12:15], v[140:143], v[208:211], v[12:15]
	v_mfma_f32_16x16x32_bf16 v[8:11], v[156:159], v[208:211], v[8:11]
	v_mfma_f32_16x16x32_bf16 v[60:63], v[144:147], v[184:187], v[60:63]
	v_mfma_f32_16x16x32_bf16 v[56:59], v[160:163], v[184:187], v[56:59]
	v_mfma_f32_16x16x32_bf16 v[44:47], v[144:147], v[192:195], v[44:47]
	v_mfma_f32_16x16x32_bf16 v[40:43], v[160:163], v[192:195], v[40:43]
	v_mfma_f32_16x16x32_bf16 v[28:31], v[144:147], v[200:203], v[28:31]
	v_mfma_f32_16x16x32_bf16 v[24:27], v[160:163], v[200:203], v[24:27]
	v_mfma_f32_16x16x32_bf16 v[12:15], v[144:147], v[212:215], v[12:15]
	v_mfma_f32_16x16x32_bf16 v[8:11], v[160:163], v[212:215], v[8:11]
	v_mfma_f32_16x16x32_bf16 v[52:55], v[164:167], v[180:183], v[52:55]
	v_mfma_f32_16x16x32_bf16 v[48:51], v[172:175], v[180:183], v[48:51]
	v_mfma_f32_16x16x32_bf16 v[36:39], v[164:167], v[188:191], v[36:39]
	v_mfma_f32_16x16x32_bf16 v[32:35], v[172:175], v[188:191], v[32:35]
	v_mfma_f32_16x16x32_bf16 v[20:23], v[164:167], v[196:199], v[20:23]
	v_mfma_f32_16x16x32_bf16 v[16:19], v[172:175], v[196:199], v[16:19]
	v_mfma_f32_16x16x32_bf16 v[4:7], v[164:167], v[208:211], v[4:7]
	v_mfma_f32_16x16x32_bf16 v[0:3], v[172:175], v[208:211], v[0:3]
	v_mfma_f32_16x16x32_bf16 v[52:55], v[168:171], v[184:187], v[52:55]
	v_mfma_f32_16x16x32_bf16 v[48:51], v[176:179], v[184:187], v[48:51]
	v_mfma_f32_16x16x32_bf16 v[36:39], v[168:171], v[192:195], v[36:39]
	v_mfma_f32_16x16x32_bf16 v[32:35], v[176:179], v[192:195], v[32:35]
	v_mfma_f32_16x16x32_bf16 v[20:23], v[168:171], v[200:203], v[20:23]
	v_mfma_f32_16x16x32_bf16 v[16:19], v[176:179], v[200:203], v[16:19]
	v_mfma_f32_16x16x32_bf16 v[4:7], v[168:171], v[212:215], v[4:7]
	v_mfma_f32_16x16x32_bf16 v[0:3], v[176:179], v[212:215], v[0:3]
	s_barrier
	s_add_i32 s61, s61, 2
	s_add_u32 s59, s59, 0x100
	s_addc_u32 s60, s60, 0
	s_add_u32 s36, s36, 0x100
	s_addc_u32 s37, s37, 0
	s_cmp_gt_u32 s61, 13
	s_cbranch_scc0 .LBB0_1561
	s_setprio 0
	s_and_b64 vcc, exec, s[24:25]
	s_cbranch_vccz .LBB0_1564
	s_barrier

.LBB0_1646:
	ds_read_b128 v[144:147], v151
	ds_read_b128 v[156:159], v151 offset:1024
	ds_read_b128 v[160:163], v151 offset:2048
	ds_read_b128 v[164:167], v151 offset:3072
	ds_read_b128 v[168:171], v152
	ds_read_b128 v[172:175], v152 offset:1024
	ds_read_b128 v[176:179], v152 offset:2048
	ds_read_b128 v[180:183], v152 offset:3072
	s_add_u32 s26, s24, 0xfffc0080
	s_addc_u32 s27, s25, -1
	s_cmp_eq_u32 s54, 12
	s_cselect_b32 s29, s19, s27
	s_cselect_b32 s28, s50, s26
	s_cselect_b32 s27, s17, s53
	s_cselect_b32 s26, s51, s52
	s_add_i32 m0, s38, 0xc000
	ds_read_b128 v[184:187], v153
	ds_read_b128 v[188:191], v153 offset:1024
	ds_read_b128 v[192:195], v153 offset:2048
	ds_read_b128 v[196:199], v153 offset:3072
	ds_read_b128 v[200:203], v153 offset:4096
	ds_read_b128 v[208:211], v153 offset:5120
	ds_read_b128 v[212:215], v153 offset:6144
	ds_read_b128 v[216:219], v153 offset:7168
	global_load_lds_dwordx4 v138, s[24:25]
	s_add_i32 m0, s38, 0xe000
	s_nop 0
	global_load_lds_dwordx4 v136, s[24:25]
	s_waitcnt vmcnt(8)
	s_waitcnt lgkmcnt(0)
	s_barrier
	s_waitcnt lgkmcnt(0)
	v_mfma_f32_16x16x32_bf16 v[124:127], v[144:147], v[184:187], v[124:127]
	v_mfma_f32_16x16x32_bf16 v[120:123], v[160:163], v[184:187], v[120:123]
	v_mfma_f32_16x16x32_bf16 v[108:111], v[144:147], v[192:195], v[108:111]
	v_mfma_f32_16x16x32_bf16 v[104:107], v[160:163], v[192:195], v[104:107]
	v_mfma_f32_16x16x32_bf16 v[92:95], v[144:147], v[200:203], v[92:95]
	v_mfma_f32_16x16x32_bf16 v[88:91], v[160:163], v[200:203], v[88:91]
	v_mfma_f32_16x16x32_bf16 v[76:79], v[144:147], v[212:215], v[76:79]
	v_mfma_f32_16x16x32_bf16 v[72:75], v[160:163], v[212:215], v[72:75]
	v_mfma_f32_16x16x32_bf16 v[124:127], v[156:159], v[188:191], v[124:127]
	v_mfma_f32_16x16x32_bf16 v[120:123], v[164:167], v[188:191], v[120:123]
	v_mfma_f32_16x16x32_bf16 v[108:111], v[156:159], v[196:199], v[108:111]
	v_mfma_f32_16x16x32_bf16 v[104:107], v[164:167], v[196:199], v[104:107]
	v_mfma_f32_16x16x32_bf16 v[92:95], v[156:159], v[208:211], v[92:95]
	v_mfma_f32_16x16x32_bf16 v[88:91], v[164:167], v[208:211], v[88:91]
	v_mfma_f32_16x16x32_bf16 v[76:79], v[156:159], v[216:219], v[76:79]
	v_mfma_f32_16x16x32_bf16 v[72:75], v[164:167], v[216:219], v[72:75]
	v_mfma_f32_16x16x32_bf16 v[116:119], v[168:171], v[184:187], v[116:119]
	v_mfma_f32_16x16x32_bf16 v[112:115], v[176:179], v[184:187], v[112:115]
	v_mfma_f32_16x16x32_bf16 v[100:103], v[168:171], v[192:195], v[100:103]
	v_mfma_f32_16x16x32_bf16 v[96:99], v[176:179], v[192:195], v[96:99]
	v_mfma_f32_16x16x32_bf16 v[84:87], v[168:171], v[200:203], v[84:87]
	v_mfma_f32_16x16x32_bf16 v[80:83], v[176:179], v[200:203], v[80:83]
	v_mfma_f32_16x16x32_bf16 v[68:71], v[168:171], v[212:215], v[68:71]
	v_mfma_f32_16x16x32_bf16 v[64:67], v[176:179], v[212:215], v[64:67]
	v_mfma_f32_16x16x32_bf16 v[116:119], v[172:175], v[188:191], v[116:119]
	v_mfma_f32_16x16x32_bf16 v[112:115], v[180:183], v[188:191], v[112:115]
	v_mfma_f32_16x16x32_bf16 v[100:103], v[172:175], v[196:199], v[100:103]
	v_mfma_f32_16x16x32_bf16 v[96:99], v[180:183], v[196:199], v[96:99]
	v_mfma_f32_16x16x32_bf16 v[84:87], v[172:175], v[208:211], v[84:87]
	v_mfma_f32_16x16x32_bf16 v[80:83], v[180:183], v[208:211], v[80:83]
	v_mfma_f32_16x16x32_bf16 v[68:71], v[172:175], v[216:219], v[68:71]
	v_mfma_f32_16x16x32_bf16 v[64:67], v[180:183], v[216:219], v[64:67]
	s_barrier
	s_add_i32 s55, s47, s35
	s_mov_b32 m0, s55
	ds_read_b128 v[184:187], v153 offset:16384
	ds_read_b128 v[188:191], v153 offset:17408
	ds_read_b128 v[192:195], v153 offset:18432
	ds_read_b128 v[196:199], v153 offset:19456
	ds_read_b128 v[200:203], v153 offset:20480
	ds_read_b128 v[208:211], v153 offset:21504
	ds_read_b128 v[212:215], v153 offset:22528
	ds_read_b128 v[216:219], v153 offset:23552
	global_load_lds_dwordx4 v132, s[26:27]
	s_add_i32 m0, s55, 0x2000
	s_add_u32 s56, s26, 0x40000
	s_mov_b64 s[98:99], s[26:27]
	s_addc_u32 s57, s27, 0
	s_add_i32 s55, s48, s35
	global_load_lds_dwordx4 v128, s[26:27]
	s_mov_b32 m0, s55
	s_mov_b64 s[100:101], s[28:29]
	global_load_lds_dwordx4 v132, s[56:57]
	s_waitcnt vmcnt(5)
	s_waitcnt lgkmcnt(0)
	s_barrier
	s_waitcnt lgkmcnt(0)
	v_mfma_f32_16x16x32_bf16 v[60:63], v[144:147], v[184:187], v[60:63]
	v_mfma_f32_16x16x32_bf16 v[56:59], v[160:163], v[184:187], v[56:59]
	v_mfma_f32_16x16x32_bf16 v[44:47], v[144:147], v[192:195], v[44:47]
	v_mfma_f32_16x16x32_bf16 v[40:43], v[160:163], v[192:195], v[40:43]
	v_mfma_f32_16x16x32_bf16 v[28:31], v[144:147], v[200:203], v[28:31]
	v_mfma_f32_16x16x32_bf16 v[24:27], v[160:163], v[200:203], v[24:27]
	v_mfma_f32_16x16x32_bf16 v[12:15], v[144:147], v[212:215], v[12:15]
	v_mfma_f32_16x16x32_bf16 v[8:11], v[160:163], v[212:215], v[8:11]
	v_mfma_f32_16x16x32_bf16 v[60:63], v[156:159], v[188:191], v[60:63]
	v_mfma_f32_16x16x32_bf16 v[56:59], v[164:167], v[188:191], v[56:59]
	v_mfma_f32_16x16x32_bf16 v[44:47], v[156:159], v[196:199], v[44:47]
	v_mfma_f32_16x16x32_bf16 v[40:43], v[164:167], v[196:199], v[40:43]
	v_mfma_f32_16x16x32_bf16 v[28:31], v[156:159], v[208:211], v[28:31]
	v_mfma_f32_16x16x32_bf16 v[24:27], v[164:167], v[208:211], v[24:27]
	v_mfma_f32_16x16x32_bf16 v[12:15], v[156:159], v[216:219], v[12:15]
	v_mfma_f32_16x16x32_bf16 v[8:11], v[164:167], v[216:219], v[8:11]
	v_mfma_f32_16x16x32_bf16 v[52:55], v[168:171], v[184:187], v[52:55]
	v_mfma_f32_16x16x32_bf16 v[48:51], v[176:179], v[184:187], v[48:51]
	v_mfma_f32_16x16x32_bf16 v[36:39], v[168:171], v[192:195], v[36:39]
	v_mfma_f32_16x16x32_bf16 v[32:35], v[176:179], v[192:195], v[32:35]
	v_mfma_f32_16x16x32_bf16 v[20:23], v[168:171], v[200:203], v[20:23]
	v_mfma_f32_16x16x32_bf16 v[16:19], v[176:179], v[200:203], v[16:19]
	v_mfma_f32_16x16x32_bf16 v[4:7], v[168:171], v[212:215], v[4:7]
	v_mfma_f32_16x16x32_bf16 v[0:3], v[176:179], v[212:215], v[0:3]
	v_mfma_f32_16x16x32_bf16 v[52:55], v[172:175], v[188:191], v[52:55]
	v_mfma_f32_16x16x32_bf16 v[48:51], v[180:183], v[188:191], v[48:51]
	v_mfma_f32_16x16x32_bf16 v[36:39], v[172:175], v[196:199], v[36:39]
	v_mfma_f32_16x16x32_bf16 v[32:35], v[180:183], v[196:199], v[32:35]
	v_mfma_f32_16x16x32_bf16 v[20:23], v[172:175], v[208:211], v[20:23]
	v_mfma_f32_16x16x32_bf16 v[16:19], v[180:183], v[208:211], v[16:19]
	v_mfma_f32_16x16x32_bf16 v[4:7], v[172:175], v[216:219], v[4:7]
	v_mfma_f32_16x16x32_bf16 v[0:3], v[180:183], v[216:219], v[0:3]
	s_barrier
	s_add_i32 m0, s55, 0x2000
	s_nop 0
	global_load_lds_dwordx4 v128, s[56:57]
	s_mov_b32 m0, s38
	s_nop 0
	global_load_lds_dwordx4 v134, s[28:29]
	s_mov_b32 m0, s39
	s_nop 0
	global_load_lds_dwordx4 v130, s[28:29]
	s_add_i32 s55, 0, 0x18000
	s_add_i32 s56, 0, 0x1c000
	v_add_u32_e32 v164, s55, v149
	v_add_u32_e32 v180, s56, v149
	ds_read_b128 v[144:147], v164
	ds_read_b128 v[156:159], v164 offset:1024
	ds_read_b128 v[160:163], v164 offset:2048
	ds_read_b128 v[164:167], v164 offset:3072
	ds_read_b128 v[168:171], v180
	ds_read_b128 v[172:175], v180 offset:1024
	ds_read_b128 v[176:179], v180 offset:2048
	ds_read_b128 v[180:183], v180 offset:3072
	s_add_u32 s28, s28, 0x40000
	s_addc_u32 s29, s29, 0
	s_mov_b32 m0, s40
	ds_read_b128 v[184:187], v153 offset:32768
	ds_read_b128 v[188:191], v153 offset:33792
	ds_read_b128 v[192:195], v153 offset:34816
	ds_read_b128 v[196:199], v153 offset:35840
	ds_read_b128 v[200:203], v153 offset:36864
	ds_read_b128 v[208:211], v153 offset:37888
	ds_read_b128 v[212:215], v153 offset:38912
	ds_read_b128 v[216:219], v153 offset:39936
	global_load_lds_dwordx4 v134, s[28:29]
	s_mov_b32 m0, s41
	s_nop 0
	global_load_lds_dwordx4 v130, s[28:29]
	s_waitcnt vmcnt(8)
	s_waitcnt lgkmcnt(0)
	s_barrier
	s_waitcnt lgkmcnt(0)
	v_mfma_f32_16x16x32_bf16 v[124:127], v[144:147], v[184:187], v[124:127]
	v_mfma_f32_16x16x32_bf16 v[120:123], v[160:163], v[184:187], v[120:123]
	v_mfma_f32_16x16x32_bf16 v[108:111], v[144:147], v[192:195], v[108:111]
	v_mfma_f32_16x16x32_bf16 v[104:107], v[160:163], v[192:195], v[104:107]
	v_mfma_f32_16x16x32_bf16 v[92:95], v[144:147], v[200:203], v[92:95]
	v_mfma_f32_16x16x32_bf16 v[88:91], v[160:163], v[200:203], v[88:91]
	v_mfma_f32_16x16x32_bf16 v[76:79], v[144:147], v[212:215], v[76:79]
	v_mfma_f32_16x16x32_bf16 v[72:75], v[160:163], v[212:215], v[72:75]
	v_mfma_f32_16x16x32_bf16 v[124:127], v[156:159], v[188:191], v[124:127]
	v_mfma_f32_16x16x32_bf16 v[120:123], v[164:167], v[188:191], v[120:123]
	v_mfma_f32_16x16x32_bf16 v[108:111], v[156:159], v[196:199], v[108:111]
	v_mfma_f32_16x16x32_bf16 v[104:107], v[164:167], v[196:199], v[104:107]
	v_mfma_f32_16x16x32_bf16 v[92:95], v[156:159], v[208:211], v[92:95]
	v_mfma_f32_16x16x32_bf16 v[88:91], v[164:167], v[208:211], v[88:91]
	v_mfma_f32_16x16x32_bf16 v[76:79], v[156:159], v[216:219], v[76:79]
	v_mfma_f32_16x16x32_bf16 v[72:75], v[164:167], v[216:219], v[72:75]
	v_mfma_f32_16x16x32_bf16 v[116:119], v[168:171], v[184:187], v[116:119]
	v_mfma_f32_16x16x32_bf16 v[112:115], v[176:179], v[184:187], v[112:115]
	v_mfma_f32_16x16x32_bf16 v[100:103], v[168:171], v[192:195], v[100:103]
	v_mfma_f32_16x16x32_bf16 v[96:99], v[176:179], v[192:195], v[96:99]
	v_mfma_f32_16x16x32_bf16 v[84:87], v[168:171], v[200:203], v[84:87]
	v_mfma_f32_16x16x32_bf16 v[80:83], v[176:179], v[200:203], v[80:83]
	v_mfma_f32_16x16x32_bf16 v[68:71], v[168:171], v[212:215], v[68:71]
	v_mfma_f32_16x16x32_bf16 v[64:67], v[176:179], v[212:215], v[64:67]
	v_mfma_f32_16x16x32_bf16 v[116:119], v[172:175], v[188:191], v[116:119]
	v_mfma_f32_16x16x32_bf16 v[112:115], v[180:183], v[188:191], v[112:115]
	v_mfma_f32_16x16x32_bf16 v[100:103], v[172:175], v[196:199], v[100:103]
	v_mfma_f32_16x16x32_bf16 v[96:99], v[180:183], v[196:199], v[96:99]
	v_mfma_f32_16x16x32_bf16 v[84:87], v[172:175], v[208:211], v[84:87]
	v_mfma_f32_16x16x32_bf16 v[80:83], v[180:183], v[208:211], v[80:83]
	v_mfma_f32_16x16x32_bf16 v[68:71], v[172:175], v[216:219], v[68:71]
	v_mfma_f32_16x16x32_bf16 v[64:67], v[180:183], v[216:219], v[64:67]
	s_barrier
	s_add_i32 s28, s55, s35
	s_mov_b32 m0, s28
	ds_read_b128 v[184:187], v153 offset:49152
	ds_read_b128 v[188:191], v153 offset:50176
	ds_read_b128 v[192:195], v153 offset:51200
	ds_read_b128 v[196:199], v153 offset:52224
	ds_read_b128 v[200:203], v153 offset:53248
	ds_read_b128 v[208:211], v153 offset:54272
	ds_read_b128 v[212:215], v153 offset:55296
	ds_read_b128 v[216:219], v153 offset:56320
	global_load_lds_dwordx4 v220, s[26:27]
	s_add_i32 m0, s28, 0x2000
	s_add_u32 s26, s26, 0x40080
	s_addc_u32 s27, s27, 0
	s_add_i32 s28, s56, s35
	global_load_lds_dwordx4 v204, s[98:99]
	s_mov_b32 m0, s28
	s_nop 0
	global_load_lds_dwordx4 v132, s[26:27]
	s_add_i32 m0, s28, 0x2000
	s_nop 0
	global_load_lds_dwordx4 v128, s[26:27]
	s_mov_b32 m0, s45
	s_nop 0
	global_load_lds_dwordx4 v221, s[100:101]
	s_mov_b32 m0, s46
	s_nop 0
	global_load_lds_dwordx4 v205, s[100:101]
	s_waitcnt vmcnt(8)
	s_waitcnt lgkmcnt(0)
	s_barrier
	s_waitcnt lgkmcnt(0)
	v_mfma_f32_16x16x32_bf16 v[60:63], v[144:147], v[184:187], v[60:63]
	v_mfma_f32_16x16x32_bf16 v[56:59], v[160:163], v[184:187], v[56:59]
	v_mfma_f32_16x16x32_bf16 v[44:47], v[144:147], v[192:195], v[44:47]
	v_mfma_f32_16x16x32_bf16 v[40:43], v[160:163], v[192:195], v[40:43]
	v_mfma_f32_16x16x32_bf16 v[28:31], v[144:147], v[200:203], v[28:31]
	v_mfma_f32_16x16x32_bf16 v[24:27], v[160:163], v[200:203], v[24:27]
	v_mfma_f32_16x16x32_bf16 v[12:15], v[144:147], v[212:215], v[12:15]
	v_mfma_f32_16x16x32_bf16 v[8:11], v[160:163], v[212:215], v[8:11]
	v_mfma_f32_16x16x32_bf16 v[60:63], v[156:159], v[188:191], v[60:63]
	v_mfma_f32_16x16x32_bf16 v[56:59], v[164:167], v[188:191], v[56:59]
	v_mfma_f32_16x16x32_bf16 v[44:47], v[156:159], v[196:199], v[44:47]
	v_mfma_f32_16x16x32_bf16 v[40:43], v[164:167], v[196:199], v[40:43]
	v_mfma_f32_16x16x32_bf16 v[28:31], v[156:159], v[208:211], v[28:31]
	v_mfma_f32_16x16x32_bf16 v[24:27], v[164:167], v[208:211], v[24:27]
	v_mfma_f32_16x16x32_bf16 v[12:15], v[156:159], v[216:219], v[12:15]
	v_mfma_f32_16x16x32_bf16 v[8:11], v[164:167], v[216:219], v[8:11]
	v_mfma_f32_16x16x32_bf16 v[52:55], v[168:171], v[184:187], v[52:55]
	v_mfma_f32_16x16x32_bf16 v[48:51], v[176:179], v[184:187], v[48:51]
	v_mfma_f32_16x16x32_bf16 v[36:39], v[168:171], v[192:195], v[36:39]
	v_mfma_f32_16x16x32_bf16 v[32:35], v[176:179], v[192:195], v[32:35]
	v_mfma_f32_16x16x32_bf16 v[20:23], v[168:171], v[200:203], v[20:23]
	v_mfma_f32_16x16x32_bf16 v[16:19], v[176:179], v[200:203], v[16:19]
	v_mfma_f32_16x16x32_bf16 v[4:7], v[168:171], v[212:215], v[4:7]
	v_mfma_f32_16x16x32_bf16 v[0:3], v[176:179], v[212:215], v[0:3]
	v_mfma_f32_16x16x32_bf16 v[52:55], v[172:175], v[188:191], v[52:55]
	v_mfma_f32_16x16x32_bf16 v[48:51], v[180:183], v[188:191], v[48:51]
	v_mfma_f32_16x16x32_bf16 v[36:39], v[172:175], v[196:199], v[36:39]
	v_mfma_f32_16x16x32_bf16 v[32:35], v[180:183], v[196:199], v[32:35]
	v_mfma_f32_16x16x32_bf16 v[20:23], v[172:175], v[208:211], v[20:23]
	v_mfma_f32_16x16x32_bf16 v[16:19], v[180:183], v[208:211], v[16:19]
	v_mfma_f32_16x16x32_bf16 v[4:7], v[172:175], v[216:219], v[4:7]
	v_mfma_f32_16x16x32_bf16 v[0:3], v[180:183], v[216:219], v[0:3]
	s_barrier
	s_add_i32 s54, s54, 2
	s_add_u32 s52, s52, 0x100
	s_addc_u32 s53, s53, 0
	s_add_u32 s24, s24, 0x100
	s_addc_u32 s25, s25, 0
	s_cmp_gt_u32 s54, 13
	s_cbranch_scc0 .LBB0_1646
	s_setprio 0
	s_and_b64 vcc, exec, s[14:15]
	s_cbranch_vccz .LBB0_1649
	s_barrier
